# GEMM K-loops: one LDS-DMA piece moved from the 6-piece SP2 load segment to the head of the following SP1 segment (5+3 instead of 6+2), SP2 wait vmcnt(7)
# speedup vs baseline: 1.0017x; 1.0017x over previous
.LBB0_251:
	s_ashr_i32 s13, s12, 31
	s_lshl_b64 s[14:15], s[12:13], 19
	s_add_u32 s14, s29, s14
	s_addc_u32 s15, s38, s15
	s_and_b64 s[16:17], s[4:5], exec
	s_cselect_b32 s13, s15, s23
	s_cselect_b32 s19, s14, s22
	s_ashr_i32 s11, s10, 31
	s_lshl_b64 s[16:17], s[10:11], 19
	s_add_u32 s16, s39, s16
	s_addc_u32 s17, s40, s17
	s_and_b64 s[24:25], s[4:5], exec
	s_cselect_b32 s11, s17, s21
	s_cselect_b32 s61, s16, s20
	s_add_u32 s62, s20, 0x100
	s_addc_u32 s63, s21, 0
	s_add_u32 s20, s22, 0x40080
	s_addc_u32 s21, s23, 0
	s_mov_b32 s68, -2
	s_add_u32 s22, s20, 0xfffc0080
	s_addc_u32 s23, s21, -1
	s_add_i32 s64, 0, 0x10000
	s_cmp_eq_u32 s68, 12
	s_cselect_b32 s25, s13, s23
	s_cselect_b32 s24, s19, s22
	s_cselect_b32 s23, s11, s63
	s_cselect_b32 s22, s61, s62
	s_lshl_b32 s74, s18, 8
	v_add_u32_e32 v178, s74, v168
	v_ashrrev_i32_e32 v179, 31, v178
	v_lshlrev_b64 v[178:179], 6, v[178:179]
	v_lshl_add_u64 v[178:179], s[70:71], 0, v[178:179]
	s_and_saveexec_b64 s[78:79], s[2:3]
	global_load_dwordx4 v[238:241], v[178:179], off
	global_load_dwordx4 v[242:245], v[178:179], off offset:16
	global_load_dwordx4 v[246:249], v[178:179], off offset:32
	global_load_dwordx4 v[250:253], v[178:179], off offset:48
	s_mov_b64 exec, s[78:79]
	s_add_i32 s69, 0, 0x14000
	v_add_u32_e32 v140, s64, v167
	v_add_u32_e32 v164, s69, v167
	ds_read_b128 v[48:51], v140
	ds_read_b128 v[56:59], v140 offset:1024
	ds_read_b128 v[136:139], v140 offset:2048
	ds_read_b128 v[140:143], v140 offset:3072
	ds_read_b128 v[156:159], v164
	ds_read_b128 v[160:163], v164 offset:1024
	ds_read_b128 v[182:185], v164 offset:2048
	ds_read_b128 v[186:189], v164 offset:3072
	s_add_i32 m0, s49, 0xc000
	ds_read_b128 v[190:193], v172
	ds_read_b128 v[194:197], v172 offset:1024
	ds_read_b128 v[198:201], v172 offset:2048
	ds_read_b128 v[202:205], v172 offset:3072
	ds_read_b128 v[206:209], v172 offset:4096
	ds_read_b128 v[210:213], v172 offset:5120
	ds_read_b128 v[228:231], v172 offset:6144
	ds_read_b128 v[232:235], v172 offset:7168
	global_load_lds_dwordx4 v154, s[20:21]
	s_add_i32 m0, s49, 0xe000
	s_nop 0
	global_load_lds_dwordx4 v152, s[20:21]
	s_waitcnt vmcnt(12) lgkmcnt(0)
	s_barrier
	s_setprio 1
	v_mfma_f32_16x16x32_bf16 v[132:135], v[48:51], v[190:193], 0
	v_mfma_f32_16x16x32_bf16 v[124:127], v[136:139], v[190:193], 0
	v_mfma_f32_16x16x32_bf16 v[116:119], v[48:51], v[198:201], 0
	v_mfma_f32_16x16x32_bf16 v[112:115], v[136:139], v[198:201], 0
	v_mfma_f32_16x16x32_bf16 v[100:103], v[48:51], v[206:209], 0
	v_mfma_f32_16x16x32_bf16 v[96:99], v[136:139], v[206:209], 0
	v_mfma_f32_16x16x32_bf16 v[84:87], v[48:51], v[228:231], 0
	v_mfma_f32_16x16x32_bf16 v[80:83], v[136:139], v[228:231], 0
	v_mfma_f32_16x16x32_bf16 v[132:135], v[56:59], v[194:197], v[132:135]
	v_mfma_f32_16x16x32_bf16 v[124:127], v[140:143], v[194:197], v[124:127]
	v_mfma_f32_16x16x32_bf16 v[116:119], v[56:59], v[202:205], v[116:119]
	v_mfma_f32_16x16x32_bf16 v[112:115], v[140:143], v[202:205], v[112:115]
	v_mfma_f32_16x16x32_bf16 v[100:103], v[56:59], v[210:213], v[100:103]
	v_mfma_f32_16x16x32_bf16 v[96:99], v[140:143], v[210:213], v[96:99]
	v_mfma_f32_16x16x32_bf16 v[84:87], v[56:59], v[232:235], v[84:87]
	v_mfma_f32_16x16x32_bf16 v[80:83], v[140:143], v[232:235], v[80:83]
	v_mfma_f32_16x16x32_bf16 v[128:131], v[156:159], v[190:193], 0
	v_mfma_f32_16x16x32_bf16 v[120:123], v[182:185], v[190:193], 0
	v_mfma_f32_16x16x32_bf16 v[108:111], v[156:159], v[198:201], 0
	v_mfma_f32_16x16x32_bf16 v[104:107], v[182:185], v[198:201], 0
	v_mfma_f32_16x16x32_bf16 v[92:95], v[156:159], v[206:209], 0
	v_mfma_f32_16x16x32_bf16 v[88:91], v[182:185], v[206:209], 0
	v_mfma_f32_16x16x32_bf16 v[76:79], v[156:159], v[228:231], 0
	v_mfma_f32_16x16x32_bf16 v[72:75], v[182:185], v[228:231], 0
	v_mfma_f32_16x16x32_bf16 v[128:131], v[160:163], v[194:197], v[128:131]
	v_mfma_f32_16x16x32_bf16 v[120:123], v[186:189], v[194:197], v[120:123]
	v_mfma_f32_16x16x32_bf16 v[108:111], v[160:163], v[202:205], v[108:111]
	v_mfma_f32_16x16x32_bf16 v[104:107], v[186:189], v[202:205], v[104:107]
	s_setprio 2
	s_barrier
	v_mfma_f32_16x16x32_bf16 v[92:95], v[160:163], v[210:213], v[92:95]
	v_mfma_f32_16x16x32_bf16 v[88:91], v[186:189], v[210:213], v[88:91]
	v_mfma_f32_16x16x32_bf16 v[76:79], v[160:163], v[232:235], v[76:79]
	v_mfma_f32_16x16x32_bf16 v[72:75], v[186:189], v[232:235], v[72:75]
	s_setprio 0
	s_add_i32 s64, s64, s41
	s_add_u32 s94, s22, s34
	s_addc_u32 s95, s23, s35
	s_mov_b32 m0, s64
	ds_read_b128 v[190:193], v172 offset:16384
	ds_read_b128 v[194:197], v172 offset:17408
	ds_read_b128 v[198:201], v172 offset:18432
	ds_read_b128 v[202:205], v172 offset:19456
	ds_read_b128 v[206:209], v172 offset:20480
	ds_read_b128 v[210:213], v172 offset:21504
	ds_read_b128 v[228:231], v172 offset:22528
	ds_read_b128 v[232:235], v172 offset:23552
	global_load_lds_dwordx4 v148, s[22:23]
	s_add_i32 m0, s64, 0x2000
	s_add_u32 s64, s22, 0x40000
	s_addc_u32 s65, s23, 0
	s_add_i32 s69, s69, s41
	global_load_lds_dwordx4 v144, s[22:23]
	s_mov_b32 m0, s69
	s_nop 0
	global_load_lds_dwordx4 v148, s[64:65]
	s_add_i32 m0, s69, 0x2000
	s_nop 0
	global_load_lds_dwordx4 v144, s[64:65]
	s_add_u32 s98, s24, s34
	s_addc_u32 s99, s25, s35
	s_mov_b32 m0, s49
	s_nop 0
	global_load_lds_dwordx4 v150, s[24:25]
	s_waitcnt vmcnt(7) lgkmcnt(0)
	s_barrier
	s_setprio 1
	v_mfma_f32_16x16x32_bf16 v[68:71], v[48:51], v[190:193], 0
	v_mfma_f32_16x16x32_bf16 v[64:67], v[136:139], v[190:193], 0
	v_mfma_f32_16x16x32_bf16 v[44:47], v[48:51], v[198:201], 0
	v_mfma_f32_16x16x32_bf16 v[40:43], v[136:139], v[198:201], 0
	v_mfma_f32_16x16x32_bf16 v[28:31], v[48:51], v[206:209], 0
	v_mfma_f32_16x16x32_bf16 v[24:27], v[136:139], v[206:209], 0
	v_mfma_f32_16x16x32_bf16 v[12:15], v[48:51], v[228:231], 0
	v_mfma_f32_16x16x32_bf16 v[8:11], v[136:139], v[228:231], 0
	v_mfma_f32_16x16x32_bf16 v[68:71], v[56:59], v[194:197], v[68:71]
	v_mfma_f32_16x16x32_bf16 v[64:67], v[140:143], v[194:197], v[64:67]
	v_mfma_f32_16x16x32_bf16 v[44:47], v[56:59], v[202:205], v[44:47]
	v_mfma_f32_16x16x32_bf16 v[40:43], v[140:143], v[202:205], v[40:43]
	v_mfma_f32_16x16x32_bf16 v[28:31], v[56:59], v[210:213], v[28:31]
	v_mfma_f32_16x16x32_bf16 v[24:27], v[140:143], v[210:213], v[24:27]
	v_mfma_f32_16x16x32_bf16 v[12:15], v[56:59], v[232:235], v[12:15]
	v_mfma_f32_16x16x32_bf16 v[8:11], v[140:143], v[232:235], v[8:11]
	v_mfma_f32_16x16x32_bf16 v[52:55], v[182:185], v[190:193], 0
	v_mfma_f32_16x16x32_bf16 v[36:39], v[156:159], v[198:201], 0
	v_mfma_f32_16x16x32_bf16 v[32:35], v[182:185], v[198:201], 0
	v_mfma_f32_16x16x32_bf16 v[20:23], v[156:159], v[206:209], 0
	v_mfma_f32_16x16x32_bf16 v[16:19], v[182:185], v[206:209], 0
	v_mfma_f32_16x16x32_bf16 v[4:7], v[156:159], v[228:231], 0
	v_mfma_f32_16x16x32_bf16 v[0:3], v[182:185], v[228:231], 0
	v_mfma_f32_16x16x32_bf16 v[48:51], v[156:159], v[190:193], 0
	v_mfma_f32_16x16x32_bf16 v[52:55], v[186:189], v[194:197], v[52:55]
	v_mfma_f32_16x16x32_bf16 v[36:39], v[160:163], v[202:205], v[36:39]
	v_mfma_f32_16x16x32_bf16 v[32:35], v[186:189], v[202:205], v[32:35]
	v_mfma_f32_16x16x32_bf16 v[20:23], v[160:163], v[210:213], v[20:23]
	s_setprio 2
	s_barrier
	v_mfma_f32_16x16x32_bf16 v[16:19], v[186:189], v[210:213], v[16:19]
	v_mfma_f32_16x16x32_bf16 v[4:7], v[160:163], v[232:235], v[4:7]
	v_mfma_f32_16x16x32_bf16 v[0:3], v[186:189], v[232:235], v[0:3]
	v_mfma_f32_16x16x32_bf16 v[48:51], v[160:163], v[194:197], v[48:51]
	s_setprio 0
	s_mov_b32 m0, s50
	s_nop 0
	global_load_lds_dwordx4 v146, s[24:25]
	s_and_saveexec_b64 s[78:79], s[2:3]
	v_add_f32_e32 v238, v238, v239
	v_add_f32_e32 v240, v240, v241
	v_add_f32_e32 v242, v242, v243
	v_add_f32_e32 v244, v244, v245
	v_add_f32_e32 v246, v246, v247
	v_add_f32_e32 v248, v248, v249
	v_add_f32_e32 v250, v250, v251
	v_add_f32_e32 v252, v252, v253
	v_add_f32_e32 v238, v238, v240
	v_add_f32_e32 v242, v242, v244
	v_add_f32_e32 v246, v246, v248
	v_add_f32_e32 v250, v250, v252
	v_add_f32_e32 v238, v238, v242
	v_add_f32_e32 v246, v246, v250
	v_add_f32_e32 v238, v238, v246
	v_fmamk_f32 v238, v238, 0x3a800000, v216
	v_rsq_f32_e32 v238, v238
	s_nop 0
	ds_write_b32 v169, v238
	s_mov_b64 exec, s[78:79]
	s_add_i32 s64, 0, 0x18000
	s_add_i32 s65, 0, 0x1c000
	v_add_u32_e32 v140, s64, v167
	v_add_u32_e32 v173, s65, v167
	ds_read_b128 v[56:59], v140
	ds_read_b128 v[60:63], v140 offset:1024
	ds_read_b128 v[136:139], v140 offset:2048
	ds_read_b128 v[140:143], v140 offset:3072
	ds_read_b128 v[156:159], v173
	ds_read_b128 v[160:163], v173 offset:1024
	ds_read_b128 v[182:185], v173 offset:2048
	ds_read_b128 v[186:189], v173 offset:3072
	s_add_u32 s24, s24, 0x40000
	s_addc_u32 s25, s25, 0
	s_mov_b32 m0, s51
	ds_read_b128 v[190:193], v172 offset:32768
	ds_read_b128 v[194:197], v172 offset:33792
	ds_read_b128 v[198:201], v172 offset:34816
	ds_read_b128 v[202:205], v172 offset:35840
	ds_read_b128 v[206:209], v172 offset:36864
	ds_read_b128 v[210:213], v172 offset:37888
	ds_read_b128 v[228:231], v172 offset:38912
	ds_read_b128 v[232:235], v172 offset:39936
	global_load_lds_dwordx4 v150, s[24:25]
	s_mov_b32 m0, s52
	s_nop 0
	global_load_lds_dwordx4 v146, s[24:25]
	s_waitcnt vmcnt(8) lgkmcnt(0)
	s_barrier
	s_setprio 1
	v_mfma_f32_16x16x32_bf16 v[132:135], v[56:59], v[190:193], v[132:135]
	v_mfma_f32_16x16x32_bf16 v[124:127], v[136:139], v[190:193], v[124:127]
	v_mfma_f32_16x16x32_bf16 v[116:119], v[56:59], v[198:201], v[116:119]
	v_mfma_f32_16x16x32_bf16 v[112:115], v[136:139], v[198:201], v[112:115]
	v_mfma_f32_16x16x32_bf16 v[100:103], v[56:59], v[206:209], v[100:103]
	v_mfma_f32_16x16x32_bf16 v[96:99], v[136:139], v[206:209], v[96:99]
	v_mfma_f32_16x16x32_bf16 v[84:87], v[56:59], v[228:231], v[84:87]
	v_mfma_f32_16x16x32_bf16 v[80:83], v[136:139], v[228:231], v[80:83]
	v_mfma_f32_16x16x32_bf16 v[132:135], v[60:63], v[194:197], v[132:135]
	v_mfma_f32_16x16x32_bf16 v[124:127], v[140:143], v[194:197], v[124:127]
	v_mfma_f32_16x16x32_bf16 v[116:119], v[60:63], v[202:205], v[116:119]
	v_mfma_f32_16x16x32_bf16 v[112:115], v[140:143], v[202:205], v[112:115]
	v_mfma_f32_16x16x32_bf16 v[100:103], v[60:63], v[210:213], v[100:103]
	v_mfma_f32_16x16x32_bf16 v[96:99], v[140:143], v[210:213], v[96:99]
	v_mfma_f32_16x16x32_bf16 v[84:87], v[60:63], v[232:235], v[84:87]
	v_mfma_f32_16x16x32_bf16 v[80:83], v[140:143], v[232:235], v[80:83]
	v_mfma_f32_16x16x32_bf16 v[128:131], v[156:159], v[190:193], v[128:131]
	v_mfma_f32_16x16x32_bf16 v[120:123], v[182:185], v[190:193], v[120:123]
	v_mfma_f32_16x16x32_bf16 v[108:111], v[156:159], v[198:201], v[108:111]
	v_mfma_f32_16x16x32_bf16 v[104:107], v[182:185], v[198:201], v[104:107]
	v_mfma_f32_16x16x32_bf16 v[92:95], v[156:159], v[206:209], v[92:95]
	v_mfma_f32_16x16x32_bf16 v[88:91], v[182:185], v[206:209], v[88:91]
	v_mfma_f32_16x16x32_bf16 v[76:79], v[156:159], v[228:231], v[76:79]
	v_mfma_f32_16x16x32_bf16 v[72:75], v[182:185], v[228:231], v[72:75]
	v_mfma_f32_16x16x32_bf16 v[128:131], v[160:163], v[194:197], v[128:131]
	v_mfma_f32_16x16x32_bf16 v[120:123], v[186:189], v[194:197], v[120:123]
	v_mfma_f32_16x16x32_bf16 v[108:111], v[160:163], v[202:205], v[108:111]
	v_mfma_f32_16x16x32_bf16 v[104:107], v[186:189], v[202:205], v[104:107]
	s_setprio 2
	s_barrier
	v_mfma_f32_16x16x32_bf16 v[92:95], v[160:163], v[210:213], v[92:95]
	v_mfma_f32_16x16x32_bf16 v[88:91], v[186:189], v[210:213], v[88:91]
	v_mfma_f32_16x16x32_bf16 v[76:79], v[160:163], v[232:235], v[76:79]
	v_mfma_f32_16x16x32_bf16 v[72:75], v[186:189], v[232:235], v[72:75]
	s_setprio 0
	s_min_i32 s74, s18, 0x80
	s_ashr_i32 s74, s74, 3
	s_mul_hi_i32 s75, s74, 0x5800
	s_mulk_i32 s74, 0x5800
	s_add_u32 s74, s53, s74
	s_addc_u32 s75, s54, s75
	s_lshl_b32 s76, s60, 8
	s_ashr_i32 s77, s76, 31
	s_lshl_b64 s[76:77], s[76:77], 2
	s_add_u32 s74, s74, s76
	s_addc_u32 s75, s75, s77
	s_add_u32 s74, s74, s59
	s_addc_u32 s75, s75, 0
	v_lshl_add_u64 v[178:179], s[74:75], 0, v[176:177]
	global_load_dwordx4 v[238:241], v[178:179], off
	global_load_dwordx4 v[242:245], v[178:179], off offset:16
	global_load_dwordx4 v[246:249], v[178:179], off offset:512
	global_load_dwordx4 v[250:253], v[178:179], off offset:528
	s_add_i32 s24, s64, s41
	s_mov_b32 m0, s24
	ds_read_b128 v[190:193], v172 offset:49152
	ds_read_b128 v[194:197], v172 offset:50176
	ds_read_b128 v[198:201], v172 offset:51200
	ds_read_b128 v[202:205], v172 offset:52224
	ds_read_b128 v[206:209], v172 offset:53248
	ds_read_b128 v[210:213], v172 offset:54272
	ds_read_b128 v[228:231], v172 offset:55296
	ds_read_b128 v[232:235], v172 offset:56320
	global_load_lds_dwordx4 v148, s[94:95]
	s_add_i32 m0, s24, 0x2000
	s_add_u32 s22, s22, 0x40080
	s_addc_u32 s23, s23, 0
	s_add_i32 s24, s65, s41
	global_load_lds_dwordx4 v144, s[94:95]
	s_mov_b32 m0, s24
	s_nop 0
	global_load_lds_dwordx4 v148, s[22:23]
	s_add_i32 m0, s24, 0x2000
	s_nop 0
	global_load_lds_dwordx4 v144, s[22:23]
	s_mov_b32 m0, s55
	s_nop 0
	global_load_lds_dwordx4 v150, s[98:99]
	s_mov_b32 m0, s56
	s_nop 0
	global_load_lds_dwordx4 v146, s[98:99]
	s_waitcnt vmcnt(12) lgkmcnt(0)
	s_barrier
	s_setprio 1
	v_mfma_f32_16x16x32_bf16 v[68:71], v[56:59], v[190:193], v[68:71]
	v_mfma_f32_16x16x32_bf16 v[64:67], v[136:139], v[190:193], v[64:67]
	v_mfma_f32_16x16x32_bf16 v[44:47], v[56:59], v[198:201], v[44:47]
	v_mfma_f32_16x16x32_bf16 v[40:43], v[136:139], v[198:201], v[40:43]
	v_mfma_f32_16x16x32_bf16 v[28:31], v[56:59], v[206:209], v[28:31]
	v_mfma_f32_16x16x32_bf16 v[24:27], v[136:139], v[206:209], v[24:27]
	v_mfma_f32_16x16x32_bf16 v[12:15], v[56:59], v[228:231], v[12:15]
	v_mfma_f32_16x16x32_bf16 v[8:11], v[136:139], v[228:231], v[8:11]
	v_mfma_f32_16x16x32_bf16 v[68:71], v[60:63], v[194:197], v[68:71]
	v_mfma_f32_16x16x32_bf16 v[64:67], v[140:143], v[194:197], v[64:67]
	v_mfma_f32_16x16x32_bf16 v[44:47], v[60:63], v[202:205], v[44:47]
	v_mfma_f32_16x16x32_bf16 v[40:43], v[140:143], v[202:205], v[40:43]
	v_mfma_f32_16x16x32_bf16 v[28:31], v[60:63], v[210:213], v[28:31]
	v_mfma_f32_16x16x32_bf16 v[24:27], v[140:143], v[210:213], v[24:27]
	v_mfma_f32_16x16x32_bf16 v[12:15], v[60:63], v[232:235], v[12:15]
	v_mfma_f32_16x16x32_bf16 v[8:11], v[140:143], v[232:235], v[8:11]
	v_mfma_f32_16x16x32_bf16 v[48:51], v[156:159], v[190:193], v[48:51]
	v_mfma_f32_16x16x32_bf16 v[60:63], v[160:163], v[194:197], v[48:51]
	v_mfma_f32_16x16x32_bf16 v[48:51], v[182:185], v[190:193], v[52:55]
	v_mfma_f32_16x16x32_bf16 v[36:39], v[156:159], v[198:201], v[36:39]
	v_mfma_f32_16x16x32_bf16 v[32:35], v[182:185], v[198:201], v[32:35]
	v_mfma_f32_16x16x32_bf16 v[20:23], v[156:159], v[206:209], v[20:23]
	v_mfma_f32_16x16x32_bf16 v[16:19], v[182:185], v[206:209], v[16:19]
	v_mfma_f32_16x16x32_bf16 v[4:7], v[156:159], v[228:231], v[4:7]
	v_mfma_f32_16x16x32_bf16 v[0:3], v[182:185], v[228:231], v[0:3]
	v_mfma_f32_16x16x32_bf16 v[52:55], v[186:189], v[194:197], v[48:51]
	v_mfma_f32_16x16x32_bf16 v[36:39], v[160:163], v[202:205], v[36:39]
	v_mfma_f32_16x16x32_bf16 v[32:35], v[186:189], v[202:205], v[32:35]
	s_setprio 2
	s_barrier
	v_mfma_f32_16x16x32_bf16 v[20:23], v[160:163], v[210:213], v[20:23]
	v_mfma_f32_16x16x32_bf16 v[16:19], v[186:189], v[210:213], v[16:19]
	v_mfma_f32_16x16x32_bf16 v[4:7], v[160:163], v[232:235], v[4:7]
	v_mfma_f32_16x16x32_bf16 v[0:3], v[186:189], v[232:235], v[0:3]
	s_setprio 0
	s_add_i32 s68, s68, 2
	s_add_u32 s62, s62, 0x100
	s_addc_u32 s63, s63, 0
	s_add_u32 s20, s20, 0x100
	s_addc_u32 s21, s21, 0
	s_cmp_gt_u32 s68, 13
.LBB0_252:
	s_add_u32 s22, s20, 0xfffc0080
	s_addc_u32 s23, s21, -1
	s_add_i32 s64, 0, 0x10000
	s_cmp_eq_u32 s68, 12
	s_cselect_b32 s25, s13, s23
	s_cselect_b32 s24, s19, s22
	s_cselect_b32 s23, s11, s63
	s_cselect_b32 s22, s61, s62
	s_add_i32 s69, 0, 0x14000
	v_add_u32_e32 v140, s64, v167
	v_add_u32_e32 v164, s69, v167
	ds_read_b128 v[48:51], v140
	ds_read_b128 v[56:59], v140 offset:1024
	ds_read_b128 v[136:139], v140 offset:2048
	ds_read_b128 v[140:143], v140 offset:3072
	ds_read_b128 v[156:159], v164
	ds_read_b128 v[160:163], v164 offset:1024
	ds_read_b128 v[182:185], v164 offset:2048
	ds_read_b128 v[186:189], v164 offset:3072
	s_add_i32 m0, s49, 0xc000
	ds_read_b128 v[190:193], v172
	ds_read_b128 v[194:197], v172 offset:1024
	ds_read_b128 v[198:201], v172 offset:2048
	ds_read_b128 v[202:205], v172 offset:3072
	ds_read_b128 v[206:209], v172 offset:4096
	ds_read_b128 v[210:213], v172 offset:5120
	ds_read_b128 v[228:231], v172 offset:6144
	ds_read_b128 v[232:235], v172 offset:7168
	global_load_lds_dwordx4 v154, s[20:21]
	s_add_i32 m0, s49, 0xe000
	s_nop 0
	global_load_lds_dwordx4 v152, s[20:21]
	s_waitcnt vmcnt(8) lgkmcnt(0)
	s_barrier
	s_setprio 1
	v_mfma_f32_16x16x32_bf16 v[132:135], v[48:51], v[190:193], v[132:135]
	v_mfma_f32_16x16x32_bf16 v[124:127], v[136:139], v[190:193], v[124:127]
	v_mfma_f32_16x16x32_bf16 v[116:119], v[48:51], v[198:201], v[116:119]
	v_mfma_f32_16x16x32_bf16 v[112:115], v[136:139], v[198:201], v[112:115]
	v_mfma_f32_16x16x32_bf16 v[100:103], v[48:51], v[206:209], v[100:103]
	v_mfma_f32_16x16x32_bf16 v[96:99], v[136:139], v[206:209], v[96:99]
	v_mfma_f32_16x16x32_bf16 v[84:87], v[48:51], v[228:231], v[84:87]
	v_mfma_f32_16x16x32_bf16 v[80:83], v[136:139], v[228:231], v[80:83]
	v_mfma_f32_16x16x32_bf16 v[132:135], v[56:59], v[194:197], v[132:135]
	v_mfma_f32_16x16x32_bf16 v[124:127], v[140:143], v[194:197], v[124:127]
	v_mfma_f32_16x16x32_bf16 v[116:119], v[56:59], v[202:205], v[116:119]
	v_mfma_f32_16x16x32_bf16 v[112:115], v[140:143], v[202:205], v[112:115]
	v_mfma_f32_16x16x32_bf16 v[100:103], v[56:59], v[210:213], v[100:103]
	v_mfma_f32_16x16x32_bf16 v[96:99], v[140:143], v[210:213], v[96:99]
	v_mfma_f32_16x16x32_bf16 v[84:87], v[56:59], v[232:235], v[84:87]
	v_mfma_f32_16x16x32_bf16 v[80:83], v[140:143], v[232:235], v[80:83]
	v_mfma_f32_16x16x32_bf16 v[128:131], v[156:159], v[190:193], v[128:131]
	v_mfma_f32_16x16x32_bf16 v[120:123], v[182:185], v[190:193], v[120:123]
	v_mfma_f32_16x16x32_bf16 v[108:111], v[156:159], v[198:201], v[108:111]
	v_mfma_f32_16x16x32_bf16 v[104:107], v[182:185], v[198:201], v[104:107]
	v_mfma_f32_16x16x32_bf16 v[92:95], v[156:159], v[206:209], v[92:95]
	v_mfma_f32_16x16x32_bf16 v[88:91], v[182:185], v[206:209], v[88:91]
	v_mfma_f32_16x16x32_bf16 v[76:79], v[156:159], v[228:231], v[76:79]
	v_mfma_f32_16x16x32_bf16 v[72:75], v[182:185], v[228:231], v[72:75]
	v_mfma_f32_16x16x32_bf16 v[128:131], v[160:163], v[194:197], v[128:131]
	v_mfma_f32_16x16x32_bf16 v[120:123], v[186:189], v[194:197], v[120:123]
	v_mfma_f32_16x16x32_bf16 v[108:111], v[160:163], v[202:205], v[108:111]
	v_mfma_f32_16x16x32_bf16 v[104:107], v[186:189], v[202:205], v[104:107]
	s_setprio 2
	s_barrier
	v_mfma_f32_16x16x32_bf16 v[92:95], v[160:163], v[210:213], v[92:95]
	v_mfma_f32_16x16x32_bf16 v[88:91], v[186:189], v[210:213], v[88:91]
	v_mfma_f32_16x16x32_bf16 v[76:79], v[160:163], v[232:235], v[76:79]
	v_mfma_f32_16x16x32_bf16 v[72:75], v[186:189], v[232:235], v[72:75]
	s_setprio 0
	s_add_i32 s64, s64, s41
	s_add_u32 s94, s22, s34
	s_addc_u32 s95, s23, s35
	s_mov_b32 m0, s64
	ds_read_b128 v[190:193], v172 offset:16384
	ds_read_b128 v[194:197], v172 offset:17408
	ds_read_b128 v[198:201], v172 offset:18432
	ds_read_b128 v[202:205], v172 offset:19456
	ds_read_b128 v[206:209], v172 offset:20480
	ds_read_b128 v[210:213], v172 offset:21504
	ds_read_b128 v[228:231], v172 offset:22528
	ds_read_b128 v[232:235], v172 offset:23552
	global_load_lds_dwordx4 v148, s[22:23]
	s_add_i32 m0, s64, 0x2000
	s_add_u32 s64, s22, 0x40000
	s_addc_u32 s65, s23, 0
	s_add_i32 s69, s69, s41
	global_load_lds_dwordx4 v144, s[22:23]
	s_mov_b32 m0, s69
	s_nop 0
	global_load_lds_dwordx4 v148, s[64:65]
	s_add_i32 m0, s69, 0x2000
	s_nop 0
	global_load_lds_dwordx4 v144, s[64:65]
	s_add_u32 s98, s24, s34
	s_addc_u32 s99, s25, s35
	s_mov_b32 m0, s49
	s_nop 0
	global_load_lds_dwordx4 v150, s[24:25]
	s_waitcnt vmcnt(7) lgkmcnt(0)
	s_barrier
	s_setprio 1
	v_mfma_f32_16x16x32_bf16 v[68:71], v[48:51], v[190:193], v[68:71]
	v_mfma_f32_16x16x32_bf16 v[64:67], v[136:139], v[190:193], v[64:67]
	v_mfma_f32_16x16x32_bf16 v[44:47], v[48:51], v[198:201], v[44:47]
	v_mfma_f32_16x16x32_bf16 v[40:43], v[136:139], v[198:201], v[40:43]
	v_mfma_f32_16x16x32_bf16 v[28:31], v[48:51], v[206:209], v[28:31]
	v_mfma_f32_16x16x32_bf16 v[24:27], v[136:139], v[206:209], v[24:27]
	v_mfma_f32_16x16x32_bf16 v[12:15], v[48:51], v[228:231], v[12:15]
	v_mfma_f32_16x16x32_bf16 v[8:11], v[136:139], v[228:231], v[8:11]
	v_mfma_f32_16x16x32_bf16 v[68:71], v[56:59], v[194:197], v[68:71]
	v_mfma_f32_16x16x32_bf16 v[64:67], v[140:143], v[194:197], v[64:67]
	v_mfma_f32_16x16x32_bf16 v[44:47], v[56:59], v[202:205], v[44:47]
	v_mfma_f32_16x16x32_bf16 v[40:43], v[140:143], v[202:205], v[40:43]
	v_mfma_f32_16x16x32_bf16 v[28:31], v[56:59], v[210:213], v[28:31]
	v_mfma_f32_16x16x32_bf16 v[24:27], v[140:143], v[210:213], v[24:27]
	v_mfma_f32_16x16x32_bf16 v[12:15], v[56:59], v[232:235], v[12:15]
	v_mfma_f32_16x16x32_bf16 v[8:11], v[140:143], v[232:235], v[8:11]
	v_mfma_f32_16x16x32_bf16 v[52:55], v[182:185], v[190:193], v[52:55]
	v_mfma_f32_16x16x32_bf16 v[36:39], v[156:159], v[198:201], v[36:39]
	v_mfma_f32_16x16x32_bf16 v[32:35], v[182:185], v[198:201], v[32:35]
	v_mfma_f32_16x16x32_bf16 v[20:23], v[156:159], v[206:209], v[20:23]
	v_mfma_f32_16x16x32_bf16 v[16:19], v[182:185], v[206:209], v[16:19]
	v_mfma_f32_16x16x32_bf16 v[4:7], v[156:159], v[228:231], v[4:7]
	v_mfma_f32_16x16x32_bf16 v[0:3], v[182:185], v[228:231], v[0:3]
	v_mfma_f32_16x16x32_bf16 v[48:51], v[156:159], v[190:193], v[60:63]
	v_mfma_f32_16x16x32_bf16 v[52:55], v[186:189], v[194:197], v[52:55]
	v_mfma_f32_16x16x32_bf16 v[36:39], v[160:163], v[202:205], v[36:39]
	v_mfma_f32_16x16x32_bf16 v[32:35], v[186:189], v[202:205], v[32:35]
	v_mfma_f32_16x16x32_bf16 v[20:23], v[160:163], v[210:213], v[20:23]
	s_setprio 2
	s_barrier
	v_mfma_f32_16x16x32_bf16 v[16:19], v[186:189], v[210:213], v[16:19]
	v_mfma_f32_16x16x32_bf16 v[4:7], v[160:163], v[232:235], v[4:7]
	v_mfma_f32_16x16x32_bf16 v[0:3], v[186:189], v[232:235], v[0:3]
	v_mfma_f32_16x16x32_bf16 v[48:51], v[160:163], v[194:197], v[48:51]
	s_setprio 0
	s_mov_b32 m0, s50
	s_nop 0
	global_load_lds_dwordx4 v146, s[24:25]
	s_add_i32 s64, 0, 0x18000
	s_add_i32 s65, 0, 0x1c000
	v_add_u32_e32 v140, s64, v167
	v_add_u32_e32 v173, s65, v167
	ds_read_b128 v[56:59], v140
	ds_read_b128 v[60:63], v140 offset:1024
	ds_read_b128 v[136:139], v140 offset:2048
	ds_read_b128 v[140:143], v140 offset:3072
	ds_read_b128 v[156:159], v173
	ds_read_b128 v[160:163], v173 offset:1024
	ds_read_b128 v[182:185], v173 offset:2048
	ds_read_b128 v[186:189], v173 offset:3072
	s_add_u32 s24, s24, 0x40000
	s_addc_u32 s25, s25, 0
	s_mov_b32 m0, s51
	ds_read_b128 v[190:193], v172 offset:32768
	ds_read_b128 v[194:197], v172 offset:33792
	ds_read_b128 v[198:201], v172 offset:34816
	ds_read_b128 v[202:205], v172 offset:35840
	ds_read_b128 v[206:209], v172 offset:36864
	ds_read_b128 v[210:213], v172 offset:37888
	ds_read_b128 v[228:231], v172 offset:38912
	ds_read_b128 v[232:235], v172 offset:39936
	global_load_lds_dwordx4 v150, s[24:25]
	s_mov_b32 m0, s52
	s_nop 0
	global_load_lds_dwordx4 v146, s[24:25]
	s_waitcnt vmcnt(8) lgkmcnt(0)
	s_barrier
	s_setprio 1
	v_mfma_f32_16x16x32_bf16 v[132:135], v[56:59], v[190:193], v[132:135]
	v_mfma_f32_16x16x32_bf16 v[124:127], v[136:139], v[190:193], v[124:127]
	v_mfma_f32_16x16x32_bf16 v[116:119], v[56:59], v[198:201], v[116:119]
	v_mfma_f32_16x16x32_bf16 v[112:115], v[136:139], v[198:201], v[112:115]
	v_mfma_f32_16x16x32_bf16 v[100:103], v[56:59], v[206:209], v[100:103]
	v_mfma_f32_16x16x32_bf16 v[96:99], v[136:139], v[206:209], v[96:99]
	v_mfma_f32_16x16x32_bf16 v[84:87], v[56:59], v[228:231], v[84:87]
	v_mfma_f32_16x16x32_bf16 v[80:83], v[136:139], v[228:231], v[80:83]
	v_mfma_f32_16x16x32_bf16 v[132:135], v[60:63], v[194:197], v[132:135]
	v_mfma_f32_16x16x32_bf16 v[124:127], v[140:143], v[194:197], v[124:127]
	v_mfma_f32_16x16x32_bf16 v[116:119], v[60:63], v[202:205], v[116:119]
	v_mfma_f32_16x16x32_bf16 v[112:115], v[140:143], v[202:205], v[112:115]
	v_mfma_f32_16x16x32_bf16 v[100:103], v[60:63], v[210:213], v[100:103]
	v_mfma_f32_16x16x32_bf16 v[96:99], v[140:143], v[210:213], v[96:99]
	v_mfma_f32_16x16x32_bf16 v[84:87], v[60:63], v[232:235], v[84:87]
	v_mfma_f32_16x16x32_bf16 v[80:83], v[140:143], v[232:235], v[80:83]
	v_mfma_f32_16x16x32_bf16 v[128:131], v[156:159], v[190:193], v[128:131]
	v_mfma_f32_16x16x32_bf16 v[120:123], v[182:185], v[190:193], v[120:123]
	v_mfma_f32_16x16x32_bf16 v[108:111], v[156:159], v[198:201], v[108:111]
	v_mfma_f32_16x16x32_bf16 v[104:107], v[182:185], v[198:201], v[104:107]
	v_mfma_f32_16x16x32_bf16 v[92:95], v[156:159], v[206:209], v[92:95]
	v_mfma_f32_16x16x32_bf16 v[88:91], v[182:185], v[206:209], v[88:91]
	v_mfma_f32_16x16x32_bf16 v[76:79], v[156:159], v[228:231], v[76:79]
	v_mfma_f32_16x16x32_bf16 v[72:75], v[182:185], v[228:231], v[72:75]
	v_mfma_f32_16x16x32_bf16 v[128:131], v[160:163], v[194:197], v[128:131]
	v_mfma_f32_16x16x32_bf16 v[120:123], v[186:189], v[194:197], v[120:123]
	v_mfma_f32_16x16x32_bf16 v[108:111], v[160:163], v[202:205], v[108:111]
	v_mfma_f32_16x16x32_bf16 v[104:107], v[186:189], v[202:205], v[104:107]
	s_setprio 2
	s_barrier
	v_mfma_f32_16x16x32_bf16 v[92:95], v[160:163], v[210:213], v[92:95]
	v_mfma_f32_16x16x32_bf16 v[88:91], v[186:189], v[210:213], v[88:91]
	v_mfma_f32_16x16x32_bf16 v[76:79], v[160:163], v[232:235], v[76:79]
	v_mfma_f32_16x16x32_bf16 v[72:75], v[186:189], v[232:235], v[72:75]
	s_setprio 0
	s_add_i32 s24, s64, s41
	s_mov_b32 m0, s24
	ds_read_b128 v[190:193], v172 offset:49152
	ds_read_b128 v[194:197], v172 offset:50176
	ds_read_b128 v[198:201], v172 offset:51200
	ds_read_b128 v[202:205], v172 offset:52224
	ds_read_b128 v[206:209], v172 offset:53248
	ds_read_b128 v[210:213], v172 offset:54272
	ds_read_b128 v[228:231], v172 offset:55296
	ds_read_b128 v[232:235], v172 offset:56320
	global_load_lds_dwordx4 v148, s[94:95]
	s_add_i32 m0, s24, 0x2000
	s_add_u32 s22, s22, 0x40080
	s_addc_u32 s23, s23, 0
	s_add_i32 s24, s65, s41
	global_load_lds_dwordx4 v144, s[94:95]
	s_mov_b32 m0, s24
	s_nop 0
	global_load_lds_dwordx4 v148, s[22:23]
	s_add_i32 m0, s24, 0x2000
	s_nop 0
	global_load_lds_dwordx4 v144, s[22:23]
	s_mov_b32 m0, s55
	s_nop 0
	global_load_lds_dwordx4 v150, s[98:99]
	s_mov_b32 m0, s56
	s_nop 0
	global_load_lds_dwordx4 v146, s[98:99]
	s_waitcnt vmcnt(8) lgkmcnt(0)
	s_barrier
	s_setprio 1
	v_mfma_f32_16x16x32_bf16 v[68:71], v[56:59], v[190:193], v[68:71]
	v_mfma_f32_16x16x32_bf16 v[64:67], v[136:139], v[190:193], v[64:67]
	v_mfma_f32_16x16x32_bf16 v[44:47], v[56:59], v[198:201], v[44:47]
	v_mfma_f32_16x16x32_bf16 v[40:43], v[136:139], v[198:201], v[40:43]
	v_mfma_f32_16x16x32_bf16 v[28:31], v[56:59], v[206:209], v[28:31]
	v_mfma_f32_16x16x32_bf16 v[24:27], v[136:139], v[206:209], v[24:27]
	v_mfma_f32_16x16x32_bf16 v[12:15], v[56:59], v[228:231], v[12:15]
	v_mfma_f32_16x16x32_bf16 v[8:11], v[136:139], v[228:231], v[8:11]
	v_mfma_f32_16x16x32_bf16 v[68:71], v[60:63], v[194:197], v[68:71]
	v_mfma_f32_16x16x32_bf16 v[64:67], v[140:143], v[194:197], v[64:67]
	v_mfma_f32_16x16x32_bf16 v[44:47], v[60:63], v[202:205], v[44:47]
	v_mfma_f32_16x16x32_bf16 v[40:43], v[140:143], v[202:205], v[40:43]
	v_mfma_f32_16x16x32_bf16 v[28:31], v[60:63], v[210:213], v[28:31]
	v_mfma_f32_16x16x32_bf16 v[24:27], v[140:143], v[210:213], v[24:27]
	v_mfma_f32_16x16x32_bf16 v[12:15], v[60:63], v[232:235], v[12:15]
	v_mfma_f32_16x16x32_bf16 v[8:11], v[140:143], v[232:235], v[8:11]
	v_mfma_f32_16x16x32_bf16 v[48:51], v[156:159], v[190:193], v[48:51]
	v_mfma_f32_16x16x32_bf16 v[60:63], v[160:163], v[194:197], v[48:51]
	v_mfma_f32_16x16x32_bf16 v[48:51], v[182:185], v[190:193], v[52:55]
	v_mfma_f32_16x16x32_bf16 v[36:39], v[156:159], v[198:201], v[36:39]
	v_mfma_f32_16x16x32_bf16 v[32:35], v[182:185], v[198:201], v[32:35]
	v_mfma_f32_16x16x32_bf16 v[20:23], v[156:159], v[206:209], v[20:23]
	v_mfma_f32_16x16x32_bf16 v[16:19], v[182:185], v[206:209], v[16:19]
	v_mfma_f32_16x16x32_bf16 v[4:7], v[156:159], v[228:231], v[4:7]
	v_mfma_f32_16x16x32_bf16 v[0:3], v[182:185], v[228:231], v[0:3]
	v_mfma_f32_16x16x32_bf16 v[52:55], v[186:189], v[194:197], v[48:51]
	v_mfma_f32_16x16x32_bf16 v[36:39], v[160:163], v[202:205], v[36:39]
	v_mfma_f32_16x16x32_bf16 v[32:35], v[186:189], v[202:205], v[32:35]
	s_setprio 2
	s_barrier
	v_mfma_f32_16x16x32_bf16 v[20:23], v[160:163], v[210:213], v[20:23]
	v_mfma_f32_16x16x32_bf16 v[16:19], v[186:189], v[210:213], v[16:19]
	v_mfma_f32_16x16x32_bf16 v[4:7], v[160:163], v[232:235], v[4:7]
	v_mfma_f32_16x16x32_bf16 v[0:3], v[186:189], v[232:235], v[0:3]
	s_setprio 0
	s_add_i32 s68, s68, 2
	s_add_u32 s62, s62, 0x100
	s_addc_u32 s63, s63, 0
	s_add_u32 s20, s20, 0x100
	s_addc_u32 s21, s21, 0
	s_cmp_gt_u32 s68, 13
	s_cbranch_scc0 .LBB0_252
	s_and_b64 vcc, exec, s[8:9]
	s_cbranch_vccz .LBB0_255
	s_barrier

.LBB0_318:
	s_ashr_i32 s15, s14, 31
	s_lshl_b64 s[16:17], s[14:15], 19
	s_add_u32 s16, s37, s16
	s_addc_u32 s17, s42, s17
	s_and_b64 s[18:19], s[6:7], exec
	s_cselect_b32 s9, s17, s25
	s_cselect_b32 s15, s16, s24
	s_ashr_i32 s13, s12, 31
	s_lshl_b64 s[18:19], s[12:13], 19
	s_add_u32 s18, s38, s18
	s_addc_u32 s19, s39, s19
	s_and_b64 s[26:27], s[6:7], exec
	s_cselect_b32 s13, s19, s23
	s_cselect_b32 s21, s18, s22
	s_add_u32 s44, s22, 0x100
	s_addc_u32 s62, s23, 0
	s_add_u32 s22, s24, 0x40080
	s_addc_u32 s23, s25, 0
	s_mov_b32 s63, -2
	s_add_u32 s24, s22, 0xfffc0080
	s_addc_u32 s25, s23, -1
	s_add_i32 s64, 0, 0x10000
	s_cmp_eq_u32 s63, 12
	s_cselect_b32 s27, s9, s25
	s_cselect_b32 s26, s15, s24
	s_cselect_b32 s25, s13, s62
	s_cselect_b32 s24, s21, s44
	s_add_i32 s68, 0, 0x14000
	v_add_u32_e32 v112, s64, v159
	v_add_u32_e32 v165, s68, v159
	ds_read_b128 v[96:99], v112
	ds_read_b128 v[100:103], v112 offset:1024
	ds_read_b128 v[108:111], v112 offset:2048
	ds_read_b128 v[112:115], v112 offset:3072
	ds_read_b128 v[154:157], v165
	ds_read_b128 v[166:169], v165 offset:1024
	ds_read_b128 v[170:173], v165 offset:2048
	ds_read_b128 v[182:185], v165 offset:3072
	s_add_i32 m0, s50, 0xc000
	ds_read_b128 v[186:189], v164
	ds_read_b128 v[190:193], v164 offset:1024
	ds_read_b128 v[194:197], v164 offset:2048
	ds_read_b128 v[198:201], v164 offset:3072
	ds_read_b128 v[202:205], v164 offset:4096
	ds_read_b128 v[206:209], v164 offset:5120
	ds_read_b128 v[210:213], v164 offset:6144
	ds_read_b128 v[228:231], v164 offset:7168
	global_load_lds_dwordx4 v152, s[22:23]
	s_add_i32 m0, s50, 0xe000
	s_nop 0
	global_load_lds_dwordx4 v150, s[22:23]
	s_waitcnt vmcnt(8) lgkmcnt(0)
	s_barrier
	s_setprio 1
	v_mfma_f32_16x16x32_bf16 v[140:143], v[96:99], v[186:189], 0
	v_mfma_f32_16x16x32_bf16 v[136:139], v[108:111], v[186:189], 0
	v_mfma_f32_16x16x32_bf16 v[124:127], v[96:99], v[194:197], 0
	v_mfma_f32_16x16x32_bf16 v[120:123], v[108:111], v[194:197], 0
	v_mfma_f32_16x16x32_bf16 v[92:95], v[96:99], v[202:205], 0
	v_mfma_f32_16x16x32_bf16 v[88:91], v[108:111], v[202:205], 0
	v_mfma_f32_16x16x32_bf16 v[76:79], v[96:99], v[210:213], 0
	v_mfma_f32_16x16x32_bf16 v[72:75], v[108:111], v[210:213], 0
	v_mfma_f32_16x16x32_bf16 v[140:143], v[100:103], v[190:193], v[140:143]
	v_mfma_f32_16x16x32_bf16 v[136:139], v[112:115], v[190:193], v[136:139]
	v_mfma_f32_16x16x32_bf16 v[124:127], v[100:103], v[198:201], v[124:127]
	v_mfma_f32_16x16x32_bf16 v[120:123], v[112:115], v[198:201], v[120:123]
	v_mfma_f32_16x16x32_bf16 v[92:95], v[100:103], v[206:209], v[92:95]
	v_mfma_f32_16x16x32_bf16 v[88:91], v[112:115], v[206:209], v[88:91]
	v_mfma_f32_16x16x32_bf16 v[76:79], v[100:103], v[228:231], v[76:79]
	v_mfma_f32_16x16x32_bf16 v[72:75], v[112:115], v[228:231], v[72:75]
	v_mfma_f32_16x16x32_bf16 v[132:135], v[154:157], v[186:189], 0
	v_mfma_f32_16x16x32_bf16 v[128:131], v[170:173], v[186:189], 0
	v_mfma_f32_16x16x32_bf16 v[116:119], v[154:157], v[194:197], 0
	v_mfma_f32_16x16x32_bf16 v[104:107], v[170:173], v[194:197], 0
	v_mfma_f32_16x16x32_bf16 v[84:87], v[154:157], v[202:205], 0
	v_mfma_f32_16x16x32_bf16 v[80:83], v[170:173], v[202:205], 0
	v_mfma_f32_16x16x32_bf16 v[68:71], v[154:157], v[210:213], 0
	v_mfma_f32_16x16x32_bf16 v[64:67], v[170:173], v[210:213], 0
	v_mfma_f32_16x16x32_bf16 v[132:135], v[166:169], v[190:193], v[132:135]
	v_mfma_f32_16x16x32_bf16 v[128:131], v[182:185], v[190:193], v[128:131]
	v_mfma_f32_16x16x32_bf16 v[116:119], v[166:169], v[198:201], v[116:119]
	v_mfma_f32_16x16x32_bf16 v[104:107], v[182:185], v[198:201], v[104:107]
	s_setprio 2
	s_barrier
	v_mfma_f32_16x16x32_bf16 v[84:87], v[166:169], v[206:209], v[84:87]
	v_mfma_f32_16x16x32_bf16 v[80:83], v[182:185], v[206:209], v[80:83]
	v_mfma_f32_16x16x32_bf16 v[68:71], v[166:169], v[228:231], v[68:71]
	v_mfma_f32_16x16x32_bf16 v[64:67], v[182:185], v[228:231], v[64:67]
	s_setprio 0
	s_add_i32 s64, s64, s43
	s_add_u32 s94, s24, s34
	s_addc_u32 s95, s25, s35
	s_mov_b32 m0, s64
	ds_read_b128 v[186:189], v164 offset:16384
	ds_read_b128 v[190:193], v164 offset:17408
	ds_read_b128 v[194:197], v164 offset:18432
	ds_read_b128 v[198:201], v164 offset:19456
	ds_read_b128 v[202:205], v164 offset:20480
	ds_read_b128 v[206:209], v164 offset:21504
	ds_read_b128 v[210:213], v164 offset:22528
	ds_read_b128 v[228:231], v164 offset:23552
	global_load_lds_dwordx4 v176, s[24:25]
	s_add_i32 m0, s64, 0x2000
	s_add_u32 s64, s24, 0x40000
	s_addc_u32 s65, s25, 0
	s_add_i32 s68, s68, s43
	global_load_lds_dwordx4 v148, s[24:25]
	s_mov_b32 m0, s68
	s_nop 0
	global_load_lds_dwordx4 v176, s[64:65]
	s_add_i32 m0, s68, 0x2000
	s_nop 0
	global_load_lds_dwordx4 v148, s[64:65]
	s_add_u32 s98, s26, s34
	s_addc_u32 s99, s27, s35
	s_mov_b32 m0, s50
	s_nop 0
	global_load_lds_dwordx4 v144, s[26:27]
	s_waitcnt vmcnt(7) lgkmcnt(0)
	s_barrier
	s_setprio 1
	v_mfma_f32_16x16x32_bf16 v[60:63], v[96:99], v[186:189], 0
	v_mfma_f32_16x16x32_bf16 v[56:59], v[108:111], v[186:189], 0
	v_mfma_f32_16x16x32_bf16 v[44:47], v[96:99], v[194:197], 0
	v_mfma_f32_16x16x32_bf16 v[40:43], v[108:111], v[194:197], 0
	v_mfma_f32_16x16x32_bf16 v[28:31], v[96:99], v[202:205], 0
	v_mfma_f32_16x16x32_bf16 v[24:27], v[108:111], v[202:205], 0
	v_mfma_f32_16x16x32_bf16 v[12:15], v[96:99], v[210:213], 0
	v_mfma_f32_16x16x32_bf16 v[8:11], v[108:111], v[210:213], 0
	v_mfma_f32_16x16x32_bf16 v[60:63], v[100:103], v[190:193], v[60:63]
	v_mfma_f32_16x16x32_bf16 v[56:59], v[112:115], v[190:193], v[56:59]
	v_mfma_f32_16x16x32_bf16 v[44:47], v[100:103], v[198:201], v[44:47]
	v_mfma_f32_16x16x32_bf16 v[40:43], v[112:115], v[198:201], v[40:43]
	v_mfma_f32_16x16x32_bf16 v[28:31], v[100:103], v[206:209], v[28:31]
	v_mfma_f32_16x16x32_bf16 v[24:27], v[112:115], v[206:209], v[24:27]
	v_mfma_f32_16x16x32_bf16 v[12:15], v[100:103], v[228:231], v[12:15]
	v_mfma_f32_16x16x32_bf16 v[8:11], v[112:115], v[228:231], v[8:11]
	v_mfma_f32_16x16x32_bf16 v[52:55], v[154:157], v[186:189], 0
	v_mfma_f32_16x16x32_bf16 v[48:51], v[170:173], v[186:189], 0
	v_mfma_f32_16x16x32_bf16 v[36:39], v[154:157], v[194:197], 0
	v_mfma_f32_16x16x32_bf16 v[32:35], v[170:173], v[194:197], 0
	v_mfma_f32_16x16x32_bf16 v[20:23], v[154:157], v[202:205], 0
	v_mfma_f32_16x16x32_bf16 v[16:19], v[170:173], v[202:205], 0
	v_mfma_f32_16x16x32_bf16 v[4:7], v[154:157], v[210:213], 0
	v_mfma_f32_16x16x32_bf16 v[0:3], v[170:173], v[210:213], 0
	v_mfma_f32_16x16x32_bf16 v[52:55], v[166:169], v[190:193], v[52:55]
	v_mfma_f32_16x16x32_bf16 v[48:51], v[182:185], v[190:193], v[48:51]
	v_mfma_f32_16x16x32_bf16 v[36:39], v[166:169], v[198:201], v[36:39]
	v_mfma_f32_16x16x32_bf16 v[32:35], v[182:185], v[198:201], v[32:35]
	s_setprio 2
	s_barrier
	v_mfma_f32_16x16x32_bf16 v[20:23], v[166:169], v[206:209], v[20:23]
	v_mfma_f32_16x16x32_bf16 v[16:19], v[182:185], v[206:209], v[16:19]
	v_mfma_f32_16x16x32_bf16 v[4:7], v[166:169], v[228:231], v[4:7]
	v_mfma_f32_16x16x32_bf16 v[0:3], v[182:185], v[228:231], v[0:3]
	s_setprio 0
	s_mov_b32 m0, s51
	s_nop 0
	global_load_lds_dwordx4 v146, s[26:27]
	s_add_i32 s64, 0, 0x18000
	s_add_i32 s65, 0, 0x1c000
	v_add_u32_e32 v112, s64, v159
	v_add_u32_e32 v165, s65, v159
	ds_read_b128 v[96:99], v112
	ds_read_b128 v[100:103], v112 offset:1024
	ds_read_b128 v[108:111], v112 offset:2048
	ds_read_b128 v[112:115], v112 offset:3072
	ds_read_b128 v[154:157], v165
	ds_read_b128 v[166:169], v165 offset:1024
	ds_read_b128 v[170:173], v165 offset:2048
	ds_read_b128 v[182:185], v165 offset:3072
	s_add_u32 s26, s26, 0x40000
	s_addc_u32 s27, s27, 0
	s_mov_b32 m0, s52
	ds_read_b128 v[186:189], v164 offset:32768
	ds_read_b128 v[190:193], v164 offset:33792
	ds_read_b128 v[194:197], v164 offset:34816
	ds_read_b128 v[198:201], v164 offset:35840
	ds_read_b128 v[202:205], v164 offset:36864
	ds_read_b128 v[206:209], v164 offset:37888
	ds_read_b128 v[210:213], v164 offset:38912
	ds_read_b128 v[228:231], v164 offset:39936
	global_load_lds_dwordx4 v144, s[26:27]
	s_mov_b32 m0, s53
	s_nop 0
	global_load_lds_dwordx4 v146, s[26:27]
	s_waitcnt vmcnt(8) lgkmcnt(0)
	s_barrier
	s_setprio 1
	v_mfma_f32_16x16x32_bf16 v[140:143], v[96:99], v[186:189], v[140:143]
	v_mfma_f32_16x16x32_bf16 v[136:139], v[108:111], v[186:189], v[136:139]
	v_mfma_f32_16x16x32_bf16 v[124:127], v[96:99], v[194:197], v[124:127]
	v_mfma_f32_16x16x32_bf16 v[120:123], v[108:111], v[194:197], v[120:123]
	v_mfma_f32_16x16x32_bf16 v[92:95], v[96:99], v[202:205], v[92:95]
	v_mfma_f32_16x16x32_bf16 v[88:91], v[108:111], v[202:205], v[88:91]
	v_mfma_f32_16x16x32_bf16 v[76:79], v[96:99], v[210:213], v[76:79]
	v_mfma_f32_16x16x32_bf16 v[72:75], v[108:111], v[210:213], v[72:75]
	v_mfma_f32_16x16x32_bf16 v[140:143], v[100:103], v[190:193], v[140:143]
	v_mfma_f32_16x16x32_bf16 v[136:139], v[112:115], v[190:193], v[136:139]
	v_mfma_f32_16x16x32_bf16 v[124:127], v[100:103], v[198:201], v[124:127]
	v_mfma_f32_16x16x32_bf16 v[120:123], v[112:115], v[198:201], v[120:123]
	v_mfma_f32_16x16x32_bf16 v[92:95], v[100:103], v[206:209], v[92:95]
	v_mfma_f32_16x16x32_bf16 v[88:91], v[112:115], v[206:209], v[88:91]
	v_mfma_f32_16x16x32_bf16 v[76:79], v[100:103], v[228:231], v[76:79]
	v_mfma_f32_16x16x32_bf16 v[72:75], v[112:115], v[228:231], v[72:75]
	v_mfma_f32_16x16x32_bf16 v[132:135], v[154:157], v[186:189], v[132:135]
	v_mfma_f32_16x16x32_bf16 v[128:131], v[170:173], v[186:189], v[128:131]
	v_mfma_f32_16x16x32_bf16 v[116:119], v[154:157], v[194:197], v[116:119]
	v_mfma_f32_16x16x32_bf16 v[104:107], v[170:173], v[194:197], v[104:107]
	v_mfma_f32_16x16x32_bf16 v[84:87], v[154:157], v[202:205], v[84:87]
	v_mfma_f32_16x16x32_bf16 v[80:83], v[170:173], v[202:205], v[80:83]
	v_mfma_f32_16x16x32_bf16 v[68:71], v[154:157], v[210:213], v[68:71]
	v_mfma_f32_16x16x32_bf16 v[64:67], v[170:173], v[210:213], v[64:67]
	v_mfma_f32_16x16x32_bf16 v[132:135], v[166:169], v[190:193], v[132:135]
	v_mfma_f32_16x16x32_bf16 v[128:131], v[182:185], v[190:193], v[128:131]
	v_mfma_f32_16x16x32_bf16 v[116:119], v[166:169], v[198:201], v[116:119]
	v_mfma_f32_16x16x32_bf16 v[104:107], v[182:185], v[198:201], v[104:107]
	s_setprio 2
	s_barrier
	v_mfma_f32_16x16x32_bf16 v[84:87], v[166:169], v[206:209], v[84:87]
	v_mfma_f32_16x16x32_bf16 v[80:83], v[182:185], v[206:209], v[80:83]
	v_mfma_f32_16x16x32_bf16 v[68:71], v[166:169], v[228:231], v[68:71]
	v_mfma_f32_16x16x32_bf16 v[64:67], v[182:185], v[228:231], v[64:67]
	s_setprio 0
	s_add_i32 s26, s64, s43
	s_mov_b32 m0, s26
	ds_read_b128 v[186:189], v164 offset:49152
	ds_read_b128 v[190:193], v164 offset:50176
	ds_read_b128 v[194:197], v164 offset:51200
	ds_read_b128 v[198:201], v164 offset:52224
	ds_read_b128 v[202:205], v164 offset:53248
	ds_read_b128 v[206:209], v164 offset:54272
	ds_read_b128 v[210:213], v164 offset:55296
	ds_read_b128 v[228:231], v164 offset:56320
	global_load_lds_dwordx4 v176, s[94:95]
	s_add_i32 m0, s26, 0x2000
	s_add_u32 s24, s24, 0x40080
	s_addc_u32 s25, s25, 0
	s_add_i32 s26, s65, s43
	global_load_lds_dwordx4 v148, s[94:95]
	s_mov_b32 m0, s26
	s_nop 0
	global_load_lds_dwordx4 v176, s[24:25]
	s_add_i32 m0, s26, 0x2000
	s_nop 0
	global_load_lds_dwordx4 v148, s[24:25]
	s_mov_b32 m0, s57
	s_nop 0
	global_load_lds_dwordx4 v144, s[98:99]
	s_mov_b32 m0, s58
	s_nop 0
	global_load_lds_dwordx4 v146, s[98:99]
	s_waitcnt vmcnt(8) lgkmcnt(0)
	s_barrier
	s_setprio 1
	v_mfma_f32_16x16x32_bf16 v[60:63], v[96:99], v[186:189], v[60:63]
	v_mfma_f32_16x16x32_bf16 v[56:59], v[108:111], v[186:189], v[56:59]
	v_mfma_f32_16x16x32_bf16 v[44:47], v[96:99], v[194:197], v[44:47]
	v_mfma_f32_16x16x32_bf16 v[40:43], v[108:111], v[194:197], v[40:43]
	v_mfma_f32_16x16x32_bf16 v[28:31], v[96:99], v[202:205], v[28:31]
	v_mfma_f32_16x16x32_bf16 v[24:27], v[108:111], v[202:205], v[24:27]
	v_mfma_f32_16x16x32_bf16 v[12:15], v[96:99], v[210:213], v[12:15]
	v_mfma_f32_16x16x32_bf16 v[8:11], v[108:111], v[210:213], v[8:11]
	v_mfma_f32_16x16x32_bf16 v[60:63], v[100:103], v[190:193], v[60:63]
	v_mfma_f32_16x16x32_bf16 v[56:59], v[112:115], v[190:193], v[56:59]
	v_mfma_f32_16x16x32_bf16 v[44:47], v[100:103], v[198:201], v[44:47]
	v_mfma_f32_16x16x32_bf16 v[40:43], v[112:115], v[198:201], v[40:43]
	v_mfma_f32_16x16x32_bf16 v[28:31], v[100:103], v[206:209], v[28:31]
	v_mfma_f32_16x16x32_bf16 v[24:27], v[112:115], v[206:209], v[24:27]
	v_mfma_f32_16x16x32_bf16 v[12:15], v[100:103], v[228:231], v[12:15]
	v_mfma_f32_16x16x32_bf16 v[8:11], v[112:115], v[228:231], v[8:11]
	v_mfma_f32_16x16x32_bf16 v[52:55], v[154:157], v[186:189], v[52:55]
	v_mfma_f32_16x16x32_bf16 v[48:51], v[170:173], v[186:189], v[48:51]
	v_mfma_f32_16x16x32_bf16 v[36:39], v[154:157], v[194:197], v[36:39]
	v_mfma_f32_16x16x32_bf16 v[32:35], v[170:173], v[194:197], v[32:35]
	v_mfma_f32_16x16x32_bf16 v[20:23], v[154:157], v[202:205], v[20:23]
	v_mfma_f32_16x16x32_bf16 v[16:19], v[170:173], v[202:205], v[16:19]
	v_mfma_f32_16x16x32_bf16 v[4:7], v[154:157], v[210:213], v[4:7]
	v_mfma_f32_16x16x32_bf16 v[0:3], v[170:173], v[210:213], v[0:3]
	v_mfma_f32_16x16x32_bf16 v[52:55], v[166:169], v[190:193], v[52:55]
	v_mfma_f32_16x16x32_bf16 v[48:51], v[182:185], v[190:193], v[48:51]
	v_mfma_f32_16x16x32_bf16 v[36:39], v[166:169], v[198:201], v[36:39]
	v_mfma_f32_16x16x32_bf16 v[32:35], v[182:185], v[198:201], v[32:35]
	s_setprio 2
	s_barrier
	v_mfma_f32_16x16x32_bf16 v[20:23], v[166:169], v[206:209], v[20:23]
	v_mfma_f32_16x16x32_bf16 v[16:19], v[182:185], v[206:209], v[16:19]
	v_mfma_f32_16x16x32_bf16 v[4:7], v[166:169], v[228:231], v[4:7]
	v_mfma_f32_16x16x32_bf16 v[0:3], v[182:185], v[228:231], v[0:3]
	s_setprio 0
	s_add_i32 s63, s63, 2
	s_add_u32 s44, s44, 0x100
	s_addc_u32 s62, s62, 0
	s_add_u32 s22, s22, 0x100
	s_addc_u32 s23, s23, 0
	s_cmp_gt_u32 s63, 13
	s_cbranch_scc1 .Lpeel_exit_0
.LBB0_319:
	s_add_u32 s24, s22, 0xfffc0080
	s_addc_u32 s25, s23, -1
	s_add_i32 s64, 0, 0x10000
	s_cmp_eq_u32 s63, 12
	s_cselect_b32 s27, s9, s25
	s_cselect_b32 s26, s15, s24
	s_cselect_b32 s25, s13, s62
	s_cselect_b32 s24, s21, s44
	s_add_i32 s68, 0, 0x14000
	v_add_u32_e32 v112, s64, v159
	v_add_u32_e32 v165, s68, v159
	ds_read_b128 v[96:99], v112
	ds_read_b128 v[100:103], v112 offset:1024
	ds_read_b128 v[108:111], v112 offset:2048
	ds_read_b128 v[112:115], v112 offset:3072
	ds_read_b128 v[154:157], v165
	ds_read_b128 v[166:169], v165 offset:1024
	ds_read_b128 v[170:173], v165 offset:2048
	ds_read_b128 v[182:185], v165 offset:3072
	s_add_i32 m0, s50, 0xc000
	ds_read_b128 v[186:189], v164
	ds_read_b128 v[190:193], v164 offset:1024
	ds_read_b128 v[194:197], v164 offset:2048
	ds_read_b128 v[198:201], v164 offset:3072
	ds_read_b128 v[202:205], v164 offset:4096
	ds_read_b128 v[206:209], v164 offset:5120
	ds_read_b128 v[210:213], v164 offset:6144
	ds_read_b128 v[228:231], v164 offset:7168
	global_load_lds_dwordx4 v152, s[22:23]
	s_add_i32 m0, s50, 0xe000
	s_nop 0
	global_load_lds_dwordx4 v150, s[22:23]
	s_waitcnt vmcnt(8) lgkmcnt(0)
	s_barrier
	s_setprio 1
	v_mfma_f32_16x16x32_bf16 v[140:143], v[96:99], v[186:189], v[140:143]
	v_mfma_f32_16x16x32_bf16 v[136:139], v[108:111], v[186:189], v[136:139]
	v_mfma_f32_16x16x32_bf16 v[124:127], v[96:99], v[194:197], v[124:127]
	v_mfma_f32_16x16x32_bf16 v[120:123], v[108:111], v[194:197], v[120:123]
	v_mfma_f32_16x16x32_bf16 v[92:95], v[96:99], v[202:205], v[92:95]
	v_mfma_f32_16x16x32_bf16 v[88:91], v[108:111], v[202:205], v[88:91]
	v_mfma_f32_16x16x32_bf16 v[76:79], v[96:99], v[210:213], v[76:79]
	v_mfma_f32_16x16x32_bf16 v[72:75], v[108:111], v[210:213], v[72:75]
	v_mfma_f32_16x16x32_bf16 v[140:143], v[100:103], v[190:193], v[140:143]
	v_mfma_f32_16x16x32_bf16 v[136:139], v[112:115], v[190:193], v[136:139]
	v_mfma_f32_16x16x32_bf16 v[124:127], v[100:103], v[198:201], v[124:127]
	v_mfma_f32_16x16x32_bf16 v[120:123], v[112:115], v[198:201], v[120:123]
	v_mfma_f32_16x16x32_bf16 v[92:95], v[100:103], v[206:209], v[92:95]
	v_mfma_f32_16x16x32_bf16 v[88:91], v[112:115], v[206:209], v[88:91]
	v_mfma_f32_16x16x32_bf16 v[76:79], v[100:103], v[228:231], v[76:79]
	v_mfma_f32_16x16x32_bf16 v[72:75], v[112:115], v[228:231], v[72:75]
	v_mfma_f32_16x16x32_bf16 v[132:135], v[154:157], v[186:189], v[132:135]
	v_mfma_f32_16x16x32_bf16 v[128:131], v[170:173], v[186:189], v[128:131]
	v_mfma_f32_16x16x32_bf16 v[116:119], v[154:157], v[194:197], v[116:119]
	v_mfma_f32_16x16x32_bf16 v[104:107], v[170:173], v[194:197], v[104:107]
	v_mfma_f32_16x16x32_bf16 v[84:87], v[154:157], v[202:205], v[84:87]
	v_mfma_f32_16x16x32_bf16 v[80:83], v[170:173], v[202:205], v[80:83]
	v_mfma_f32_16x16x32_bf16 v[68:71], v[154:157], v[210:213], v[68:71]
	v_mfma_f32_16x16x32_bf16 v[64:67], v[170:173], v[210:213], v[64:67]
	v_mfma_f32_16x16x32_bf16 v[132:135], v[166:169], v[190:193], v[132:135]
	v_mfma_f32_16x16x32_bf16 v[128:131], v[182:185], v[190:193], v[128:131]
	v_mfma_f32_16x16x32_bf16 v[116:119], v[166:169], v[198:201], v[116:119]
	v_mfma_f32_16x16x32_bf16 v[104:107], v[182:185], v[198:201], v[104:107]
	s_setprio 2
	s_barrier
	v_mfma_f32_16x16x32_bf16 v[84:87], v[166:169], v[206:209], v[84:87]
	v_mfma_f32_16x16x32_bf16 v[80:83], v[182:185], v[206:209], v[80:83]
	v_mfma_f32_16x16x32_bf16 v[68:71], v[166:169], v[228:231], v[68:71]
	v_mfma_f32_16x16x32_bf16 v[64:67], v[182:185], v[228:231], v[64:67]
	s_setprio 0
	s_add_i32 s64, s64, s43
	s_add_u32 s94, s24, s34
	s_addc_u32 s95, s25, s35
	s_mov_b32 m0, s64
	ds_read_b128 v[186:189], v164 offset:16384
	ds_read_b128 v[190:193], v164 offset:17408
	ds_read_b128 v[194:197], v164 offset:18432
	ds_read_b128 v[198:201], v164 offset:19456
	ds_read_b128 v[202:205], v164 offset:20480
	ds_read_b128 v[206:209], v164 offset:21504
	ds_read_b128 v[210:213], v164 offset:22528
	ds_read_b128 v[228:231], v164 offset:23552
	global_load_lds_dwordx4 v176, s[24:25]
	s_add_i32 m0, s64, 0x2000
	s_add_u32 s64, s24, 0x40000
	s_addc_u32 s65, s25, 0
	s_add_i32 s68, s68, s43
	global_load_lds_dwordx4 v148, s[24:25]
	s_mov_b32 m0, s68
	s_nop 0
	global_load_lds_dwordx4 v176, s[64:65]
	s_add_i32 m0, s68, 0x2000
	s_nop 0
	global_load_lds_dwordx4 v148, s[64:65]
	s_add_u32 s98, s26, s34
	s_addc_u32 s99, s27, s35
	s_mov_b32 m0, s50
	s_nop 0
	global_load_lds_dwordx4 v144, s[26:27]
	s_waitcnt vmcnt(7) lgkmcnt(0)
	s_barrier
	s_setprio 1
	v_mfma_f32_16x16x32_bf16 v[60:63], v[96:99], v[186:189], v[60:63]
	v_mfma_f32_16x16x32_bf16 v[56:59], v[108:111], v[186:189], v[56:59]
	v_mfma_f32_16x16x32_bf16 v[44:47], v[96:99], v[194:197], v[44:47]
	v_mfma_f32_16x16x32_bf16 v[40:43], v[108:111], v[194:197], v[40:43]
	v_mfma_f32_16x16x32_bf16 v[28:31], v[96:99], v[202:205], v[28:31]
	v_mfma_f32_16x16x32_bf16 v[24:27], v[108:111], v[202:205], v[24:27]
	v_mfma_f32_16x16x32_bf16 v[12:15], v[96:99], v[210:213], v[12:15]
	v_mfma_f32_16x16x32_bf16 v[8:11], v[108:111], v[210:213], v[8:11]
	v_mfma_f32_16x16x32_bf16 v[60:63], v[100:103], v[190:193], v[60:63]
	v_mfma_f32_16x16x32_bf16 v[56:59], v[112:115], v[190:193], v[56:59]
	v_mfma_f32_16x16x32_bf16 v[44:47], v[100:103], v[198:201], v[44:47]
	v_mfma_f32_16x16x32_bf16 v[40:43], v[112:115], v[198:201], v[40:43]
	v_mfma_f32_16x16x32_bf16 v[28:31], v[100:103], v[206:209], v[28:31]
	v_mfma_f32_16x16x32_bf16 v[24:27], v[112:115], v[206:209], v[24:27]
	v_mfma_f32_16x16x32_bf16 v[12:15], v[100:103], v[228:231], v[12:15]
	v_mfma_f32_16x16x32_bf16 v[8:11], v[112:115], v[228:231], v[8:11]
	v_mfma_f32_16x16x32_bf16 v[52:55], v[154:157], v[186:189], v[52:55]
	v_mfma_f32_16x16x32_bf16 v[48:51], v[170:173], v[186:189], v[48:51]
	v_mfma_f32_16x16x32_bf16 v[36:39], v[154:157], v[194:197], v[36:39]
	v_mfma_f32_16x16x32_bf16 v[32:35], v[170:173], v[194:197], v[32:35]
	v_mfma_f32_16x16x32_bf16 v[20:23], v[154:157], v[202:205], v[20:23]
	v_mfma_f32_16x16x32_bf16 v[16:19], v[170:173], v[202:205], v[16:19]
	v_mfma_f32_16x16x32_bf16 v[4:7], v[154:157], v[210:213], v[4:7]
	v_mfma_f32_16x16x32_bf16 v[0:3], v[170:173], v[210:213], v[0:3]
	v_mfma_f32_16x16x32_bf16 v[52:55], v[166:169], v[190:193], v[52:55]
	v_mfma_f32_16x16x32_bf16 v[48:51], v[182:185], v[190:193], v[48:51]
	v_mfma_f32_16x16x32_bf16 v[36:39], v[166:169], v[198:201], v[36:39]
	v_mfma_f32_16x16x32_bf16 v[32:35], v[182:185], v[198:201], v[32:35]
	s_setprio 2
	s_barrier
	v_mfma_f32_16x16x32_bf16 v[20:23], v[166:169], v[206:209], v[20:23]
	v_mfma_f32_16x16x32_bf16 v[16:19], v[182:185], v[206:209], v[16:19]
	v_mfma_f32_16x16x32_bf16 v[4:7], v[166:169], v[228:231], v[4:7]
	v_mfma_f32_16x16x32_bf16 v[0:3], v[182:185], v[228:231], v[0:3]
	s_setprio 0
	s_mov_b32 m0, s51
	s_nop 0
	global_load_lds_dwordx4 v146, s[26:27]
	s_add_i32 s64, 0, 0x18000
	s_add_i32 s65, 0, 0x1c000
	v_add_u32_e32 v112, s64, v159
	v_add_u32_e32 v165, s65, v159
	ds_read_b128 v[96:99], v112
	ds_read_b128 v[100:103], v112 offset:1024
	ds_read_b128 v[108:111], v112 offset:2048
	ds_read_b128 v[112:115], v112 offset:3072
	ds_read_b128 v[154:157], v165
	ds_read_b128 v[166:169], v165 offset:1024
	ds_read_b128 v[170:173], v165 offset:2048
	ds_read_b128 v[182:185], v165 offset:3072
	s_add_u32 s26, s26, 0x40000
	s_addc_u32 s27, s27, 0
	s_mov_b32 m0, s52
	ds_read_b128 v[186:189], v164 offset:32768
	ds_read_b128 v[190:193], v164 offset:33792
	ds_read_b128 v[194:197], v164 offset:34816
	ds_read_b128 v[198:201], v164 offset:35840
	ds_read_b128 v[202:205], v164 offset:36864
	ds_read_b128 v[206:209], v164 offset:37888
	ds_read_b128 v[210:213], v164 offset:38912
	ds_read_b128 v[228:231], v164 offset:39936
	global_load_lds_dwordx4 v144, s[26:27]
	s_mov_b32 m0, s53
	s_nop 0
	global_load_lds_dwordx4 v146, s[26:27]
	s_waitcnt vmcnt(8) lgkmcnt(0)
	s_barrier
	s_setprio 1
	v_mfma_f32_16x16x32_bf16 v[140:143], v[96:99], v[186:189], v[140:143]
	v_mfma_f32_16x16x32_bf16 v[136:139], v[108:111], v[186:189], v[136:139]
	v_mfma_f32_16x16x32_bf16 v[124:127], v[96:99], v[194:197], v[124:127]
	v_mfma_f32_16x16x32_bf16 v[120:123], v[108:111], v[194:197], v[120:123]
	v_mfma_f32_16x16x32_bf16 v[92:95], v[96:99], v[202:205], v[92:95]
	v_mfma_f32_16x16x32_bf16 v[88:91], v[108:111], v[202:205], v[88:91]
	v_mfma_f32_16x16x32_bf16 v[76:79], v[96:99], v[210:213], v[76:79]
	v_mfma_f32_16x16x32_bf16 v[72:75], v[108:111], v[210:213], v[72:75]
	v_mfma_f32_16x16x32_bf16 v[140:143], v[100:103], v[190:193], v[140:143]
	v_mfma_f32_16x16x32_bf16 v[136:139], v[112:115], v[190:193], v[136:139]
	v_mfma_f32_16x16x32_bf16 v[124:127], v[100:103], v[198:201], v[124:127]
	v_mfma_f32_16x16x32_bf16 v[120:123], v[112:115], v[198:201], v[120:123]
	v_mfma_f32_16x16x32_bf16 v[92:95], v[100:103], v[206:209], v[92:95]
	v_mfma_f32_16x16x32_bf16 v[88:91], v[112:115], v[206:209], v[88:91]
	v_mfma_f32_16x16x32_bf16 v[76:79], v[100:103], v[228:231], v[76:79]
	v_mfma_f32_16x16x32_bf16 v[72:75], v[112:115], v[228:231], v[72:75]
	v_mfma_f32_16x16x32_bf16 v[132:135], v[154:157], v[186:189], v[132:135]
	v_mfma_f32_16x16x32_bf16 v[128:131], v[170:173], v[186:189], v[128:131]
	v_mfma_f32_16x16x32_bf16 v[116:119], v[154:157], v[194:197], v[116:119]
	v_mfma_f32_16x16x32_bf16 v[104:107], v[170:173], v[194:197], v[104:107]
	v_mfma_f32_16x16x32_bf16 v[84:87], v[154:157], v[202:205], v[84:87]
	v_mfma_f32_16x16x32_bf16 v[80:83], v[170:173], v[202:205], v[80:83]
	v_mfma_f32_16x16x32_bf16 v[68:71], v[154:157], v[210:213], v[68:71]
	v_mfma_f32_16x16x32_bf16 v[64:67], v[170:173], v[210:213], v[64:67]
	v_mfma_f32_16x16x32_bf16 v[132:135], v[166:169], v[190:193], v[132:135]
	v_mfma_f32_16x16x32_bf16 v[128:131], v[182:185], v[190:193], v[128:131]
	v_mfma_f32_16x16x32_bf16 v[116:119], v[166:169], v[198:201], v[116:119]
	v_mfma_f32_16x16x32_bf16 v[104:107], v[182:185], v[198:201], v[104:107]
	s_setprio 2
	s_barrier
	v_mfma_f32_16x16x32_bf16 v[84:87], v[166:169], v[206:209], v[84:87]
	v_mfma_f32_16x16x32_bf16 v[80:83], v[182:185], v[206:209], v[80:83]
	v_mfma_f32_16x16x32_bf16 v[68:71], v[166:169], v[228:231], v[68:71]
	v_mfma_f32_16x16x32_bf16 v[64:67], v[182:185], v[228:231], v[64:67]
	s_setprio 0
	s_add_i32 s26, s64, s43
	s_mov_b32 m0, s26
	ds_read_b128 v[186:189], v164 offset:49152
	ds_read_b128 v[190:193], v164 offset:50176
	ds_read_b128 v[194:197], v164 offset:51200
	ds_read_b128 v[198:201], v164 offset:52224
	ds_read_b128 v[202:205], v164 offset:53248
	ds_read_b128 v[206:209], v164 offset:54272
	ds_read_b128 v[210:213], v164 offset:55296
	ds_read_b128 v[228:231], v164 offset:56320
	global_load_lds_dwordx4 v176, s[94:95]
	s_add_i32 m0, s26, 0x2000
	s_add_u32 s24, s24, 0x40080
	s_addc_u32 s25, s25, 0
	s_add_i32 s26, s65, s43
	global_load_lds_dwordx4 v148, s[94:95]
	s_mov_b32 m0, s26
	s_nop 0
	global_load_lds_dwordx4 v176, s[24:25]
	s_add_i32 m0, s26, 0x2000
	s_nop 0
	global_load_lds_dwordx4 v148, s[24:25]
	s_mov_b32 m0, s57
	s_nop 0
	global_load_lds_dwordx4 v144, s[98:99]
	s_mov_b32 m0, s58
	s_nop 0
	global_load_lds_dwordx4 v146, s[98:99]
	s_waitcnt vmcnt(8) lgkmcnt(0)
	s_barrier
	s_setprio 1
	v_mfma_f32_16x16x32_bf16 v[60:63], v[96:99], v[186:189], v[60:63]
	v_mfma_f32_16x16x32_bf16 v[56:59], v[108:111], v[186:189], v[56:59]
	v_mfma_f32_16x16x32_bf16 v[44:47], v[96:99], v[194:197], v[44:47]
	v_mfma_f32_16x16x32_bf16 v[40:43], v[108:111], v[194:197], v[40:43]
	v_mfma_f32_16x16x32_bf16 v[28:31], v[96:99], v[202:205], v[28:31]
	v_mfma_f32_16x16x32_bf16 v[24:27], v[108:111], v[202:205], v[24:27]
	v_mfma_f32_16x16x32_bf16 v[12:15], v[96:99], v[210:213], v[12:15]
	v_mfma_f32_16x16x32_bf16 v[8:11], v[108:111], v[210:213], v[8:11]
	v_mfma_f32_16x16x32_bf16 v[60:63], v[100:103], v[190:193], v[60:63]
	v_mfma_f32_16x16x32_bf16 v[56:59], v[112:115], v[190:193], v[56:59]
	v_mfma_f32_16x16x32_bf16 v[44:47], v[100:103], v[198:201], v[44:47]
	v_mfma_f32_16x16x32_bf16 v[40:43], v[112:115], v[198:201], v[40:43]
	v_mfma_f32_16x16x32_bf16 v[28:31], v[100:103], v[206:209], v[28:31]
	v_mfma_f32_16x16x32_bf16 v[24:27], v[112:115], v[206:209], v[24:27]
	v_mfma_f32_16x16x32_bf16 v[12:15], v[100:103], v[228:231], v[12:15]
	v_mfma_f32_16x16x32_bf16 v[8:11], v[112:115], v[228:231], v[8:11]
	v_mfma_f32_16x16x32_bf16 v[52:55], v[154:157], v[186:189], v[52:55]
	v_mfma_f32_16x16x32_bf16 v[48:51], v[170:173], v[186:189], v[48:51]
	v_mfma_f32_16x16x32_bf16 v[36:39], v[154:157], v[194:197], v[36:39]
	v_mfma_f32_16x16x32_bf16 v[32:35], v[170:173], v[194:197], v[32:35]
	v_mfma_f32_16x16x32_bf16 v[20:23], v[154:157], v[202:205], v[20:23]
	v_mfma_f32_16x16x32_bf16 v[16:19], v[170:173], v[202:205], v[16:19]
	v_mfma_f32_16x16x32_bf16 v[4:7], v[154:157], v[210:213], v[4:7]
	v_mfma_f32_16x16x32_bf16 v[0:3], v[170:173], v[210:213], v[0:3]
	v_mfma_f32_16x16x32_bf16 v[52:55], v[166:169], v[190:193], v[52:55]
	v_mfma_f32_16x16x32_bf16 v[48:51], v[182:185], v[190:193], v[48:51]
	v_mfma_f32_16x16x32_bf16 v[36:39], v[166:169], v[198:201], v[36:39]
	v_mfma_f32_16x16x32_bf16 v[32:35], v[182:185], v[198:201], v[32:35]
	s_setprio 2
	s_barrier
	v_mfma_f32_16x16x32_bf16 v[20:23], v[166:169], v[206:209], v[20:23]
	v_mfma_f32_16x16x32_bf16 v[16:19], v[182:185], v[206:209], v[16:19]
	v_mfma_f32_16x16x32_bf16 v[4:7], v[166:169], v[228:231], v[4:7]
	v_mfma_f32_16x16x32_bf16 v[0:3], v[182:185], v[228:231], v[0:3]
	s_setprio 0
	s_add_i32 s63, s63, 2
	s_add_u32 s44, s44, 0x100
	s_addc_u32 s62, s62, 0
	s_add_u32 s22, s22, 0x100
	s_addc_u32 s23, s23, 0
	s_cmp_gt_u32 s63, 13
	s_cbranch_scc0 .LBB0_319

.LBB0_633:
	s_ashr_i32 s13, s12, 31
	s_lshl_b64 s[14:15], s[12:13], 19
	s_add_u32 s14, s37, s14
	s_addc_u32 s15, s42, s15
	s_and_b64 s[16:17], s[4:5], exec
	s_cselect_b32 s13, s15, s23
	s_cselect_b32 s19, s14, s22
	s_ashr_i32 s11, s10, 31
	s_lshl_b64 s[16:17], s[10:11], 19
	s_add_u32 s16, s29, s16
	s_addc_u32 s17, s43, s17
	s_and_b64 s[24:25], s[4:5], exec
	s_cselect_b32 s11, s17, s21
	s_cselect_b32 s60, s16, s20
	s_add_u32 s61, s20, 0x100
	s_addc_u32 s62, s21, 0
	s_add_u32 s20, s22, 0x40080
	s_addc_u32 s21, s23, 0
	s_mov_b32 s63, -2
	s_add_u32 s22, s20, 0xfffc0080
	s_addc_u32 s23, s21, -1
	s_add_i32 s64, 0, 0x10000
	s_cmp_eq_u32 s63, 12
	s_cselect_b32 s25, s13, s23
	s_cselect_b32 s24, s19, s22
	s_cselect_b32 s23, s11, s62
	s_cselect_b32 s22, s60, s61
	s_add_i32 s68, 0, 0x14000
	s_waitcnt lgkmcnt(0)
	s_lshl_b32 s74, s18, 8
	v_add_u32_e32 v178, s74, v182
	v_ashrrev_i32_e32 v179, 31, v178
	v_lshlrev_b64 v[178:179], 6, v[178:179]
	v_lshl_add_u64 v[178:179], s[70:71], 0, v[178:179]
	s_and_saveexec_b64 s[78:79], s[2:3]
	global_load_dwordx4 v[238:241], v[178:179], off
	global_load_dwordx4 v[242:245], v[178:179], off offset:16
	global_load_dwordx4 v[246:249], v[178:179], off offset:32
	global_load_dwordx4 v[250:253], v[178:179], off offset:48
	s_mov_b64 exec, s[78:79]
	v_add_u32_e32 v140, s64, v175
	v_add_u32_e32 v170, s68, v175
	ds_read_b128 v[128:131], v140
	ds_read_b128 v[132:135], v140 offset:1024
	ds_read_b128 v[136:139], v140 offset:2048
	ds_read_b128 v[140:143], v140 offset:3072
	ds_read_b128 v[144:147], v170
	ds_read_b128 v[162:165], v170 offset:1024
	ds_read_b128 v[166:169], v170 offset:2048
	ds_read_b128 v[170:173], v170 offset:3072
	s_add_i32 m0, s50, 0xc000
	ds_read_b128 v[186:189], v185
	ds_read_b128 v[190:193], v185 offset:1024
	ds_read_b128 v[194:197], v185 offset:2048
	ds_read_b128 v[198:201], v185 offset:3072
	ds_read_b128 v[202:205], v185 offset:4096
	ds_read_b128 v[206:209], v185 offset:5120
	ds_read_b128 v[210:213], v185 offset:6144
	ds_read_b128 v[228:231], v185 offset:7168
	global_load_lds_dwordx4 v160, s[20:21]
	s_add_i32 m0, s50, 0xe000
	s_nop 0
	global_load_lds_dwordx4 v158, s[20:21]
	s_waitcnt vmcnt(16) lgkmcnt(0)
	s_barrier
	s_setprio 1
	v_mfma_f32_16x16x32_bf16 v[124:127], v[128:131], v[186:189], 0
	v_mfma_f32_16x16x32_bf16 v[120:123], v[136:139], v[186:189], 0
	v_mfma_f32_16x16x32_bf16 v[108:111], v[128:131], v[194:197], 0
	v_mfma_f32_16x16x32_bf16 v[104:107], v[136:139], v[194:197], 0
	v_mfma_f32_16x16x32_bf16 v[92:95], v[128:131], v[202:205], 0
	v_mfma_f32_16x16x32_bf16 v[88:91], v[136:139], v[202:205], 0
	v_mfma_f32_16x16x32_bf16 v[76:79], v[128:131], v[210:213], 0
	v_mfma_f32_16x16x32_bf16 v[72:75], v[136:139], v[210:213], 0
	v_mfma_f32_16x16x32_bf16 v[124:127], v[132:135], v[190:193], v[124:127]
	v_mfma_f32_16x16x32_bf16 v[120:123], v[140:143], v[190:193], v[120:123]
	v_mfma_f32_16x16x32_bf16 v[108:111], v[132:135], v[198:201], v[108:111]
	v_mfma_f32_16x16x32_bf16 v[104:107], v[140:143], v[198:201], v[104:107]
	v_mfma_f32_16x16x32_bf16 v[92:95], v[132:135], v[206:209], v[92:95]
	v_mfma_f32_16x16x32_bf16 v[88:91], v[140:143], v[206:209], v[88:91]
	v_mfma_f32_16x16x32_bf16 v[76:79], v[132:135], v[228:231], v[76:79]
	v_mfma_f32_16x16x32_bf16 v[72:75], v[140:143], v[228:231], v[72:75]
	v_mfma_f32_16x16x32_bf16 v[116:119], v[144:147], v[186:189], 0
	v_mfma_f32_16x16x32_bf16 v[112:115], v[166:169], v[186:189], 0
	v_mfma_f32_16x16x32_bf16 v[100:103], v[144:147], v[194:197], 0
	v_mfma_f32_16x16x32_bf16 v[96:99], v[166:169], v[194:197], 0
	v_mfma_f32_16x16x32_bf16 v[84:87], v[144:147], v[202:205], 0
	v_mfma_f32_16x16x32_bf16 v[80:83], v[166:169], v[202:205], 0
	v_mfma_f32_16x16x32_bf16 v[68:71], v[144:147], v[210:213], 0
	v_mfma_f32_16x16x32_bf16 v[64:67], v[166:169], v[210:213], 0
	v_mfma_f32_16x16x32_bf16 v[116:119], v[162:165], v[190:193], v[116:119]
	v_mfma_f32_16x16x32_bf16 v[112:115], v[170:173], v[190:193], v[112:115]
	v_mfma_f32_16x16x32_bf16 v[100:103], v[162:165], v[198:201], v[100:103]
	v_mfma_f32_16x16x32_bf16 v[96:99], v[170:173], v[198:201], v[96:99]
	s_setprio 2
	s_barrier
	v_mfma_f32_16x16x32_bf16 v[84:87], v[162:165], v[206:209], v[84:87]
	v_mfma_f32_16x16x32_bf16 v[80:83], v[170:173], v[206:209], v[80:83]
	v_mfma_f32_16x16x32_bf16 v[68:71], v[162:165], v[228:231], v[68:71]
	v_mfma_f32_16x16x32_bf16 v[64:67], v[170:173], v[228:231], v[64:67]
	s_setprio 0
	s_add_i32 s64, s64, s46
	s_add_u32 s94, s22, s34
	s_addc_u32 s95, s23, s35
	s_mov_b32 m0, s64
	ds_read_b128 v[186:189], v185 offset:16384
	ds_read_b128 v[190:193], v185 offset:17408
	ds_read_b128 v[194:197], v185 offset:18432
	ds_read_b128 v[198:201], v185 offset:19456
	ds_read_b128 v[202:205], v185 offset:20480
	ds_read_b128 v[206:209], v185 offset:21504
	ds_read_b128 v[210:213], v185 offset:22528
	ds_read_b128 v[228:231], v185 offset:23552
	global_load_lds_dwordx4 v152, s[22:23]
	s_add_i32 m0, s64, 0x2000
	s_add_u32 s64, s22, 0x40000
	s_addc_u32 s65, s23, 0
	s_add_i32 s68, s68, s46
	global_load_lds_dwordx4 v148, s[22:23]
	s_mov_b32 m0, s68
	s_nop 0
	global_load_lds_dwordx4 v152, s[64:65]
	s_add_i32 m0, s68, 0x2000
	s_nop 0
	global_load_lds_dwordx4 v148, s[64:65]
	s_add_u32 s98, s24, s34
	s_addc_u32 s99, s25, s35
	s_mov_b32 m0, s50
	s_nop 0
	global_load_lds_dwordx4 v154, s[24:25]
	s_waitcnt vmcnt(7) lgkmcnt(0)
	s_barrier
	s_setprio 1
	v_mfma_f32_16x16x32_bf16 v[60:63], v[128:131], v[186:189], 0
	v_mfma_f32_16x16x32_bf16 v[56:59], v[136:139], v[186:189], 0
	v_mfma_f32_16x16x32_bf16 v[48:51], v[128:131], v[194:197], 0
	v_mfma_f32_16x16x32_bf16 v[40:43], v[136:139], v[194:197], 0
	v_mfma_f32_16x16x32_bf16 v[32:35], v[128:131], v[202:205], 0
	v_mfma_f32_16x16x32_bf16 v[24:27], v[136:139], v[202:205], 0
	v_mfma_f32_16x16x32_bf16 v[16:19], v[128:131], v[210:213], 0
	v_mfma_f32_16x16x32_bf16 v[8:11], v[136:139], v[210:213], 0
	v_mfma_f32_16x16x32_bf16 v[60:63], v[132:135], v[190:193], v[60:63]
	v_mfma_f32_16x16x32_bf16 v[56:59], v[140:143], v[190:193], v[56:59]
	v_mfma_f32_16x16x32_bf16 v[48:51], v[132:135], v[198:201], v[48:51]
	v_mfma_f32_16x16x32_bf16 v[40:43], v[140:143], v[198:201], v[40:43]
	v_mfma_f32_16x16x32_bf16 v[32:35], v[132:135], v[206:209], v[32:35]
	v_mfma_f32_16x16x32_bf16 v[24:27], v[140:143], v[206:209], v[24:27]
	v_mfma_f32_16x16x32_bf16 v[16:19], v[132:135], v[228:231], v[16:19]
	v_mfma_f32_16x16x32_bf16 v[8:11], v[140:143], v[228:231], v[8:11]
	v_mfma_f32_16x16x32_bf16 v[52:55], v[144:147], v[186:189], 0
	v_mfma_f32_16x16x32_bf16 v[44:47], v[166:169], v[186:189], 0
	v_mfma_f32_16x16x32_bf16 v[36:39], v[144:147], v[194:197], 0
	v_mfma_f32_16x16x32_bf16 v[28:31], v[166:169], v[194:197], 0
	v_mfma_f32_16x16x32_bf16 v[20:23], v[144:147], v[202:205], 0
	v_mfma_f32_16x16x32_bf16 v[12:15], v[166:169], v[202:205], 0
	v_mfma_f32_16x16x32_bf16 v[4:7], v[144:147], v[210:213], 0
	v_mfma_f32_16x16x32_bf16 v[0:3], v[166:169], v[210:213], 0
	v_mfma_f32_16x16x32_bf16 v[52:55], v[162:165], v[190:193], v[52:55]
	v_mfma_f32_16x16x32_bf16 v[44:47], v[170:173], v[190:193], v[44:47]
	v_mfma_f32_16x16x32_bf16 v[36:39], v[162:165], v[198:201], v[36:39]
	v_mfma_f32_16x16x32_bf16 v[28:31], v[170:173], v[198:201], v[28:31]
	s_setprio 2
	s_barrier
	v_mfma_f32_16x16x32_bf16 v[20:23], v[162:165], v[206:209], v[20:23]
	v_mfma_f32_16x16x32_bf16 v[12:15], v[170:173], v[206:209], v[12:15]
	v_mfma_f32_16x16x32_bf16 v[4:7], v[162:165], v[228:231], v[4:7]
	v_mfma_f32_16x16x32_bf16 v[0:3], v[170:173], v[228:231], v[0:3]
	s_setprio 0
	s_mov_b32 m0, s51
	s_nop 0
	global_load_lds_dwordx4 v150, s[24:25]
	s_and_saveexec_b64 s[78:79], s[2:3]
	v_add_f32_e32 v238, v238, v239
	v_add_f32_e32 v240, v240, v241
	v_add_f32_e32 v242, v242, v243
	v_add_f32_e32 v244, v244, v245
	v_add_f32_e32 v246, v246, v247
	v_add_f32_e32 v248, v248, v249
	v_add_f32_e32 v250, v250, v251
	v_add_f32_e32 v252, v252, v253
	v_add_f32_e32 v238, v238, v240
	v_add_f32_e32 v242, v242, v244
	v_add_f32_e32 v246, v246, v248
	v_add_f32_e32 v250, v250, v252
	v_add_f32_e32 v238, v238, v242
	v_add_f32_e32 v246, v246, v250
	v_add_f32_e32 v238, v238, v246
	v_fmamk_f32 v238, v238, 0x3a800000, v216
	v_rsq_f32_e32 v238, v238
	s_nop 0
	ds_write_b32 v183, v238
	s_mov_b64 exec, s[78:79]
	s_add_i32 s64, 0, 0x18000
	s_add_i32 s65, 0, 0x1c000
	v_add_u32_e32 v140, s64, v175
	v_add_u32_e32 v170, s65, v175
	ds_read_b128 v[128:131], v140
	ds_read_b128 v[132:135], v140 offset:1024
	ds_read_b128 v[136:139], v140 offset:2048
	ds_read_b128 v[140:143], v140 offset:3072
	ds_read_b128 v[144:147], v170
	ds_read_b128 v[162:165], v170 offset:1024
	ds_read_b128 v[166:169], v170 offset:2048
	ds_read_b128 v[170:173], v170 offset:3072
	s_add_u32 s24, s24, 0x40000
	s_addc_u32 s25, s25, 0
	s_mov_b32 m0, s52
	ds_read_b128 v[186:189], v185 offset:32768
	ds_read_b128 v[190:193], v185 offset:33792
	ds_read_b128 v[194:197], v185 offset:34816
	ds_read_b128 v[198:201], v185 offset:35840
	ds_read_b128 v[202:205], v185 offset:36864
	ds_read_b128 v[206:209], v185 offset:37888
	ds_read_b128 v[210:213], v185 offset:38912
	ds_read_b128 v[228:231], v185 offset:39936
	global_load_lds_dwordx4 v154, s[24:25]
	s_mov_b32 m0, s53
	s_nop 0
	global_load_lds_dwordx4 v150, s[24:25]
	s_waitcnt vmcnt(8) lgkmcnt(0)
	s_barrier
	s_setprio 1
	v_mfma_f32_16x16x32_bf16 v[124:127], v[128:131], v[186:189], v[124:127]
	v_mfma_f32_16x16x32_bf16 v[120:123], v[136:139], v[186:189], v[120:123]
	v_mfma_f32_16x16x32_bf16 v[108:111], v[128:131], v[194:197], v[108:111]
	v_mfma_f32_16x16x32_bf16 v[104:107], v[136:139], v[194:197], v[104:107]
	v_mfma_f32_16x16x32_bf16 v[92:95], v[128:131], v[202:205], v[92:95]
	v_mfma_f32_16x16x32_bf16 v[88:91], v[136:139], v[202:205], v[88:91]
	v_mfma_f32_16x16x32_bf16 v[76:79], v[128:131], v[210:213], v[76:79]
	v_mfma_f32_16x16x32_bf16 v[72:75], v[136:139], v[210:213], v[72:75]
	v_mfma_f32_16x16x32_bf16 v[124:127], v[132:135], v[190:193], v[124:127]
	v_mfma_f32_16x16x32_bf16 v[120:123], v[140:143], v[190:193], v[120:123]
	v_mfma_f32_16x16x32_bf16 v[108:111], v[132:135], v[198:201], v[108:111]
	v_mfma_f32_16x16x32_bf16 v[104:107], v[140:143], v[198:201], v[104:107]
	v_mfma_f32_16x16x32_bf16 v[92:95], v[132:135], v[206:209], v[92:95]
	v_mfma_f32_16x16x32_bf16 v[88:91], v[140:143], v[206:209], v[88:91]
	v_mfma_f32_16x16x32_bf16 v[76:79], v[132:135], v[228:231], v[76:79]
	v_mfma_f32_16x16x32_bf16 v[72:75], v[140:143], v[228:231], v[72:75]
	v_mfma_f32_16x16x32_bf16 v[116:119], v[144:147], v[186:189], v[116:119]
	v_mfma_f32_16x16x32_bf16 v[112:115], v[166:169], v[186:189], v[112:115]
	v_mfma_f32_16x16x32_bf16 v[100:103], v[144:147], v[194:197], v[100:103]
	v_mfma_f32_16x16x32_bf16 v[96:99], v[166:169], v[194:197], v[96:99]
	v_mfma_f32_16x16x32_bf16 v[84:87], v[144:147], v[202:205], v[84:87]
	v_mfma_f32_16x16x32_bf16 v[80:83], v[166:169], v[202:205], v[80:83]
	v_mfma_f32_16x16x32_bf16 v[68:71], v[144:147], v[210:213], v[68:71]
	v_mfma_f32_16x16x32_bf16 v[64:67], v[166:169], v[210:213], v[64:67]
	v_mfma_f32_16x16x32_bf16 v[116:119], v[162:165], v[190:193], v[116:119]
	v_mfma_f32_16x16x32_bf16 v[112:115], v[170:173], v[190:193], v[112:115]
	v_mfma_f32_16x16x32_bf16 v[100:103], v[162:165], v[198:201], v[100:103]
	v_mfma_f32_16x16x32_bf16 v[96:99], v[170:173], v[198:201], v[96:99]
	s_setprio 2
	s_barrier
	v_mfma_f32_16x16x32_bf16 v[84:87], v[162:165], v[206:209], v[84:87]
	v_mfma_f32_16x16x32_bf16 v[80:83], v[170:173], v[206:209], v[80:83]
	v_mfma_f32_16x16x32_bf16 v[68:71], v[162:165], v[228:231], v[68:71]
	v_mfma_f32_16x16x32_bf16 v[64:67], v[170:173], v[228:231], v[64:67]
	s_setprio 0
	s_min_i32 s74, s18, 0x80
	s_ashr_i32 s74, s74, 3
	s_mul_hi_i32 s75, s74, 0x3000
	s_mulk_i32 s74, 0x3000
	s_add_u32 s74, s54, s74
	s_addc_u32 s75, s55, s75
	s_lshl_b32 s76, s44, 8
	s_ashr_i32 s77, s76, 31
	s_lshl_b64 s[76:77], s[76:77], 2
	s_add_u32 s74, s74, s76
	s_addc_u32 s75, s75, s77
	v_lshl_add_u64 v[178:179], s[74:75], 0, v[176:177]
	global_load_dwordx4 v[238:241], v[178:179], off
	global_load_dwordx4 v[242:245], v[178:179], off offset:16
	global_load_dwordx4 v[246:249], v[178:179], off offset:512
	global_load_dwordx4 v[250:253], v[178:179], off offset:528
	s_add_i32 s24, s64, s46
	s_mov_b32 m0, s24
	ds_read_b128 v[186:189], v185 offset:49152
	ds_read_b128 v[190:193], v185 offset:50176
	ds_read_b128 v[194:197], v185 offset:51200
	ds_read_b128 v[198:201], v185 offset:52224
	ds_read_b128 v[202:205], v185 offset:53248
	ds_read_b128 v[206:209], v185 offset:54272
	ds_read_b128 v[210:213], v185 offset:55296
	ds_read_b128 v[228:231], v185 offset:56320
	global_load_lds_dwordx4 v152, s[94:95]
	s_add_i32 m0, s24, 0x2000
	s_add_u32 s22, s22, 0x40080
	s_addc_u32 s23, s23, 0
	s_add_i32 s24, s65, s46
	global_load_lds_dwordx4 v148, s[94:95]
	s_mov_b32 m0, s24
	s_nop 0
	global_load_lds_dwordx4 v152, s[22:23]
	s_add_i32 m0, s24, 0x2000
	s_nop 0
	global_load_lds_dwordx4 v148, s[22:23]
	s_mov_b32 m0, s56
	s_nop 0
	global_load_lds_dwordx4 v154, s[98:99]
	s_mov_b32 m0, s57
	s_nop 0
	global_load_lds_dwordx4 v150, s[98:99]
	s_waitcnt vmcnt(12) lgkmcnt(0)
	s_barrier
	s_setprio 1
	v_mfma_f32_16x16x32_bf16 v[60:63], v[128:131], v[186:189], v[60:63]
	v_mfma_f32_16x16x32_bf16 v[56:59], v[136:139], v[186:189], v[56:59]
	v_mfma_f32_16x16x32_bf16 v[48:51], v[128:131], v[194:197], v[48:51]
	v_mfma_f32_16x16x32_bf16 v[40:43], v[136:139], v[194:197], v[40:43]
	v_mfma_f32_16x16x32_bf16 v[32:35], v[128:131], v[202:205], v[32:35]
	v_mfma_f32_16x16x32_bf16 v[24:27], v[136:139], v[202:205], v[24:27]
	v_mfma_f32_16x16x32_bf16 v[16:19], v[128:131], v[210:213], v[16:19]
	v_mfma_f32_16x16x32_bf16 v[8:11], v[136:139], v[210:213], v[8:11]
	v_mfma_f32_16x16x32_bf16 v[60:63], v[132:135], v[190:193], v[60:63]
	v_mfma_f32_16x16x32_bf16 v[56:59], v[140:143], v[190:193], v[56:59]
	v_mfma_f32_16x16x32_bf16 v[48:51], v[132:135], v[198:201], v[48:51]
	v_mfma_f32_16x16x32_bf16 v[40:43], v[140:143], v[198:201], v[40:43]
	v_mfma_f32_16x16x32_bf16 v[32:35], v[132:135], v[206:209], v[32:35]
	v_mfma_f32_16x16x32_bf16 v[24:27], v[140:143], v[206:209], v[24:27]
	v_mfma_f32_16x16x32_bf16 v[16:19], v[132:135], v[228:231], v[16:19]
	v_mfma_f32_16x16x32_bf16 v[8:11], v[140:143], v[228:231], v[8:11]
	v_mfma_f32_16x16x32_bf16 v[52:55], v[144:147], v[186:189], v[52:55]
	v_mfma_f32_16x16x32_bf16 v[44:47], v[166:169], v[186:189], v[44:47]
	v_mfma_f32_16x16x32_bf16 v[36:39], v[144:147], v[194:197], v[36:39]
	v_mfma_f32_16x16x32_bf16 v[28:31], v[166:169], v[194:197], v[28:31]
	v_mfma_f32_16x16x32_bf16 v[20:23], v[144:147], v[202:205], v[20:23]
	v_mfma_f32_16x16x32_bf16 v[12:15], v[166:169], v[202:205], v[12:15]
	v_mfma_f32_16x16x32_bf16 v[4:7], v[144:147], v[210:213], v[4:7]
	v_mfma_f32_16x16x32_bf16 v[0:3], v[166:169], v[210:213], v[0:3]
	v_mfma_f32_16x16x32_bf16 v[52:55], v[162:165], v[190:193], v[52:55]
	v_mfma_f32_16x16x32_bf16 v[44:47], v[170:173], v[190:193], v[44:47]
	v_mfma_f32_16x16x32_bf16 v[36:39], v[162:165], v[198:201], v[36:39]
	v_mfma_f32_16x16x32_bf16 v[28:31], v[170:173], v[198:201], v[28:31]
	s_setprio 2
	s_barrier
	v_mfma_f32_16x16x32_bf16 v[20:23], v[162:165], v[206:209], v[20:23]
	v_mfma_f32_16x16x32_bf16 v[12:15], v[170:173], v[206:209], v[12:15]
	v_mfma_f32_16x16x32_bf16 v[4:7], v[162:165], v[228:231], v[4:7]
	v_mfma_f32_16x16x32_bf16 v[0:3], v[170:173], v[228:231], v[0:3]
	s_setprio 0
	s_add_i32 s63, s63, 2
	s_add_u32 s61, s61, 0x100
	s_addc_u32 s62, s62, 0
	s_add_u32 s20, s20, 0x100
	s_addc_u32 s21, s21, 0
	s_cmp_gt_u32 s63, 13
	s_cbranch_scc1 .Lpeel_exit_1
.LBB0_634:
	s_add_u32 s22, s20, 0xfffc0080
	s_addc_u32 s23, s21, -1
	s_add_i32 s64, 0, 0x10000
	s_cmp_eq_u32 s63, 12
	s_cselect_b32 s25, s13, s23
	s_cselect_b32 s24, s19, s22
	s_cselect_b32 s23, s11, s62
	s_cselect_b32 s22, s60, s61
	s_add_i32 s68, 0, 0x14000
	s_waitcnt lgkmcnt(0)
	v_add_u32_e32 v140, s64, v175
	v_add_u32_e32 v170, s68, v175
	ds_read_b128 v[128:131], v140
	ds_read_b128 v[132:135], v140 offset:1024
	ds_read_b128 v[136:139], v140 offset:2048
	ds_read_b128 v[140:143], v140 offset:3072
	ds_read_b128 v[144:147], v170
	ds_read_b128 v[162:165], v170 offset:1024
	ds_read_b128 v[166:169], v170 offset:2048
	ds_read_b128 v[170:173], v170 offset:3072
	s_add_i32 m0, s50, 0xc000
	ds_read_b128 v[186:189], v185
	ds_read_b128 v[190:193], v185 offset:1024
	ds_read_b128 v[194:197], v185 offset:2048
	ds_read_b128 v[198:201], v185 offset:3072
	ds_read_b128 v[202:205], v185 offset:4096
	ds_read_b128 v[206:209], v185 offset:5120
	ds_read_b128 v[210:213], v185 offset:6144
	ds_read_b128 v[228:231], v185 offset:7168
	global_load_lds_dwordx4 v160, s[20:21]
	s_add_i32 m0, s50, 0xe000
	s_nop 0
	global_load_lds_dwordx4 v158, s[20:21]
	s_waitcnt vmcnt(8) lgkmcnt(0)
	s_barrier
	s_setprio 1
	v_mfma_f32_16x16x32_bf16 v[124:127], v[128:131], v[186:189], v[124:127]
	v_mfma_f32_16x16x32_bf16 v[120:123], v[136:139], v[186:189], v[120:123]
	v_mfma_f32_16x16x32_bf16 v[108:111], v[128:131], v[194:197], v[108:111]
	v_mfma_f32_16x16x32_bf16 v[104:107], v[136:139], v[194:197], v[104:107]
	v_mfma_f32_16x16x32_bf16 v[92:95], v[128:131], v[202:205], v[92:95]
	v_mfma_f32_16x16x32_bf16 v[88:91], v[136:139], v[202:205], v[88:91]
	v_mfma_f32_16x16x32_bf16 v[76:79], v[128:131], v[210:213], v[76:79]
	v_mfma_f32_16x16x32_bf16 v[72:75], v[136:139], v[210:213], v[72:75]
	v_mfma_f32_16x16x32_bf16 v[124:127], v[132:135], v[190:193], v[124:127]
	v_mfma_f32_16x16x32_bf16 v[120:123], v[140:143], v[190:193], v[120:123]
	v_mfma_f32_16x16x32_bf16 v[108:111], v[132:135], v[198:201], v[108:111]
	v_mfma_f32_16x16x32_bf16 v[104:107], v[140:143], v[198:201], v[104:107]
	v_mfma_f32_16x16x32_bf16 v[92:95], v[132:135], v[206:209], v[92:95]
	v_mfma_f32_16x16x32_bf16 v[88:91], v[140:143], v[206:209], v[88:91]
	v_mfma_f32_16x16x32_bf16 v[76:79], v[132:135], v[228:231], v[76:79]
	v_mfma_f32_16x16x32_bf16 v[72:75], v[140:143], v[228:231], v[72:75]
	v_mfma_f32_16x16x32_bf16 v[116:119], v[144:147], v[186:189], v[116:119]
	v_mfma_f32_16x16x32_bf16 v[112:115], v[166:169], v[186:189], v[112:115]
	v_mfma_f32_16x16x32_bf16 v[100:103], v[144:147], v[194:197], v[100:103]
	v_mfma_f32_16x16x32_bf16 v[96:99], v[166:169], v[194:197], v[96:99]
	v_mfma_f32_16x16x32_bf16 v[84:87], v[144:147], v[202:205], v[84:87]
	v_mfma_f32_16x16x32_bf16 v[80:83], v[166:169], v[202:205], v[80:83]
	v_mfma_f32_16x16x32_bf16 v[68:71], v[144:147], v[210:213], v[68:71]
	v_mfma_f32_16x16x32_bf16 v[64:67], v[166:169], v[210:213], v[64:67]
	v_mfma_f32_16x16x32_bf16 v[116:119], v[162:165], v[190:193], v[116:119]
	v_mfma_f32_16x16x32_bf16 v[112:115], v[170:173], v[190:193], v[112:115]
	v_mfma_f32_16x16x32_bf16 v[100:103], v[162:165], v[198:201], v[100:103]
	v_mfma_f32_16x16x32_bf16 v[96:99], v[170:173], v[198:201], v[96:99]
	s_setprio 2
	s_barrier
	v_mfma_f32_16x16x32_bf16 v[84:87], v[162:165], v[206:209], v[84:87]
	v_mfma_f32_16x16x32_bf16 v[80:83], v[170:173], v[206:209], v[80:83]
	v_mfma_f32_16x16x32_bf16 v[68:71], v[162:165], v[228:231], v[68:71]
	v_mfma_f32_16x16x32_bf16 v[64:67], v[170:173], v[228:231], v[64:67]
	s_setprio 0
	s_add_i32 s64, s64, s46
	s_add_u32 s94, s22, s34
	s_addc_u32 s95, s23, s35
	s_mov_b32 m0, s64
	ds_read_b128 v[186:189], v185 offset:16384
	ds_read_b128 v[190:193], v185 offset:17408
	ds_read_b128 v[194:197], v185 offset:18432
	ds_read_b128 v[198:201], v185 offset:19456
	ds_read_b128 v[202:205], v185 offset:20480
	ds_read_b128 v[206:209], v185 offset:21504
	ds_read_b128 v[210:213], v185 offset:22528
	ds_read_b128 v[228:231], v185 offset:23552
	global_load_lds_dwordx4 v152, s[22:23]
	s_add_i32 m0, s64, 0x2000
	s_add_u32 s64, s22, 0x40000
	s_addc_u32 s65, s23, 0
	s_add_i32 s68, s68, s46
	global_load_lds_dwordx4 v148, s[22:23]
	s_mov_b32 m0, s68
	s_nop 0
	global_load_lds_dwordx4 v152, s[64:65]
	s_add_i32 m0, s68, 0x2000
	s_nop 0
	global_load_lds_dwordx4 v148, s[64:65]
	s_add_u32 s98, s24, s34
	s_addc_u32 s99, s25, s35
	s_mov_b32 m0, s50
	s_nop 0
	global_load_lds_dwordx4 v154, s[24:25]
	s_waitcnt vmcnt(7) lgkmcnt(0)
	s_barrier
	s_setprio 1
	v_mfma_f32_16x16x32_bf16 v[60:63], v[128:131], v[186:189], v[60:63]
	v_mfma_f32_16x16x32_bf16 v[56:59], v[136:139], v[186:189], v[56:59]
	v_mfma_f32_16x16x32_bf16 v[48:51], v[128:131], v[194:197], v[48:51]
	v_mfma_f32_16x16x32_bf16 v[40:43], v[136:139], v[194:197], v[40:43]
	v_mfma_f32_16x16x32_bf16 v[32:35], v[128:131], v[202:205], v[32:35]
	v_mfma_f32_16x16x32_bf16 v[24:27], v[136:139], v[202:205], v[24:27]
	v_mfma_f32_16x16x32_bf16 v[16:19], v[128:131], v[210:213], v[16:19]
	v_mfma_f32_16x16x32_bf16 v[8:11], v[136:139], v[210:213], v[8:11]
	v_mfma_f32_16x16x32_bf16 v[60:63], v[132:135], v[190:193], v[60:63]
	v_mfma_f32_16x16x32_bf16 v[56:59], v[140:143], v[190:193], v[56:59]
	v_mfma_f32_16x16x32_bf16 v[48:51], v[132:135], v[198:201], v[48:51]
	v_mfma_f32_16x16x32_bf16 v[40:43], v[140:143], v[198:201], v[40:43]
	v_mfma_f32_16x16x32_bf16 v[32:35], v[132:135], v[206:209], v[32:35]
	v_mfma_f32_16x16x32_bf16 v[24:27], v[140:143], v[206:209], v[24:27]
	v_mfma_f32_16x16x32_bf16 v[16:19], v[132:135], v[228:231], v[16:19]
	v_mfma_f32_16x16x32_bf16 v[8:11], v[140:143], v[228:231], v[8:11]
	v_mfma_f32_16x16x32_bf16 v[52:55], v[144:147], v[186:189], v[52:55]
	v_mfma_f32_16x16x32_bf16 v[44:47], v[166:169], v[186:189], v[44:47]
	v_mfma_f32_16x16x32_bf16 v[36:39], v[144:147], v[194:197], v[36:39]
	v_mfma_f32_16x16x32_bf16 v[28:31], v[166:169], v[194:197], v[28:31]
	v_mfma_f32_16x16x32_bf16 v[20:23], v[144:147], v[202:205], v[20:23]
	v_mfma_f32_16x16x32_bf16 v[12:15], v[166:169], v[202:205], v[12:15]
	v_mfma_f32_16x16x32_bf16 v[4:7], v[144:147], v[210:213], v[4:7]
	v_mfma_f32_16x16x32_bf16 v[0:3], v[166:169], v[210:213], v[0:3]
	v_mfma_f32_16x16x32_bf16 v[52:55], v[162:165], v[190:193], v[52:55]
	v_mfma_f32_16x16x32_bf16 v[44:47], v[170:173], v[190:193], v[44:47]
	v_mfma_f32_16x16x32_bf16 v[36:39], v[162:165], v[198:201], v[36:39]
	v_mfma_f32_16x16x32_bf16 v[28:31], v[170:173], v[198:201], v[28:31]
	s_setprio 2
	s_barrier
	v_mfma_f32_16x16x32_bf16 v[20:23], v[162:165], v[206:209], v[20:23]
	v_mfma_f32_16x16x32_bf16 v[12:15], v[170:173], v[206:209], v[12:15]
	v_mfma_f32_16x16x32_bf16 v[4:7], v[162:165], v[228:231], v[4:7]
	v_mfma_f32_16x16x32_bf16 v[0:3], v[170:173], v[228:231], v[0:3]
	s_setprio 0
	s_mov_b32 m0, s51
	s_nop 0
	global_load_lds_dwordx4 v150, s[24:25]
	s_add_i32 s64, 0, 0x18000
	s_add_i32 s65, 0, 0x1c000
	v_add_u32_e32 v140, s64, v175
	v_add_u32_e32 v170, s65, v175
	ds_read_b128 v[128:131], v140
	ds_read_b128 v[132:135], v140 offset:1024
	ds_read_b128 v[136:139], v140 offset:2048
	ds_read_b128 v[140:143], v140 offset:3072
	ds_read_b128 v[144:147], v170
	ds_read_b128 v[162:165], v170 offset:1024
	ds_read_b128 v[166:169], v170 offset:2048
	ds_read_b128 v[170:173], v170 offset:3072
	s_add_u32 s24, s24, 0x40000
	s_addc_u32 s25, s25, 0
	s_mov_b32 m0, s52
	ds_read_b128 v[186:189], v185 offset:32768
	ds_read_b128 v[190:193], v185 offset:33792
	ds_read_b128 v[194:197], v185 offset:34816
	ds_read_b128 v[198:201], v185 offset:35840
	ds_read_b128 v[202:205], v185 offset:36864
	ds_read_b128 v[206:209], v185 offset:37888
	ds_read_b128 v[210:213], v185 offset:38912
	ds_read_b128 v[228:231], v185 offset:39936
	global_load_lds_dwordx4 v154, s[24:25]
	s_mov_b32 m0, s53
	s_nop 0
	global_load_lds_dwordx4 v150, s[24:25]
	s_waitcnt vmcnt(8) lgkmcnt(0)
	s_barrier
	s_setprio 1
	v_mfma_f32_16x16x32_bf16 v[124:127], v[128:131], v[186:189], v[124:127]
	v_mfma_f32_16x16x32_bf16 v[120:123], v[136:139], v[186:189], v[120:123]
	v_mfma_f32_16x16x32_bf16 v[108:111], v[128:131], v[194:197], v[108:111]
	v_mfma_f32_16x16x32_bf16 v[104:107], v[136:139], v[194:197], v[104:107]
	v_mfma_f32_16x16x32_bf16 v[92:95], v[128:131], v[202:205], v[92:95]
	v_mfma_f32_16x16x32_bf16 v[88:91], v[136:139], v[202:205], v[88:91]
	v_mfma_f32_16x16x32_bf16 v[76:79], v[128:131], v[210:213], v[76:79]
	v_mfma_f32_16x16x32_bf16 v[72:75], v[136:139], v[210:213], v[72:75]
	v_mfma_f32_16x16x32_bf16 v[124:127], v[132:135], v[190:193], v[124:127]
	v_mfma_f32_16x16x32_bf16 v[120:123], v[140:143], v[190:193], v[120:123]
	v_mfma_f32_16x16x32_bf16 v[108:111], v[132:135], v[198:201], v[108:111]
	v_mfma_f32_16x16x32_bf16 v[104:107], v[140:143], v[198:201], v[104:107]
	v_mfma_f32_16x16x32_bf16 v[92:95], v[132:135], v[206:209], v[92:95]
	v_mfma_f32_16x16x32_bf16 v[88:91], v[140:143], v[206:209], v[88:91]
	v_mfma_f32_16x16x32_bf16 v[76:79], v[132:135], v[228:231], v[76:79]
	v_mfma_f32_16x16x32_bf16 v[72:75], v[140:143], v[228:231], v[72:75]
	v_mfma_f32_16x16x32_bf16 v[116:119], v[144:147], v[186:189], v[116:119]
	v_mfma_f32_16x16x32_bf16 v[112:115], v[166:169], v[186:189], v[112:115]
	v_mfma_f32_16x16x32_bf16 v[100:103], v[144:147], v[194:197], v[100:103]
	v_mfma_f32_16x16x32_bf16 v[96:99], v[166:169], v[194:197], v[96:99]
	v_mfma_f32_16x16x32_bf16 v[84:87], v[144:147], v[202:205], v[84:87]
	v_mfma_f32_16x16x32_bf16 v[80:83], v[166:169], v[202:205], v[80:83]
	v_mfma_f32_16x16x32_bf16 v[68:71], v[144:147], v[210:213], v[68:71]
	v_mfma_f32_16x16x32_bf16 v[64:67], v[166:169], v[210:213], v[64:67]
	v_mfma_f32_16x16x32_bf16 v[116:119], v[162:165], v[190:193], v[116:119]
	v_mfma_f32_16x16x32_bf16 v[112:115], v[170:173], v[190:193], v[112:115]
	v_mfma_f32_16x16x32_bf16 v[100:103], v[162:165], v[198:201], v[100:103]
	v_mfma_f32_16x16x32_bf16 v[96:99], v[170:173], v[198:201], v[96:99]
	s_setprio 2
	s_barrier
	v_mfma_f32_16x16x32_bf16 v[84:87], v[162:165], v[206:209], v[84:87]
	v_mfma_f32_16x16x32_bf16 v[80:83], v[170:173], v[206:209], v[80:83]
	v_mfma_f32_16x16x32_bf16 v[68:71], v[162:165], v[228:231], v[68:71]
	v_mfma_f32_16x16x32_bf16 v[64:67], v[170:173], v[228:231], v[64:67]
	s_setprio 0
	s_add_i32 s24, s64, s46
	s_mov_b32 m0, s24
	ds_read_b128 v[186:189], v185 offset:49152
	ds_read_b128 v[190:193], v185 offset:50176
	ds_read_b128 v[194:197], v185 offset:51200
	ds_read_b128 v[198:201], v185 offset:52224
	ds_read_b128 v[202:205], v185 offset:53248
	ds_read_b128 v[206:209], v185 offset:54272
	ds_read_b128 v[210:213], v185 offset:55296
	ds_read_b128 v[228:231], v185 offset:56320
	global_load_lds_dwordx4 v152, s[94:95]
	s_add_i32 m0, s24, 0x2000
	s_add_u32 s22, s22, 0x40080
	s_addc_u32 s23, s23, 0
	s_add_i32 s24, s65, s46
	global_load_lds_dwordx4 v148, s[94:95]
	s_mov_b32 m0, s24
	s_nop 0
	global_load_lds_dwordx4 v152, s[22:23]
	s_add_i32 m0, s24, 0x2000
	s_nop 0
	global_load_lds_dwordx4 v148, s[22:23]
	s_mov_b32 m0, s56
	s_nop 0
	global_load_lds_dwordx4 v154, s[98:99]
	s_mov_b32 m0, s57
	s_nop 0
	global_load_lds_dwordx4 v150, s[98:99]
	s_waitcnt vmcnt(8) lgkmcnt(0)
	s_barrier
	s_setprio 1
	v_mfma_f32_16x16x32_bf16 v[60:63], v[128:131], v[186:189], v[60:63]
	v_mfma_f32_16x16x32_bf16 v[56:59], v[136:139], v[186:189], v[56:59]
	v_mfma_f32_16x16x32_bf16 v[48:51], v[128:131], v[194:197], v[48:51]
	v_mfma_f32_16x16x32_bf16 v[40:43], v[136:139], v[194:197], v[40:43]
	v_mfma_f32_16x16x32_bf16 v[32:35], v[128:131], v[202:205], v[32:35]
	v_mfma_f32_16x16x32_bf16 v[24:27], v[136:139], v[202:205], v[24:27]
	v_mfma_f32_16x16x32_bf16 v[16:19], v[128:131], v[210:213], v[16:19]
	v_mfma_f32_16x16x32_bf16 v[8:11], v[136:139], v[210:213], v[8:11]
	v_mfma_f32_16x16x32_bf16 v[60:63], v[132:135], v[190:193], v[60:63]
	v_mfma_f32_16x16x32_bf16 v[56:59], v[140:143], v[190:193], v[56:59]
	v_mfma_f32_16x16x32_bf16 v[48:51], v[132:135], v[198:201], v[48:51]
	v_mfma_f32_16x16x32_bf16 v[40:43], v[140:143], v[198:201], v[40:43]
	v_mfma_f32_16x16x32_bf16 v[32:35], v[132:135], v[206:209], v[32:35]
	v_mfma_f32_16x16x32_bf16 v[24:27], v[140:143], v[206:209], v[24:27]
	v_mfma_f32_16x16x32_bf16 v[16:19], v[132:135], v[228:231], v[16:19]
	v_mfma_f32_16x16x32_bf16 v[8:11], v[140:143], v[228:231], v[8:11]
	v_mfma_f32_16x16x32_bf16 v[52:55], v[144:147], v[186:189], v[52:55]
	v_mfma_f32_16x16x32_bf16 v[44:47], v[166:169], v[186:189], v[44:47]
	v_mfma_f32_16x16x32_bf16 v[36:39], v[144:147], v[194:197], v[36:39]
	v_mfma_f32_16x16x32_bf16 v[28:31], v[166:169], v[194:197], v[28:31]
	v_mfma_f32_16x16x32_bf16 v[20:23], v[144:147], v[202:205], v[20:23]
	v_mfma_f32_16x16x32_bf16 v[12:15], v[166:169], v[202:205], v[12:15]
	v_mfma_f32_16x16x32_bf16 v[4:7], v[144:147], v[210:213], v[4:7]
	v_mfma_f32_16x16x32_bf16 v[0:3], v[166:169], v[210:213], v[0:3]
	v_mfma_f32_16x16x32_bf16 v[52:55], v[162:165], v[190:193], v[52:55]
	v_mfma_f32_16x16x32_bf16 v[44:47], v[170:173], v[190:193], v[44:47]
	v_mfma_f32_16x16x32_bf16 v[36:39], v[162:165], v[198:201], v[36:39]
	v_mfma_f32_16x16x32_bf16 v[28:31], v[170:173], v[198:201], v[28:31]
	s_setprio 2
	s_barrier
	v_mfma_f32_16x16x32_bf16 v[20:23], v[162:165], v[206:209], v[20:23]
	v_mfma_f32_16x16x32_bf16 v[12:15], v[170:173], v[206:209], v[12:15]
	v_mfma_f32_16x16x32_bf16 v[4:7], v[162:165], v[228:231], v[4:7]
	v_mfma_f32_16x16x32_bf16 v[0:3], v[170:173], v[228:231], v[0:3]
	s_setprio 0
	s_add_i32 s63, s63, 2
	s_add_u32 s61, s61, 0x100
	s_addc_u32 s62, s62, 0
	s_add_u32 s20, s20, 0x100
	s_addc_u32 s21, s21, 0
	s_cmp_gt_u32 s63, 13
	s_cbranch_scc0 .LBB0_634

.LBB0_768:
	s_add_u32 s44, s40, 0x100
	s_addc_u32 s55, s41, 0
	s_mov_b32 s92, -2
	s_add_u32 s40, s8, 0x100
	s_addc_u32 s41, s9, 0
	s_add_i32 s64, 0, 0x10000
	s_cmp_eq_u32 s92, 40
	s_cselect_b32 s53, s1, s41
	s_cselect_b32 s52, s0, s40
	s_cselect_b32 s51, s39, s55
	s_cselect_b32 s50, s38, s44
	s_add_i32 s65, 0, 0x14000
	v_add_u32_e32 v140, s64, v228
	v_add_u32_e32 v156, s65, v228
	ds_read_b128 v[128:131], v140
	ds_read_b128 v[132:135], v140 offset:1024
	ds_read_b128 v[136:139], v140 offset:2048
	ds_read_b128 v[140:143], v140 offset:3072
	ds_read_b128 v[144:147], v156
	ds_read_b128 v[148:151], v156 offset:1024
	ds_read_b128 v[152:155], v156 offset:2048
	ds_read_b128 v[156:159], v156 offset:3072
	s_add_i32 m0, s62, 0xc000
	ds_read_b128 v[160:163], v231
	ds_read_b128 v[164:167], v231 offset:1024
	ds_read_b128 v[186:189], v231 offset:2048
	ds_read_b128 v[190:193], v231 offset:3072
	ds_read_b128 v[194:197], v231 offset:4096
	ds_read_b128 v[198:201], v231 offset:5120
	ds_read_b128 v[202:205], v231 offset:6144
	ds_read_b128 v[206:209], v231 offset:7168
	global_load_lds_dwordx4 v184, s[8:9]
	s_add_i32 m0, s62, 0xe000
	s_nop 0
	global_load_lds_dwordx4 v182, s[8:9]
	s_waitcnt vmcnt(24) lgkmcnt(0)
	s_barrier
	s_setprio 1
	v_mfma_f32_16x16x32_bf16 v[124:127], v[128:131], v[160:163], 0
	v_mfma_f32_16x16x32_bf16 v[120:123], v[136:139], v[160:163], 0
	v_mfma_f32_16x16x32_bf16 v[108:111], v[128:131], v[186:189], 0
	v_mfma_f32_16x16x32_bf16 v[104:107], v[136:139], v[186:189], 0
	v_mfma_f32_16x16x32_bf16 v[92:95], v[128:131], v[194:197], 0
	v_mfma_f32_16x16x32_bf16 v[88:91], v[136:139], v[194:197], 0
	v_mfma_f32_16x16x32_bf16 v[76:79], v[128:131], v[202:205], 0
	v_mfma_f32_16x16x32_bf16 v[72:75], v[136:139], v[202:205], 0
	v_mfma_f32_16x16x32_bf16 v[124:127], v[132:135], v[164:167], v[124:127]
	v_mfma_f32_16x16x32_bf16 v[120:123], v[140:143], v[164:167], v[120:123]
	v_mfma_f32_16x16x32_bf16 v[108:111], v[132:135], v[190:193], v[108:111]
	v_mfma_f32_16x16x32_bf16 v[104:107], v[140:143], v[190:193], v[104:107]
	v_mfma_f32_16x16x32_bf16 v[92:95], v[132:135], v[198:201], v[92:95]
	v_mfma_f32_16x16x32_bf16 v[88:91], v[140:143], v[198:201], v[88:91]
	v_mfma_f32_16x16x32_bf16 v[76:79], v[132:135], v[206:209], v[76:79]
	v_mfma_f32_16x16x32_bf16 v[72:75], v[140:143], v[206:209], v[72:75]
	v_mfma_f32_16x16x32_bf16 v[116:119], v[144:147], v[160:163], 0
	v_mfma_f32_16x16x32_bf16 v[112:115], v[152:155], v[160:163], 0
	v_mfma_f32_16x16x32_bf16 v[100:103], v[144:147], v[186:189], 0
	v_mfma_f32_16x16x32_bf16 v[96:99], v[152:155], v[186:189], 0
	v_mfma_f32_16x16x32_bf16 v[84:87], v[144:147], v[194:197], 0
	v_mfma_f32_16x16x32_bf16 v[80:83], v[152:155], v[194:197], 0
	v_mfma_f32_16x16x32_bf16 v[68:71], v[144:147], v[202:205], 0
	v_mfma_f32_16x16x32_bf16 v[64:67], v[152:155], v[202:205], 0
	v_mfma_f32_16x16x32_bf16 v[116:119], v[148:151], v[164:167], v[116:119]
	v_mfma_f32_16x16x32_bf16 v[112:115], v[156:159], v[164:167], v[112:115]
	v_mfma_f32_16x16x32_bf16 v[100:103], v[148:151], v[190:193], v[100:103]
	v_mfma_f32_16x16x32_bf16 v[96:99], v[156:159], v[190:193], v[96:99]
	s_setprio 2
	s_barrier
	v_mfma_f32_16x16x32_bf16 v[84:87], v[148:151], v[198:201], v[84:87]
	v_mfma_f32_16x16x32_bf16 v[80:83], v[156:159], v[198:201], v[80:83]
	v_mfma_f32_16x16x32_bf16 v[68:71], v[148:151], v[206:209], v[68:71]
	v_mfma_f32_16x16x32_bf16 v[64:67], v[156:159], v[206:209], v[64:67]
	s_setprio 0
	s_add_i32 s8, s64, s37
	s_add_u32 s98, s50, s34
	s_addc_u32 s99, s51, s35
	s_mov_b32 m0, s8
	ds_read_b128 v[160:163], v231 offset:16384
	ds_read_b128 v[164:167], v231 offset:17408
	ds_read_b128 v[186:189], v231 offset:18432
	ds_read_b128 v[190:193], v231 offset:19456
	ds_read_b128 v[194:197], v231 offset:20480
	ds_read_b128 v[198:201], v231 offset:21504
	ds_read_b128 v[202:205], v231 offset:22528
	ds_read_b128 v[206:209], v231 offset:23552
	global_load_lds_dwordx4 v170, s[50:51]
	s_add_i32 m0, s8, 0x2000
	s_add_u32 s8, s50, 0xb0000
	s_addc_u32 s9, s51, 0
	s_add_i32 s64, s65, s37
	global_load_lds_dwordx4 v174, s[50:51]
	s_mov_b32 m0, s64
	s_nop 0
	global_load_lds_dwordx4 v170, s[8:9]
	s_add_i32 m0, s64, 0x2000
	s_nop 0
	global_load_lds_dwordx4 v174, s[8:9]
	s_add_u32 s100, s52, s34
	s_addc_u32 s101, s53, s35
	s_mov_b32 m0, s62
	s_nop 0
	global_load_lds_dwordx4 v168, s[52:53]
	s_waitcnt vmcnt(7) lgkmcnt(0)
	s_barrier
	s_setprio 1
	v_mfma_f32_16x16x32_bf16 v[60:63], v[128:131], v[160:163], 0
	v_mfma_f32_16x16x32_bf16 v[56:59], v[136:139], v[160:163], 0
	v_mfma_f32_16x16x32_bf16 v[44:47], v[128:131], v[186:189], 0
	v_mfma_f32_16x16x32_bf16 v[40:43], v[136:139], v[186:189], 0
	v_mfma_f32_16x16x32_bf16 v[28:31], v[128:131], v[194:197], 0
	v_mfma_f32_16x16x32_bf16 v[24:27], v[136:139], v[194:197], 0
	v_mfma_f32_16x16x32_bf16 v[12:15], v[128:131], v[202:205], 0
	v_mfma_f32_16x16x32_bf16 v[8:11], v[136:139], v[202:205], 0
	v_mfma_f32_16x16x32_bf16 v[60:63], v[132:135], v[164:167], v[60:63]
	v_mfma_f32_16x16x32_bf16 v[56:59], v[140:143], v[164:167], v[56:59]
	v_mfma_f32_16x16x32_bf16 v[44:47], v[132:135], v[190:193], v[44:47]
	v_mfma_f32_16x16x32_bf16 v[40:43], v[140:143], v[190:193], v[40:43]
	v_mfma_f32_16x16x32_bf16 v[28:31], v[132:135], v[198:201], v[28:31]
	v_mfma_f32_16x16x32_bf16 v[24:27], v[140:143], v[198:201], v[24:27]
	v_mfma_f32_16x16x32_bf16 v[12:15], v[132:135], v[206:209], v[12:15]
	v_mfma_f32_16x16x32_bf16 v[8:11], v[140:143], v[206:209], v[8:11]
	v_mfma_f32_16x16x32_bf16 v[52:55], v[144:147], v[160:163], 0
	v_mfma_f32_16x16x32_bf16 v[48:51], v[152:155], v[160:163], 0
	v_mfma_f32_16x16x32_bf16 v[36:39], v[144:147], v[186:189], 0
	v_mfma_f32_16x16x32_bf16 v[32:35], v[152:155], v[186:189], 0
	v_mfma_f32_16x16x32_bf16 v[20:23], v[144:147], v[194:197], 0
	v_mfma_f32_16x16x32_bf16 v[16:19], v[152:155], v[194:197], 0
	v_mfma_f32_16x16x32_bf16 v[4:7], v[144:147], v[202:205], 0
	v_mfma_f32_16x16x32_bf16 v[0:3], v[152:155], v[202:205], 0
	v_mfma_f32_16x16x32_bf16 v[52:55], v[148:151], v[164:167], v[52:55]
	v_mfma_f32_16x16x32_bf16 v[48:51], v[156:159], v[164:167], v[48:51]
	v_mfma_f32_16x16x32_bf16 v[36:39], v[148:151], v[190:193], v[36:39]
	v_mfma_f32_16x16x32_bf16 v[32:35], v[156:159], v[190:193], v[32:35]
	s_setprio 2
	s_barrier
	v_mfma_f32_16x16x32_bf16 v[20:23], v[148:151], v[198:201], v[20:23]
	v_mfma_f32_16x16x32_bf16 v[16:19], v[156:159], v[198:201], v[16:19]
	v_mfma_f32_16x16x32_bf16 v[4:7], v[148:151], v[206:209], v[4:7]
	v_mfma_f32_16x16x32_bf16 v[0:3], v[156:159], v[206:209], v[0:3]
	s_setprio 0
	s_mov_b32 m0, s63
	s_nop 0
	global_load_lds_dwordx4 v172, s[52:53]
	s_add_i32 s64, 0, 0x18000
	s_add_i32 s65, 0, 0x1c000
	v_add_u32_e32 v140, s64, v228
	v_add_u32_e32 v156, s65, v228
	ds_read_b128 v[128:131], v140
	ds_read_b128 v[132:135], v140 offset:1024
	ds_read_b128 v[136:139], v140 offset:2048
	ds_read_b128 v[140:143], v140 offset:3072
	ds_read_b128 v[144:147], v156
	ds_read_b128 v[148:151], v156 offset:1024
	ds_read_b128 v[152:155], v156 offset:2048
	ds_read_b128 v[156:159], v156 offset:3072
	s_add_u32 s8, s52, 0xb0000
	s_addc_u32 s9, s53, 0
	s_mov_b32 m0, s68
	ds_read_b128 v[160:163], v231 offset:32768
	ds_read_b128 v[164:167], v231 offset:33792
	ds_read_b128 v[186:189], v231 offset:34816
	ds_read_b128 v[190:193], v231 offset:35840
	ds_read_b128 v[194:197], v231 offset:36864
	ds_read_b128 v[198:201], v231 offset:37888
	ds_read_b128 v[202:205], v231 offset:38912
	ds_read_b128 v[206:209], v231 offset:39936
	global_load_lds_dwordx4 v168, s[8:9]
	s_mov_b32 m0, s69
	s_nop 0
	global_load_lds_dwordx4 v172, s[8:9]
	s_waitcnt vmcnt(8) lgkmcnt(0)
	s_barrier
	s_setprio 1
	v_mfma_f32_16x16x32_bf16 v[124:127], v[128:131], v[160:163], v[124:127]
	v_mfma_f32_16x16x32_bf16 v[120:123], v[136:139], v[160:163], v[120:123]
	v_mfma_f32_16x16x32_bf16 v[108:111], v[128:131], v[186:189], v[108:111]
	v_mfma_f32_16x16x32_bf16 v[104:107], v[136:139], v[186:189], v[104:107]
	v_mfma_f32_16x16x32_bf16 v[92:95], v[128:131], v[194:197], v[92:95]
	v_mfma_f32_16x16x32_bf16 v[88:91], v[136:139], v[194:197], v[88:91]
	v_mfma_f32_16x16x32_bf16 v[76:79], v[128:131], v[202:205], v[76:79]
	v_mfma_f32_16x16x32_bf16 v[72:75], v[136:139], v[202:205], v[72:75]
	v_mfma_f32_16x16x32_bf16 v[124:127], v[132:135], v[164:167], v[124:127]
	v_mfma_f32_16x16x32_bf16 v[120:123], v[140:143], v[164:167], v[120:123]
	v_mfma_f32_16x16x32_bf16 v[108:111], v[132:135], v[190:193], v[108:111]
	v_mfma_f32_16x16x32_bf16 v[104:107], v[140:143], v[190:193], v[104:107]
	v_mfma_f32_16x16x32_bf16 v[92:95], v[132:135], v[198:201], v[92:95]
	v_mfma_f32_16x16x32_bf16 v[88:91], v[140:143], v[198:201], v[88:91]
	v_mfma_f32_16x16x32_bf16 v[76:79], v[132:135], v[206:209], v[76:79]
	v_mfma_f32_16x16x32_bf16 v[72:75], v[140:143], v[206:209], v[72:75]
	v_mfma_f32_16x16x32_bf16 v[116:119], v[144:147], v[160:163], v[116:119]
	v_mfma_f32_16x16x32_bf16 v[112:115], v[152:155], v[160:163], v[112:115]
	v_mfma_f32_16x16x32_bf16 v[100:103], v[144:147], v[186:189], v[100:103]
	v_mfma_f32_16x16x32_bf16 v[96:99], v[152:155], v[186:189], v[96:99]
	v_mfma_f32_16x16x32_bf16 v[84:87], v[144:147], v[194:197], v[84:87]
	v_mfma_f32_16x16x32_bf16 v[80:83], v[152:155], v[194:197], v[80:83]
	v_mfma_f32_16x16x32_bf16 v[68:71], v[144:147], v[202:205], v[68:71]
	v_mfma_f32_16x16x32_bf16 v[64:67], v[152:155], v[202:205], v[64:67]
	v_mfma_f32_16x16x32_bf16 v[116:119], v[148:151], v[164:167], v[116:119]
	v_mfma_f32_16x16x32_bf16 v[112:115], v[156:159], v[164:167], v[112:115]
	v_mfma_f32_16x16x32_bf16 v[100:103], v[148:151], v[190:193], v[100:103]
	v_mfma_f32_16x16x32_bf16 v[96:99], v[156:159], v[190:193], v[96:99]
	s_setprio 2
	s_barrier
	v_mfma_f32_16x16x32_bf16 v[84:87], v[148:151], v[198:201], v[84:87]
	v_mfma_f32_16x16x32_bf16 v[80:83], v[156:159], v[198:201], v[80:83]
	v_mfma_f32_16x16x32_bf16 v[68:71], v[148:151], v[206:209], v[68:71]
	v_mfma_f32_16x16x32_bf16 v[64:67], v[156:159], v[206:209], v[64:67]
	s_setprio 0
	s_add_i32 s8, s64, s37
	s_mov_b32 m0, s8
	ds_read_b128 v[160:163], v231 offset:49152
	ds_read_b128 v[164:167], v231 offset:50176
	ds_read_b128 v[186:189], v231 offset:51200
	ds_read_b128 v[190:193], v231 offset:52224
	ds_read_b128 v[194:197], v231 offset:53248
	ds_read_b128 v[198:201], v231 offset:54272
	ds_read_b128 v[202:205], v231 offset:55296
	ds_read_b128 v[206:209], v231 offset:56320
	global_load_lds_dwordx4 v170, s[98:99]
	s_add_i32 m0, s8, 0x2000
	s_add_u32 s8, s50, 0xb0080
	s_addc_u32 s9, s51, 0
	s_add_i32 s50, s65, s37
	global_load_lds_dwordx4 v174, s[98:99]
	s_mov_b32 m0, s50
	s_nop 0
	global_load_lds_dwordx4 v170, s[8:9]
	s_add_i32 m0, s50, 0x2000
	s_nop 0
	global_load_lds_dwordx4 v174, s[8:9]
	s_mov_b32 m0, s73
	s_nop 0
	global_load_lds_dwordx4 v168, s[100:101]
	s_mov_b32 m0, s74
	s_nop 0
	global_load_lds_dwordx4 v172, s[100:101]
	s_waitcnt vmcnt(8) lgkmcnt(0)
	s_barrier
	s_setprio 1
	v_mfma_f32_16x16x32_bf16 v[60:63], v[128:131], v[160:163], v[60:63]
	v_mfma_f32_16x16x32_bf16 v[56:59], v[136:139], v[160:163], v[56:59]
	v_mfma_f32_16x16x32_bf16 v[44:47], v[128:131], v[186:189], v[44:47]
	v_mfma_f32_16x16x32_bf16 v[40:43], v[136:139], v[186:189], v[40:43]
	v_mfma_f32_16x16x32_bf16 v[28:31], v[128:131], v[194:197], v[28:31]
	v_mfma_f32_16x16x32_bf16 v[24:27], v[136:139], v[194:197], v[24:27]
	v_mfma_f32_16x16x32_bf16 v[12:15], v[128:131], v[202:205], v[12:15]
	v_mfma_f32_16x16x32_bf16 v[8:11], v[136:139], v[202:205], v[8:11]
	v_mfma_f32_16x16x32_bf16 v[60:63], v[132:135], v[164:167], v[60:63]
	v_mfma_f32_16x16x32_bf16 v[56:59], v[140:143], v[164:167], v[56:59]
	v_mfma_f32_16x16x32_bf16 v[44:47], v[132:135], v[190:193], v[44:47]
	v_mfma_f32_16x16x32_bf16 v[40:43], v[140:143], v[190:193], v[40:43]
	v_mfma_f32_16x16x32_bf16 v[28:31], v[132:135], v[198:201], v[28:31]
	v_mfma_f32_16x16x32_bf16 v[24:27], v[140:143], v[198:201], v[24:27]
	v_mfma_f32_16x16x32_bf16 v[12:15], v[132:135], v[206:209], v[12:15]
	v_mfma_f32_16x16x32_bf16 v[8:11], v[140:143], v[206:209], v[8:11]
	v_mfma_f32_16x16x32_bf16 v[52:55], v[144:147], v[160:163], v[52:55]
	v_mfma_f32_16x16x32_bf16 v[48:51], v[152:155], v[160:163], v[48:51]
	v_mfma_f32_16x16x32_bf16 v[36:39], v[144:147], v[186:189], v[36:39]
	v_mfma_f32_16x16x32_bf16 v[32:35], v[152:155], v[186:189], v[32:35]
	v_mfma_f32_16x16x32_bf16 v[20:23], v[144:147], v[194:197], v[20:23]
	v_mfma_f32_16x16x32_bf16 v[16:19], v[152:155], v[194:197], v[16:19]
	v_mfma_f32_16x16x32_bf16 v[4:7], v[144:147], v[202:205], v[4:7]
	v_mfma_f32_16x16x32_bf16 v[0:3], v[152:155], v[202:205], v[0:3]
	v_mfma_f32_16x16x32_bf16 v[52:55], v[148:151], v[164:167], v[52:55]
	v_mfma_f32_16x16x32_bf16 v[48:51], v[156:159], v[164:167], v[48:51]
	v_mfma_f32_16x16x32_bf16 v[36:39], v[148:151], v[190:193], v[36:39]
	v_mfma_f32_16x16x32_bf16 v[32:35], v[156:159], v[190:193], v[32:35]
	s_setprio 2
	s_barrier
	v_mfma_f32_16x16x32_bf16 v[20:23], v[148:151], v[198:201], v[20:23]
	v_mfma_f32_16x16x32_bf16 v[16:19], v[156:159], v[198:201], v[16:19]
	v_mfma_f32_16x16x32_bf16 v[4:7], v[148:151], v[206:209], v[4:7]
	v_mfma_f32_16x16x32_bf16 v[0:3], v[156:159], v[206:209], v[0:3]
	s_setprio 0
	s_add_i32 s92, s92, 2
	s_add_u32 s44, s44, 0x100
	s_addc_u32 s55, s55, 0
	s_cmp_gt_u32 s92, 41
	s_mov_b64 s[8:9], s[40:41]
	s_cbranch_scc1 .Lpeel_exit_2
.LBB0_769:
	s_add_u32 s40, s8, 0x100
	s_addc_u32 s41, s9, 0
	s_add_i32 s64, 0, 0x10000
	s_cmp_eq_u32 s92, 40
	s_cselect_b32 s53, s1, s41
	s_cselect_b32 s52, s0, s40
	s_cselect_b32 s51, s39, s55
	s_cselect_b32 s50, s38, s44
	s_add_i32 s65, 0, 0x14000
	v_add_u32_e32 v140, s64, v228
	v_add_u32_e32 v156, s65, v228
	ds_read_b128 v[128:131], v140
	ds_read_b128 v[132:135], v140 offset:1024
	ds_read_b128 v[136:139], v140 offset:2048
	ds_read_b128 v[140:143], v140 offset:3072
	ds_read_b128 v[144:147], v156
	ds_read_b128 v[148:151], v156 offset:1024
	ds_read_b128 v[152:155], v156 offset:2048
	ds_read_b128 v[156:159], v156 offset:3072
	s_add_i32 m0, s62, 0xc000
	ds_read_b128 v[160:163], v231
	ds_read_b128 v[164:167], v231 offset:1024
	ds_read_b128 v[186:189], v231 offset:2048
	ds_read_b128 v[190:193], v231 offset:3072
	ds_read_b128 v[194:197], v231 offset:4096
	ds_read_b128 v[198:201], v231 offset:5120
	ds_read_b128 v[202:205], v231 offset:6144
	ds_read_b128 v[206:209], v231 offset:7168
	global_load_lds_dwordx4 v184, s[8:9]
	s_add_i32 m0, s62, 0xe000
	s_nop 0
	global_load_lds_dwordx4 v182, s[8:9]
	s_waitcnt vmcnt(8) lgkmcnt(0)
	s_barrier
	s_setprio 1
	v_mfma_f32_16x16x32_bf16 v[124:127], v[128:131], v[160:163], v[124:127]
	v_mfma_f32_16x16x32_bf16 v[120:123], v[136:139], v[160:163], v[120:123]
	v_mfma_f32_16x16x32_bf16 v[108:111], v[128:131], v[186:189], v[108:111]
	v_mfma_f32_16x16x32_bf16 v[104:107], v[136:139], v[186:189], v[104:107]
	v_mfma_f32_16x16x32_bf16 v[92:95], v[128:131], v[194:197], v[92:95]
	v_mfma_f32_16x16x32_bf16 v[88:91], v[136:139], v[194:197], v[88:91]
	v_mfma_f32_16x16x32_bf16 v[76:79], v[128:131], v[202:205], v[76:79]
	v_mfma_f32_16x16x32_bf16 v[72:75], v[136:139], v[202:205], v[72:75]
	v_mfma_f32_16x16x32_bf16 v[124:127], v[132:135], v[164:167], v[124:127]
	v_mfma_f32_16x16x32_bf16 v[120:123], v[140:143], v[164:167], v[120:123]
	v_mfma_f32_16x16x32_bf16 v[108:111], v[132:135], v[190:193], v[108:111]
	v_mfma_f32_16x16x32_bf16 v[104:107], v[140:143], v[190:193], v[104:107]
	v_mfma_f32_16x16x32_bf16 v[92:95], v[132:135], v[198:201], v[92:95]
	v_mfma_f32_16x16x32_bf16 v[88:91], v[140:143], v[198:201], v[88:91]
	v_mfma_f32_16x16x32_bf16 v[76:79], v[132:135], v[206:209], v[76:79]
	v_mfma_f32_16x16x32_bf16 v[72:75], v[140:143], v[206:209], v[72:75]
	v_mfma_f32_16x16x32_bf16 v[116:119], v[144:147], v[160:163], v[116:119]
	v_mfma_f32_16x16x32_bf16 v[112:115], v[152:155], v[160:163], v[112:115]
	v_mfma_f32_16x16x32_bf16 v[100:103], v[144:147], v[186:189], v[100:103]
	v_mfma_f32_16x16x32_bf16 v[96:99], v[152:155], v[186:189], v[96:99]
	v_mfma_f32_16x16x32_bf16 v[84:87], v[144:147], v[194:197], v[84:87]
	v_mfma_f32_16x16x32_bf16 v[80:83], v[152:155], v[194:197], v[80:83]
	v_mfma_f32_16x16x32_bf16 v[68:71], v[144:147], v[202:205], v[68:71]
	v_mfma_f32_16x16x32_bf16 v[64:67], v[152:155], v[202:205], v[64:67]
	v_mfma_f32_16x16x32_bf16 v[116:119], v[148:151], v[164:167], v[116:119]
	v_mfma_f32_16x16x32_bf16 v[112:115], v[156:159], v[164:167], v[112:115]
	v_mfma_f32_16x16x32_bf16 v[100:103], v[148:151], v[190:193], v[100:103]
	v_mfma_f32_16x16x32_bf16 v[96:99], v[156:159], v[190:193], v[96:99]
	s_setprio 2
	s_barrier
	v_mfma_f32_16x16x32_bf16 v[84:87], v[148:151], v[198:201], v[84:87]
	v_mfma_f32_16x16x32_bf16 v[80:83], v[156:159], v[198:201], v[80:83]
	v_mfma_f32_16x16x32_bf16 v[68:71], v[148:151], v[206:209], v[68:71]
	v_mfma_f32_16x16x32_bf16 v[64:67], v[156:159], v[206:209], v[64:67]
	s_setprio 0
	s_add_i32 s8, s64, s37
	s_add_u32 s98, s50, s34
	s_addc_u32 s99, s51, s35
	s_mov_b32 m0, s8
	ds_read_b128 v[160:163], v231 offset:16384
	ds_read_b128 v[164:167], v231 offset:17408
	ds_read_b128 v[186:189], v231 offset:18432
	ds_read_b128 v[190:193], v231 offset:19456
	ds_read_b128 v[194:197], v231 offset:20480
	ds_read_b128 v[198:201], v231 offset:21504
	ds_read_b128 v[202:205], v231 offset:22528
	ds_read_b128 v[206:209], v231 offset:23552
	global_load_lds_dwordx4 v170, s[50:51]
	s_add_i32 m0, s8, 0x2000
	s_add_u32 s8, s50, 0xb0000
	s_addc_u32 s9, s51, 0
	s_add_i32 s64, s65, s37
	global_load_lds_dwordx4 v174, s[50:51]
	s_mov_b32 m0, s64
	s_nop 0
	global_load_lds_dwordx4 v170, s[8:9]
	s_add_i32 m0, s64, 0x2000
	s_nop 0
	global_load_lds_dwordx4 v174, s[8:9]
	s_add_u32 s100, s52, s34
	s_addc_u32 s101, s53, s35
	s_mov_b32 m0, s62
	s_nop 0
	global_load_lds_dwordx4 v168, s[52:53]
	s_waitcnt vmcnt(7) lgkmcnt(0)
	s_barrier
	s_setprio 1
	v_mfma_f32_16x16x32_bf16 v[60:63], v[128:131], v[160:163], v[60:63]
	v_mfma_f32_16x16x32_bf16 v[56:59], v[136:139], v[160:163], v[56:59]
	v_mfma_f32_16x16x32_bf16 v[44:47], v[128:131], v[186:189], v[44:47]
	v_mfma_f32_16x16x32_bf16 v[40:43], v[136:139], v[186:189], v[40:43]
	v_mfma_f32_16x16x32_bf16 v[28:31], v[128:131], v[194:197], v[28:31]
	v_mfma_f32_16x16x32_bf16 v[24:27], v[136:139], v[194:197], v[24:27]
	v_mfma_f32_16x16x32_bf16 v[12:15], v[128:131], v[202:205], v[12:15]
	v_mfma_f32_16x16x32_bf16 v[8:11], v[136:139], v[202:205], v[8:11]
	v_mfma_f32_16x16x32_bf16 v[60:63], v[132:135], v[164:167], v[60:63]
	v_mfma_f32_16x16x32_bf16 v[56:59], v[140:143], v[164:167], v[56:59]
	v_mfma_f32_16x16x32_bf16 v[44:47], v[132:135], v[190:193], v[44:47]
	v_mfma_f32_16x16x32_bf16 v[40:43], v[140:143], v[190:193], v[40:43]
	v_mfma_f32_16x16x32_bf16 v[28:31], v[132:135], v[198:201], v[28:31]
	v_mfma_f32_16x16x32_bf16 v[24:27], v[140:143], v[198:201], v[24:27]
	v_mfma_f32_16x16x32_bf16 v[12:15], v[132:135], v[206:209], v[12:15]
	v_mfma_f32_16x16x32_bf16 v[8:11], v[140:143], v[206:209], v[8:11]
	v_mfma_f32_16x16x32_bf16 v[52:55], v[144:147], v[160:163], v[52:55]
	v_mfma_f32_16x16x32_bf16 v[48:51], v[152:155], v[160:163], v[48:51]
	v_mfma_f32_16x16x32_bf16 v[36:39], v[144:147], v[186:189], v[36:39]
	v_mfma_f32_16x16x32_bf16 v[32:35], v[152:155], v[186:189], v[32:35]
	v_mfma_f32_16x16x32_bf16 v[20:23], v[144:147], v[194:197], v[20:23]
	v_mfma_f32_16x16x32_bf16 v[16:19], v[152:155], v[194:197], v[16:19]
	v_mfma_f32_16x16x32_bf16 v[4:7], v[144:147], v[202:205], v[4:7]
	v_mfma_f32_16x16x32_bf16 v[0:3], v[152:155], v[202:205], v[0:3]
	v_mfma_f32_16x16x32_bf16 v[52:55], v[148:151], v[164:167], v[52:55]
	v_mfma_f32_16x16x32_bf16 v[48:51], v[156:159], v[164:167], v[48:51]
	v_mfma_f32_16x16x32_bf16 v[36:39], v[148:151], v[190:193], v[36:39]
	v_mfma_f32_16x16x32_bf16 v[32:35], v[156:159], v[190:193], v[32:35]
	s_setprio 2
	s_barrier
	v_mfma_f32_16x16x32_bf16 v[20:23], v[148:151], v[198:201], v[20:23]
	v_mfma_f32_16x16x32_bf16 v[16:19], v[156:159], v[198:201], v[16:19]
	v_mfma_f32_16x16x32_bf16 v[4:7], v[148:151], v[206:209], v[4:7]
	v_mfma_f32_16x16x32_bf16 v[0:3], v[156:159], v[206:209], v[0:3]
	s_setprio 0
	s_mov_b32 m0, s63
	s_nop 0
	global_load_lds_dwordx4 v172, s[52:53]
	s_add_i32 s64, 0, 0x18000
	s_add_i32 s65, 0, 0x1c000
	v_add_u32_e32 v140, s64, v228
	v_add_u32_e32 v156, s65, v228
	ds_read_b128 v[128:131], v140
	ds_read_b128 v[132:135], v140 offset:1024
	ds_read_b128 v[136:139], v140 offset:2048
	ds_read_b128 v[140:143], v140 offset:3072
	ds_read_b128 v[144:147], v156
	ds_read_b128 v[148:151], v156 offset:1024
	ds_read_b128 v[152:155], v156 offset:2048
	ds_read_b128 v[156:159], v156 offset:3072
	s_add_u32 s8, s52, 0xb0000
	s_addc_u32 s9, s53, 0
	s_mov_b32 m0, s68
	ds_read_b128 v[160:163], v231 offset:32768
	ds_read_b128 v[164:167], v231 offset:33792
	ds_read_b128 v[186:189], v231 offset:34816
	ds_read_b128 v[190:193], v231 offset:35840
	ds_read_b128 v[194:197], v231 offset:36864
	ds_read_b128 v[198:201], v231 offset:37888
	ds_read_b128 v[202:205], v231 offset:38912
	ds_read_b128 v[206:209], v231 offset:39936
	global_load_lds_dwordx4 v168, s[8:9]
	s_mov_b32 m0, s69
	s_nop 0
	global_load_lds_dwordx4 v172, s[8:9]
	s_waitcnt vmcnt(8) lgkmcnt(0)
	s_barrier
	s_setprio 1
	v_mfma_f32_16x16x32_bf16 v[124:127], v[128:131], v[160:163], v[124:127]
	v_mfma_f32_16x16x32_bf16 v[120:123], v[136:139], v[160:163], v[120:123]
	v_mfma_f32_16x16x32_bf16 v[108:111], v[128:131], v[186:189], v[108:111]
	v_mfma_f32_16x16x32_bf16 v[104:107], v[136:139], v[186:189], v[104:107]
	v_mfma_f32_16x16x32_bf16 v[92:95], v[128:131], v[194:197], v[92:95]
	v_mfma_f32_16x16x32_bf16 v[88:91], v[136:139], v[194:197], v[88:91]
	v_mfma_f32_16x16x32_bf16 v[76:79], v[128:131], v[202:205], v[76:79]
	v_mfma_f32_16x16x32_bf16 v[72:75], v[136:139], v[202:205], v[72:75]
	v_mfma_f32_16x16x32_bf16 v[124:127], v[132:135], v[164:167], v[124:127]
	v_mfma_f32_16x16x32_bf16 v[120:123], v[140:143], v[164:167], v[120:123]
	v_mfma_f32_16x16x32_bf16 v[108:111], v[132:135], v[190:193], v[108:111]
	v_mfma_f32_16x16x32_bf16 v[104:107], v[140:143], v[190:193], v[104:107]
	v_mfma_f32_16x16x32_bf16 v[92:95], v[132:135], v[198:201], v[92:95]
	v_mfma_f32_16x16x32_bf16 v[88:91], v[140:143], v[198:201], v[88:91]
	v_mfma_f32_16x16x32_bf16 v[76:79], v[132:135], v[206:209], v[76:79]
	v_mfma_f32_16x16x32_bf16 v[72:75], v[140:143], v[206:209], v[72:75]
	v_mfma_f32_16x16x32_bf16 v[116:119], v[144:147], v[160:163], v[116:119]
	v_mfma_f32_16x16x32_bf16 v[112:115], v[152:155], v[160:163], v[112:115]
	v_mfma_f32_16x16x32_bf16 v[100:103], v[144:147], v[186:189], v[100:103]
	v_mfma_f32_16x16x32_bf16 v[96:99], v[152:155], v[186:189], v[96:99]
	v_mfma_f32_16x16x32_bf16 v[84:87], v[144:147], v[194:197], v[84:87]
	v_mfma_f32_16x16x32_bf16 v[80:83], v[152:155], v[194:197], v[80:83]
	v_mfma_f32_16x16x32_bf16 v[68:71], v[144:147], v[202:205], v[68:71]
	v_mfma_f32_16x16x32_bf16 v[64:67], v[152:155], v[202:205], v[64:67]
	v_mfma_f32_16x16x32_bf16 v[116:119], v[148:151], v[164:167], v[116:119]
	v_mfma_f32_16x16x32_bf16 v[112:115], v[156:159], v[164:167], v[112:115]
	v_mfma_f32_16x16x32_bf16 v[100:103], v[148:151], v[190:193], v[100:103]
	v_mfma_f32_16x16x32_bf16 v[96:99], v[156:159], v[190:193], v[96:99]
	s_setprio 2
	s_barrier
	v_mfma_f32_16x16x32_bf16 v[84:87], v[148:151], v[198:201], v[84:87]
	v_mfma_f32_16x16x32_bf16 v[80:83], v[156:159], v[198:201], v[80:83]
	v_mfma_f32_16x16x32_bf16 v[68:71], v[148:151], v[206:209], v[68:71]
	v_mfma_f32_16x16x32_bf16 v[64:67], v[156:159], v[206:209], v[64:67]
	s_setprio 0
	s_add_i32 s8, s64, s37
	s_mov_b32 m0, s8
	ds_read_b128 v[160:163], v231 offset:49152
	ds_read_b128 v[164:167], v231 offset:50176
	ds_read_b128 v[186:189], v231 offset:51200
	ds_read_b128 v[190:193], v231 offset:52224
	ds_read_b128 v[194:197], v231 offset:53248
	ds_read_b128 v[198:201], v231 offset:54272
	ds_read_b128 v[202:205], v231 offset:55296
	ds_read_b128 v[206:209], v231 offset:56320
	global_load_lds_dwordx4 v170, s[98:99]
	s_add_i32 m0, s8, 0x2000
	s_add_u32 s8, s50, 0xb0080
	s_addc_u32 s9, s51, 0
	s_add_i32 s50, s65, s37
	global_load_lds_dwordx4 v174, s[98:99]
	s_mov_b32 m0, s50
	s_nop 0
	global_load_lds_dwordx4 v170, s[8:9]
	s_add_i32 m0, s50, 0x2000
	s_nop 0
	global_load_lds_dwordx4 v174, s[8:9]
	s_mov_b32 m0, s73
	s_nop 0
	global_load_lds_dwordx4 v168, s[100:101]
	s_mov_b32 m0, s74
	s_nop 0
	global_load_lds_dwordx4 v172, s[100:101]
	s_waitcnt vmcnt(8) lgkmcnt(0)
	s_barrier
	s_setprio 1
	v_mfma_f32_16x16x32_bf16 v[60:63], v[128:131], v[160:163], v[60:63]
	v_mfma_f32_16x16x32_bf16 v[56:59], v[136:139], v[160:163], v[56:59]
	v_mfma_f32_16x16x32_bf16 v[44:47], v[128:131], v[186:189], v[44:47]
	v_mfma_f32_16x16x32_bf16 v[40:43], v[136:139], v[186:189], v[40:43]
	v_mfma_f32_16x16x32_bf16 v[28:31], v[128:131], v[194:197], v[28:31]
	v_mfma_f32_16x16x32_bf16 v[24:27], v[136:139], v[194:197], v[24:27]
	v_mfma_f32_16x16x32_bf16 v[12:15], v[128:131], v[202:205], v[12:15]
	v_mfma_f32_16x16x32_bf16 v[8:11], v[136:139], v[202:205], v[8:11]
	v_mfma_f32_16x16x32_bf16 v[60:63], v[132:135], v[164:167], v[60:63]
	v_mfma_f32_16x16x32_bf16 v[56:59], v[140:143], v[164:167], v[56:59]
	v_mfma_f32_16x16x32_bf16 v[44:47], v[132:135], v[190:193], v[44:47]
	v_mfma_f32_16x16x32_bf16 v[40:43], v[140:143], v[190:193], v[40:43]
	v_mfma_f32_16x16x32_bf16 v[28:31], v[132:135], v[198:201], v[28:31]
	v_mfma_f32_16x16x32_bf16 v[24:27], v[140:143], v[198:201], v[24:27]
	v_mfma_f32_16x16x32_bf16 v[12:15], v[132:135], v[206:209], v[12:15]
	v_mfma_f32_16x16x32_bf16 v[8:11], v[140:143], v[206:209], v[8:11]
	v_mfma_f32_16x16x32_bf16 v[52:55], v[144:147], v[160:163], v[52:55]
	v_mfma_f32_16x16x32_bf16 v[48:51], v[152:155], v[160:163], v[48:51]
	v_mfma_f32_16x16x32_bf16 v[36:39], v[144:147], v[186:189], v[36:39]
	v_mfma_f32_16x16x32_bf16 v[32:35], v[152:155], v[186:189], v[32:35]
	v_mfma_f32_16x16x32_bf16 v[20:23], v[144:147], v[194:197], v[20:23]
	v_mfma_f32_16x16x32_bf16 v[16:19], v[152:155], v[194:197], v[16:19]
	v_mfma_f32_16x16x32_bf16 v[4:7], v[144:147], v[202:205], v[4:7]
	v_mfma_f32_16x16x32_bf16 v[0:3], v[152:155], v[202:205], v[0:3]
	v_mfma_f32_16x16x32_bf16 v[52:55], v[148:151], v[164:167], v[52:55]
	v_mfma_f32_16x16x32_bf16 v[48:51], v[156:159], v[164:167], v[48:51]
	v_mfma_f32_16x16x32_bf16 v[36:39], v[148:151], v[190:193], v[36:39]
	v_mfma_f32_16x16x32_bf16 v[32:35], v[156:159], v[190:193], v[32:35]
	s_setprio 2
	s_barrier
	v_mfma_f32_16x16x32_bf16 v[20:23], v[148:151], v[198:201], v[20:23]
	v_mfma_f32_16x16x32_bf16 v[16:19], v[156:159], v[198:201], v[16:19]
	v_mfma_f32_16x16x32_bf16 v[4:7], v[148:151], v[206:209], v[4:7]
	v_mfma_f32_16x16x32_bf16 v[0:3], v[156:159], v[206:209], v[0:3]
	s_setprio 0
	s_add_i32 s92, s92, 2
	s_add_u32 s44, s44, 0x100
	s_addc_u32 s55, s55, 0
	s_cmp_gt_u32 s92, 41
	s_mov_b64 s[8:9], s[40:41]
	s_cbranch_scc0 .LBB0_769

.LBB0_862:
	s_add_i32 s27, s63, -2
	s_add_u32 vcc_lo, s40, 0x100
	s_addc_u32 vcc_hi, s41, 0
	s_mov_b32 s50, 0
	s_add_i32 s64, s50, 2
	s_add_u32 s40, s8, 0x100
	s_addc_u32 s41, s9, 0
	s_add_i32 s65, 0, 0x10000
	s_cmp_eq_u32 s27, s50
	s_cselect_b32 s53, s29, s41
	s_cselect_b32 s52, s28, s40
	s_cselect_b32 s51, s39, vcc_hi
	s_cselect_b32 s50, s38, vcc_lo
	s_add_i32 s66, 0, 0x14000
	v_add_u32_e32 v140, s65, v228
	v_add_u32_e32 v156, s66, v228
	ds_read_b128 v[128:131], v140
	ds_read_b128 v[132:135], v140 offset:1024
	ds_read_b128 v[136:139], v140 offset:2048
	ds_read_b128 v[140:143], v140 offset:3072
	ds_read_b128 v[144:147], v156
	ds_read_b128 v[148:151], v156 offset:1024
	ds_read_b128 v[152:155], v156 offset:2048
	ds_read_b128 v[156:159], v156 offset:3072
	s_add_i32 m0, s74, 0xc000
	ds_read_b128 v[160:163], v232
	ds_read_b128 v[164:167], v232 offset:1024
	ds_read_b128 v[186:189], v232 offset:2048
	ds_read_b128 v[190:193], v232 offset:3072
	ds_read_b128 v[194:197], v232 offset:4096
	ds_read_b128 v[198:201], v232 offset:5120
	ds_read_b128 v[202:205], v232 offset:6144
	ds_read_b128 v[206:209], v232 offset:7168
	global_load_lds_dwordx4 v184, s[8:9]
	s_add_i32 m0, s74, 0xe000
	s_nop 0
	global_load_lds_dwordx4 v182, s[8:9]
	s_waitcnt vmcnt(24) lgkmcnt(0)
	s_barrier
	s_setprio 1
	v_mfma_f32_16x16x32_bf16 v[124:127], v[128:131], v[160:163], 0
	v_mfma_f32_16x16x32_bf16 v[120:123], v[136:139], v[160:163], 0
	v_mfma_f32_16x16x32_bf16 v[108:111], v[128:131], v[186:189], 0
	v_mfma_f32_16x16x32_bf16 v[104:107], v[136:139], v[186:189], 0
	v_mfma_f32_16x16x32_bf16 v[92:95], v[128:131], v[194:197], 0
	v_mfma_f32_16x16x32_bf16 v[88:91], v[136:139], v[194:197], 0
	v_mfma_f32_16x16x32_bf16 v[76:79], v[128:131], v[202:205], 0
	v_mfma_f32_16x16x32_bf16 v[72:75], v[136:139], v[202:205], 0
	v_mfma_f32_16x16x32_bf16 v[124:127], v[132:135], v[164:167], v[124:127]
	v_mfma_f32_16x16x32_bf16 v[120:123], v[140:143], v[164:167], v[120:123]
	v_mfma_f32_16x16x32_bf16 v[108:111], v[132:135], v[190:193], v[108:111]
	v_mfma_f32_16x16x32_bf16 v[104:107], v[140:143], v[190:193], v[104:107]
	v_mfma_f32_16x16x32_bf16 v[92:95], v[132:135], v[198:201], v[92:95]
	v_mfma_f32_16x16x32_bf16 v[88:91], v[140:143], v[198:201], v[88:91]
	v_mfma_f32_16x16x32_bf16 v[76:79], v[132:135], v[206:209], v[76:79]
	v_mfma_f32_16x16x32_bf16 v[72:75], v[140:143], v[206:209], v[72:75]
	v_mfma_f32_16x16x32_bf16 v[116:119], v[144:147], v[160:163], 0
	v_mfma_f32_16x16x32_bf16 v[112:115], v[152:155], v[160:163], 0
	v_mfma_f32_16x16x32_bf16 v[100:103], v[144:147], v[186:189], 0
	v_mfma_f32_16x16x32_bf16 v[96:99], v[152:155], v[186:189], 0
	v_mfma_f32_16x16x32_bf16 v[84:87], v[144:147], v[194:197], 0
	v_mfma_f32_16x16x32_bf16 v[80:83], v[152:155], v[194:197], 0
	v_mfma_f32_16x16x32_bf16 v[68:71], v[144:147], v[202:205], 0
	v_mfma_f32_16x16x32_bf16 v[64:67], v[152:155], v[202:205], 0
	v_mfma_f32_16x16x32_bf16 v[116:119], v[148:151], v[164:167], v[116:119]
	v_mfma_f32_16x16x32_bf16 v[112:115], v[156:159], v[164:167], v[112:115]
	v_mfma_f32_16x16x32_bf16 v[100:103], v[148:151], v[190:193], v[100:103]
	v_mfma_f32_16x16x32_bf16 v[96:99], v[156:159], v[190:193], v[96:99]
	s_setprio 2
	s_barrier
	v_mfma_f32_16x16x32_bf16 v[84:87], v[148:151], v[198:201], v[84:87]
	v_mfma_f32_16x16x32_bf16 v[80:83], v[156:159], v[198:201], v[80:83]
	v_mfma_f32_16x16x32_bf16 v[68:71], v[148:151], v[206:209], v[68:71]
	v_mfma_f32_16x16x32_bf16 v[64:67], v[156:159], v[206:209], v[64:67]
	s_setprio 0
	s_add_i32 s8, s65, s72
	s_add_u32 s98, s50, s34
	s_addc_u32 s99, s51, s35
	s_mov_b32 m0, s8
	ds_read_b128 v[160:163], v232 offset:16384
	ds_read_b128 v[164:167], v232 offset:17408
	ds_read_b128 v[186:189], v232 offset:18432
	ds_read_b128 v[190:193], v232 offset:19456
	ds_read_b128 v[194:197], v232 offset:20480
	ds_read_b128 v[198:201], v232 offset:21504
	ds_read_b128 v[202:205], v232 offset:22528
	ds_read_b128 v[206:209], v232 offset:23552
	global_load_lds_dwordx4 v170, s[50:51]
	s_add_i32 m0, s8, 0x2000
	s_add_u32 s8, s50, 0xb0000
	s_addc_u32 s9, s51, 0
	s_add_i32 s65, s66, s72
	global_load_lds_dwordx4 v174, s[50:51]
	s_mov_b32 m0, s65
	s_nop 0
	global_load_lds_dwordx4 v170, s[8:9]
	s_add_i32 m0, s65, 0x2000
	s_nop 0
	global_load_lds_dwordx4 v174, s[8:9]
	s_add_u32 s100, s52, s34
	s_addc_u32 s101, s53, s35
	s_mov_b32 m0, s74
	s_nop 0
	global_load_lds_dwordx4 v168, s[52:53]
	s_waitcnt vmcnt(7) lgkmcnt(0)
	s_barrier
	s_setprio 1
	v_mfma_f32_16x16x32_bf16 v[60:63], v[128:131], v[160:163], 0
	v_mfma_f32_16x16x32_bf16 v[56:59], v[136:139], v[160:163], 0
	v_mfma_f32_16x16x32_bf16 v[44:47], v[128:131], v[186:189], 0
	v_mfma_f32_16x16x32_bf16 v[40:43], v[136:139], v[186:189], 0
	v_mfma_f32_16x16x32_bf16 v[28:31], v[128:131], v[194:197], 0
	v_mfma_f32_16x16x32_bf16 v[24:27], v[136:139], v[194:197], 0
	v_mfma_f32_16x16x32_bf16 v[12:15], v[128:131], v[202:205], 0
	v_mfma_f32_16x16x32_bf16 v[8:11], v[136:139], v[202:205], 0
	v_mfma_f32_16x16x32_bf16 v[60:63], v[132:135], v[164:167], v[60:63]
	v_mfma_f32_16x16x32_bf16 v[56:59], v[140:143], v[164:167], v[56:59]
	v_mfma_f32_16x16x32_bf16 v[44:47], v[132:135], v[190:193], v[44:47]
	v_mfma_f32_16x16x32_bf16 v[40:43], v[140:143], v[190:193], v[40:43]
	v_mfma_f32_16x16x32_bf16 v[28:31], v[132:135], v[198:201], v[28:31]
	v_mfma_f32_16x16x32_bf16 v[24:27], v[140:143], v[198:201], v[24:27]
	v_mfma_f32_16x16x32_bf16 v[12:15], v[132:135], v[206:209], v[12:15]
	v_mfma_f32_16x16x32_bf16 v[8:11], v[140:143], v[206:209], v[8:11]
	v_mfma_f32_16x16x32_bf16 v[52:55], v[144:147], v[160:163], 0
	v_mfma_f32_16x16x32_bf16 v[48:51], v[152:155], v[160:163], 0
	v_mfma_f32_16x16x32_bf16 v[36:39], v[144:147], v[186:189], 0
	v_mfma_f32_16x16x32_bf16 v[32:35], v[152:155], v[186:189], 0
	v_mfma_f32_16x16x32_bf16 v[20:23], v[144:147], v[194:197], 0
	v_mfma_f32_16x16x32_bf16 v[16:19], v[152:155], v[194:197], 0
	v_mfma_f32_16x16x32_bf16 v[4:7], v[144:147], v[202:205], 0
	v_mfma_f32_16x16x32_bf16 v[0:3], v[152:155], v[202:205], 0
	v_mfma_f32_16x16x32_bf16 v[52:55], v[148:151], v[164:167], v[52:55]
	v_mfma_f32_16x16x32_bf16 v[48:51], v[156:159], v[164:167], v[48:51]
	v_mfma_f32_16x16x32_bf16 v[36:39], v[148:151], v[190:193], v[36:39]
	v_mfma_f32_16x16x32_bf16 v[32:35], v[156:159], v[190:193], v[32:35]
	s_setprio 2
	s_barrier
	v_mfma_f32_16x16x32_bf16 v[20:23], v[148:151], v[198:201], v[20:23]
	v_mfma_f32_16x16x32_bf16 v[16:19], v[156:159], v[198:201], v[16:19]
	v_mfma_f32_16x16x32_bf16 v[4:7], v[148:151], v[206:209], v[4:7]
	v_mfma_f32_16x16x32_bf16 v[0:3], v[156:159], v[206:209], v[0:3]
	s_setprio 0
	s_mov_b32 m0, s75
	s_nop 0
	global_load_lds_dwordx4 v172, s[52:53]
	s_add_i32 s65, 0, 0x18000
	s_add_i32 s66, 0, 0x1c000
	v_add_u32_e32 v140, s65, v228
	v_add_u32_e32 v156, s66, v228
	ds_read_b128 v[128:131], v140
	ds_read_b128 v[132:135], v140 offset:1024
	ds_read_b128 v[136:139], v140 offset:2048
	ds_read_b128 v[140:143], v140 offset:3072
	ds_read_b128 v[144:147], v156
	ds_read_b128 v[148:151], v156 offset:1024
	ds_read_b128 v[152:155], v156 offset:2048
	ds_read_b128 v[156:159], v156 offset:3072
	s_add_u32 s8, s52, 0xb0000
	s_addc_u32 s9, s53, 0
	s_mov_b32 m0, s80
	ds_read_b128 v[160:163], v232 offset:32768
	ds_read_b128 v[164:167], v232 offset:33792
	ds_read_b128 v[186:189], v232 offset:34816
	ds_read_b128 v[190:193], v232 offset:35840
	ds_read_b128 v[194:197], v232 offset:36864
	ds_read_b128 v[198:201], v232 offset:37888
	ds_read_b128 v[202:205], v232 offset:38912
	ds_read_b128 v[206:209], v232 offset:39936
	global_load_lds_dwordx4 v168, s[8:9]
	s_mov_b32 m0, s81
	s_nop 0
	global_load_lds_dwordx4 v172, s[8:9]
	s_waitcnt vmcnt(8) lgkmcnt(0)
	s_barrier
	s_setprio 1
	v_mfma_f32_16x16x32_bf16 v[124:127], v[128:131], v[160:163], v[124:127]
	v_mfma_f32_16x16x32_bf16 v[120:123], v[136:139], v[160:163], v[120:123]
	v_mfma_f32_16x16x32_bf16 v[108:111], v[128:131], v[186:189], v[108:111]
	v_mfma_f32_16x16x32_bf16 v[104:107], v[136:139], v[186:189], v[104:107]
	v_mfma_f32_16x16x32_bf16 v[92:95], v[128:131], v[194:197], v[92:95]
	v_mfma_f32_16x16x32_bf16 v[88:91], v[136:139], v[194:197], v[88:91]
	v_mfma_f32_16x16x32_bf16 v[76:79], v[128:131], v[202:205], v[76:79]
	v_mfma_f32_16x16x32_bf16 v[72:75], v[136:139], v[202:205], v[72:75]
	v_mfma_f32_16x16x32_bf16 v[124:127], v[132:135], v[164:167], v[124:127]
	v_mfma_f32_16x16x32_bf16 v[120:123], v[140:143], v[164:167], v[120:123]
	v_mfma_f32_16x16x32_bf16 v[108:111], v[132:135], v[190:193], v[108:111]
	v_mfma_f32_16x16x32_bf16 v[104:107], v[140:143], v[190:193], v[104:107]
	v_mfma_f32_16x16x32_bf16 v[92:95], v[132:135], v[198:201], v[92:95]
	v_mfma_f32_16x16x32_bf16 v[88:91], v[140:143], v[198:201], v[88:91]
	v_mfma_f32_16x16x32_bf16 v[76:79], v[132:135], v[206:209], v[76:79]
	v_mfma_f32_16x16x32_bf16 v[72:75], v[140:143], v[206:209], v[72:75]
	v_mfma_f32_16x16x32_bf16 v[116:119], v[144:147], v[160:163], v[116:119]
	v_mfma_f32_16x16x32_bf16 v[112:115], v[152:155], v[160:163], v[112:115]
	v_mfma_f32_16x16x32_bf16 v[100:103], v[144:147], v[186:189], v[100:103]
	v_mfma_f32_16x16x32_bf16 v[96:99], v[152:155], v[186:189], v[96:99]
	v_mfma_f32_16x16x32_bf16 v[84:87], v[144:147], v[194:197], v[84:87]
	v_mfma_f32_16x16x32_bf16 v[80:83], v[152:155], v[194:197], v[80:83]
	v_mfma_f32_16x16x32_bf16 v[68:71], v[144:147], v[202:205], v[68:71]
	v_mfma_f32_16x16x32_bf16 v[64:67], v[152:155], v[202:205], v[64:67]
	v_mfma_f32_16x16x32_bf16 v[116:119], v[148:151], v[164:167], v[116:119]
	v_mfma_f32_16x16x32_bf16 v[112:115], v[156:159], v[164:167], v[112:115]
	v_mfma_f32_16x16x32_bf16 v[100:103], v[148:151], v[190:193], v[100:103]
	v_mfma_f32_16x16x32_bf16 v[96:99], v[156:159], v[190:193], v[96:99]
	s_setprio 2
	s_barrier
	v_mfma_f32_16x16x32_bf16 v[84:87], v[148:151], v[198:201], v[84:87]
	v_mfma_f32_16x16x32_bf16 v[80:83], v[156:159], v[198:201], v[80:83]
	v_mfma_f32_16x16x32_bf16 v[68:71], v[148:151], v[206:209], v[68:71]
	v_mfma_f32_16x16x32_bf16 v[64:67], v[156:159], v[206:209], v[64:67]
	s_setprio 0
	s_add_i32 s8, s65, s72
	s_mov_b32 m0, s8
	ds_read_b128 v[160:163], v232 offset:49152
	ds_read_b128 v[164:167], v232 offset:50176
	ds_read_b128 v[186:189], v232 offset:51200
	ds_read_b128 v[190:193], v232 offset:52224
	ds_read_b128 v[194:197], v232 offset:53248
	ds_read_b128 v[198:201], v232 offset:54272
	ds_read_b128 v[202:205], v232 offset:55296
	ds_read_b128 v[206:209], v232 offset:56320
	global_load_lds_dwordx4 v170, s[98:99]
	s_add_i32 m0, s8, 0x2000
	s_add_u32 s8, s50, 0xb0080
	s_addc_u32 s9, s51, 0
	s_add_i32 s50, s66, s72
	global_load_lds_dwordx4 v174, s[98:99]
	s_mov_b32 m0, s50
	s_nop 0
	global_load_lds_dwordx4 v170, s[8:9]
	s_add_i32 m0, s50, 0x2000
	s_nop 0
	global_load_lds_dwordx4 v174, s[8:9]
	s_mov_b32 m0, s83
	s_nop 0
	global_load_lds_dwordx4 v168, s[100:101]
	s_mov_b32 m0, s91
	s_nop 0
	global_load_lds_dwordx4 v172, s[100:101]
	s_waitcnt vmcnt(8) lgkmcnt(0)
	s_barrier
	s_setprio 1
	v_mfma_f32_16x16x32_bf16 v[60:63], v[128:131], v[160:163], v[60:63]
	v_mfma_f32_16x16x32_bf16 v[56:59], v[136:139], v[160:163], v[56:59]
	v_mfma_f32_16x16x32_bf16 v[44:47], v[128:131], v[186:189], v[44:47]
	v_mfma_f32_16x16x32_bf16 v[40:43], v[136:139], v[186:189], v[40:43]
	v_mfma_f32_16x16x32_bf16 v[28:31], v[128:131], v[194:197], v[28:31]
	v_mfma_f32_16x16x32_bf16 v[24:27], v[136:139], v[194:197], v[24:27]
	v_mfma_f32_16x16x32_bf16 v[12:15], v[128:131], v[202:205], v[12:15]
	v_mfma_f32_16x16x32_bf16 v[8:11], v[136:139], v[202:205], v[8:11]
	v_mfma_f32_16x16x32_bf16 v[60:63], v[132:135], v[164:167], v[60:63]
	v_mfma_f32_16x16x32_bf16 v[56:59], v[140:143], v[164:167], v[56:59]
	v_mfma_f32_16x16x32_bf16 v[44:47], v[132:135], v[190:193], v[44:47]
	v_mfma_f32_16x16x32_bf16 v[40:43], v[140:143], v[190:193], v[40:43]
	v_mfma_f32_16x16x32_bf16 v[28:31], v[132:135], v[198:201], v[28:31]
	v_mfma_f32_16x16x32_bf16 v[24:27], v[140:143], v[198:201], v[24:27]
	v_mfma_f32_16x16x32_bf16 v[12:15], v[132:135], v[206:209], v[12:15]
	v_mfma_f32_16x16x32_bf16 v[8:11], v[140:143], v[206:209], v[8:11]
	v_mfma_f32_16x16x32_bf16 v[52:55], v[144:147], v[160:163], v[52:55]
	v_mfma_f32_16x16x32_bf16 v[48:51], v[152:155], v[160:163], v[48:51]
	v_mfma_f32_16x16x32_bf16 v[36:39], v[144:147], v[186:189], v[36:39]
	v_mfma_f32_16x16x32_bf16 v[32:35], v[152:155], v[186:189], v[32:35]
	v_mfma_f32_16x16x32_bf16 v[20:23], v[144:147], v[194:197], v[20:23]
	v_mfma_f32_16x16x32_bf16 v[16:19], v[152:155], v[194:197], v[16:19]
	v_mfma_f32_16x16x32_bf16 v[4:7], v[144:147], v[202:205], v[4:7]
	v_mfma_f32_16x16x32_bf16 v[0:3], v[152:155], v[202:205], v[0:3]
	v_mfma_f32_16x16x32_bf16 v[52:55], v[148:151], v[164:167], v[52:55]
	v_mfma_f32_16x16x32_bf16 v[48:51], v[156:159], v[164:167], v[48:51]
	v_mfma_f32_16x16x32_bf16 v[36:39], v[148:151], v[190:193], v[36:39]
	v_mfma_f32_16x16x32_bf16 v[32:35], v[156:159], v[190:193], v[32:35]
	s_setprio 2
	s_barrier
	v_mfma_f32_16x16x32_bf16 v[20:23], v[148:151], v[198:201], v[20:23]
	v_mfma_f32_16x16x32_bf16 v[16:19], v[156:159], v[198:201], v[16:19]
	v_mfma_f32_16x16x32_bf16 v[4:7], v[148:151], v[206:209], v[4:7]
	v_mfma_f32_16x16x32_bf16 v[0:3], v[156:159], v[206:209], v[0:3]
	s_setprio 0
	s_add_u32 vcc_lo, vcc_lo, 0x100
	s_addc_u32 vcc_hi, vcc_hi, 0
	s_cmp_ge_i32 s64, s63
	s_mov_b64 s[8:9], s[40:41]
	s_mov_b32 s50, s64
	s_cbranch_scc1 .Lpeel_exit_3
.LBB0_863:
	s_add_i32 s64, s50, 2
	s_add_u32 s40, s8, 0x100
	s_addc_u32 s41, s9, 0
	s_add_i32 s65, 0, 0x10000
	s_cmp_eq_u32 s27, s50
	s_cselect_b32 s53, s29, s41
	s_cselect_b32 s52, s28, s40
	s_cselect_b32 s51, s39, vcc_hi
	s_cselect_b32 s50, s38, vcc_lo
	s_add_i32 s66, 0, 0x14000
	v_add_u32_e32 v140, s65, v228
	v_add_u32_e32 v156, s66, v228
	ds_read_b128 v[128:131], v140
	ds_read_b128 v[132:135], v140 offset:1024
	ds_read_b128 v[136:139], v140 offset:2048
	ds_read_b128 v[140:143], v140 offset:3072
	ds_read_b128 v[144:147], v156
	ds_read_b128 v[148:151], v156 offset:1024
	ds_read_b128 v[152:155], v156 offset:2048
	ds_read_b128 v[156:159], v156 offset:3072
	s_add_i32 m0, s74, 0xc000
	ds_read_b128 v[160:163], v232
	ds_read_b128 v[164:167], v232 offset:1024
	ds_read_b128 v[186:189], v232 offset:2048
	ds_read_b128 v[190:193], v232 offset:3072
	ds_read_b128 v[194:197], v232 offset:4096
	ds_read_b128 v[198:201], v232 offset:5120
	ds_read_b128 v[202:205], v232 offset:6144
	ds_read_b128 v[206:209], v232 offset:7168
	global_load_lds_dwordx4 v184, s[8:9]
	s_add_i32 m0, s74, 0xe000
	s_nop 0
	global_load_lds_dwordx4 v182, s[8:9]
	s_waitcnt vmcnt(8) lgkmcnt(0)
	s_barrier
	s_setprio 1
	v_mfma_f32_16x16x32_bf16 v[124:127], v[128:131], v[160:163], v[124:127]
	v_mfma_f32_16x16x32_bf16 v[120:123], v[136:139], v[160:163], v[120:123]
	v_mfma_f32_16x16x32_bf16 v[108:111], v[128:131], v[186:189], v[108:111]
	v_mfma_f32_16x16x32_bf16 v[104:107], v[136:139], v[186:189], v[104:107]
	v_mfma_f32_16x16x32_bf16 v[92:95], v[128:131], v[194:197], v[92:95]
	v_mfma_f32_16x16x32_bf16 v[88:91], v[136:139], v[194:197], v[88:91]
	v_mfma_f32_16x16x32_bf16 v[76:79], v[128:131], v[202:205], v[76:79]
	v_mfma_f32_16x16x32_bf16 v[72:75], v[136:139], v[202:205], v[72:75]
	v_mfma_f32_16x16x32_bf16 v[124:127], v[132:135], v[164:167], v[124:127]
	v_mfma_f32_16x16x32_bf16 v[120:123], v[140:143], v[164:167], v[120:123]
	v_mfma_f32_16x16x32_bf16 v[108:111], v[132:135], v[190:193], v[108:111]
	v_mfma_f32_16x16x32_bf16 v[104:107], v[140:143], v[190:193], v[104:107]
	v_mfma_f32_16x16x32_bf16 v[92:95], v[132:135], v[198:201], v[92:95]
	v_mfma_f32_16x16x32_bf16 v[88:91], v[140:143], v[198:201], v[88:91]
	v_mfma_f32_16x16x32_bf16 v[76:79], v[132:135], v[206:209], v[76:79]
	v_mfma_f32_16x16x32_bf16 v[72:75], v[140:143], v[206:209], v[72:75]
	v_mfma_f32_16x16x32_bf16 v[116:119], v[144:147], v[160:163], v[116:119]
	v_mfma_f32_16x16x32_bf16 v[112:115], v[152:155], v[160:163], v[112:115]
	v_mfma_f32_16x16x32_bf16 v[100:103], v[144:147], v[186:189], v[100:103]
	v_mfma_f32_16x16x32_bf16 v[96:99], v[152:155], v[186:189], v[96:99]
	v_mfma_f32_16x16x32_bf16 v[84:87], v[144:147], v[194:197], v[84:87]
	v_mfma_f32_16x16x32_bf16 v[80:83], v[152:155], v[194:197], v[80:83]
	v_mfma_f32_16x16x32_bf16 v[68:71], v[144:147], v[202:205], v[68:71]
	v_mfma_f32_16x16x32_bf16 v[64:67], v[152:155], v[202:205], v[64:67]
	v_mfma_f32_16x16x32_bf16 v[116:119], v[148:151], v[164:167], v[116:119]
	v_mfma_f32_16x16x32_bf16 v[112:115], v[156:159], v[164:167], v[112:115]
	v_mfma_f32_16x16x32_bf16 v[100:103], v[148:151], v[190:193], v[100:103]
	v_mfma_f32_16x16x32_bf16 v[96:99], v[156:159], v[190:193], v[96:99]
	s_setprio 2
	s_barrier
	v_mfma_f32_16x16x32_bf16 v[84:87], v[148:151], v[198:201], v[84:87]
	v_mfma_f32_16x16x32_bf16 v[80:83], v[156:159], v[198:201], v[80:83]
	v_mfma_f32_16x16x32_bf16 v[68:71], v[148:151], v[206:209], v[68:71]
	v_mfma_f32_16x16x32_bf16 v[64:67], v[156:159], v[206:209], v[64:67]
	s_setprio 0
	s_add_i32 s8, s65, s72
	s_add_u32 s98, s50, s34
	s_addc_u32 s99, s51, s35
	s_mov_b32 m0, s8
	ds_read_b128 v[160:163], v232 offset:16384
	ds_read_b128 v[164:167], v232 offset:17408
	ds_read_b128 v[186:189], v232 offset:18432
	ds_read_b128 v[190:193], v232 offset:19456
	ds_read_b128 v[194:197], v232 offset:20480
	ds_read_b128 v[198:201], v232 offset:21504
	ds_read_b128 v[202:205], v232 offset:22528
	ds_read_b128 v[206:209], v232 offset:23552
	global_load_lds_dwordx4 v170, s[50:51]
	s_add_i32 m0, s8, 0x2000
	s_add_u32 s8, s50, 0xb0000
	s_addc_u32 s9, s51, 0
	s_add_i32 s65, s66, s72
	global_load_lds_dwordx4 v174, s[50:51]
	s_mov_b32 m0, s65
	s_nop 0
	global_load_lds_dwordx4 v170, s[8:9]
	s_add_i32 m0, s65, 0x2000
	s_nop 0
	global_load_lds_dwordx4 v174, s[8:9]
	s_add_u32 s100, s52, s34
	s_addc_u32 s101, s53, s35
	s_mov_b32 m0, s74
	s_nop 0
	global_load_lds_dwordx4 v168, s[52:53]
	s_waitcnt vmcnt(7) lgkmcnt(0)
	s_barrier
	s_setprio 1
	v_mfma_f32_16x16x32_bf16 v[60:63], v[128:131], v[160:163], v[60:63]
	v_mfma_f32_16x16x32_bf16 v[56:59], v[136:139], v[160:163], v[56:59]
	v_mfma_f32_16x16x32_bf16 v[44:47], v[128:131], v[186:189], v[44:47]
	v_mfma_f32_16x16x32_bf16 v[40:43], v[136:139], v[186:189], v[40:43]
	v_mfma_f32_16x16x32_bf16 v[28:31], v[128:131], v[194:197], v[28:31]
	v_mfma_f32_16x16x32_bf16 v[24:27], v[136:139], v[194:197], v[24:27]
	v_mfma_f32_16x16x32_bf16 v[12:15], v[128:131], v[202:205], v[12:15]
	v_mfma_f32_16x16x32_bf16 v[8:11], v[136:139], v[202:205], v[8:11]
	v_mfma_f32_16x16x32_bf16 v[60:63], v[132:135], v[164:167], v[60:63]
	v_mfma_f32_16x16x32_bf16 v[56:59], v[140:143], v[164:167], v[56:59]
	v_mfma_f32_16x16x32_bf16 v[44:47], v[132:135], v[190:193], v[44:47]
	v_mfma_f32_16x16x32_bf16 v[40:43], v[140:143], v[190:193], v[40:43]
	v_mfma_f32_16x16x32_bf16 v[28:31], v[132:135], v[198:201], v[28:31]
	v_mfma_f32_16x16x32_bf16 v[24:27], v[140:143], v[198:201], v[24:27]
	v_mfma_f32_16x16x32_bf16 v[12:15], v[132:135], v[206:209], v[12:15]
	v_mfma_f32_16x16x32_bf16 v[8:11], v[140:143], v[206:209], v[8:11]
	v_mfma_f32_16x16x32_bf16 v[52:55], v[144:147], v[160:163], v[52:55]
	v_mfma_f32_16x16x32_bf16 v[48:51], v[152:155], v[160:163], v[48:51]
	v_mfma_f32_16x16x32_bf16 v[36:39], v[144:147], v[186:189], v[36:39]
	v_mfma_f32_16x16x32_bf16 v[32:35], v[152:155], v[186:189], v[32:35]
	v_mfma_f32_16x16x32_bf16 v[20:23], v[144:147], v[194:197], v[20:23]
	v_mfma_f32_16x16x32_bf16 v[16:19], v[152:155], v[194:197], v[16:19]
	v_mfma_f32_16x16x32_bf16 v[4:7], v[144:147], v[202:205], v[4:7]
	v_mfma_f32_16x16x32_bf16 v[0:3], v[152:155], v[202:205], v[0:3]
	v_mfma_f32_16x16x32_bf16 v[52:55], v[148:151], v[164:167], v[52:55]
	v_mfma_f32_16x16x32_bf16 v[48:51], v[156:159], v[164:167], v[48:51]
	v_mfma_f32_16x16x32_bf16 v[36:39], v[148:151], v[190:193], v[36:39]
	v_mfma_f32_16x16x32_bf16 v[32:35], v[156:159], v[190:193], v[32:35]
	s_setprio 2
	s_barrier
	v_mfma_f32_16x16x32_bf16 v[20:23], v[148:151], v[198:201], v[20:23]
	v_mfma_f32_16x16x32_bf16 v[16:19], v[156:159], v[198:201], v[16:19]
	v_mfma_f32_16x16x32_bf16 v[4:7], v[148:151], v[206:209], v[4:7]
	v_mfma_f32_16x16x32_bf16 v[0:3], v[156:159], v[206:209], v[0:3]
	s_setprio 0
	s_mov_b32 m0, s75
	s_nop 0
	global_load_lds_dwordx4 v172, s[52:53]
	s_add_i32 s65, 0, 0x18000
	s_add_i32 s66, 0, 0x1c000
	v_add_u32_e32 v140, s65, v228
	v_add_u32_e32 v156, s66, v228
	ds_read_b128 v[128:131], v140
	ds_read_b128 v[132:135], v140 offset:1024
	ds_read_b128 v[136:139], v140 offset:2048
	ds_read_b128 v[140:143], v140 offset:3072
	ds_read_b128 v[144:147], v156
	ds_read_b128 v[148:151], v156 offset:1024
	ds_read_b128 v[152:155], v156 offset:2048
	ds_read_b128 v[156:159], v156 offset:3072
	s_add_u32 s8, s52, 0xb0000
	s_addc_u32 s9, s53, 0
	s_mov_b32 m0, s80
	ds_read_b128 v[160:163], v232 offset:32768
	ds_read_b128 v[164:167], v232 offset:33792
	ds_read_b128 v[186:189], v232 offset:34816
	ds_read_b128 v[190:193], v232 offset:35840
	ds_read_b128 v[194:197], v232 offset:36864
	ds_read_b128 v[198:201], v232 offset:37888
	ds_read_b128 v[202:205], v232 offset:38912
	ds_read_b128 v[206:209], v232 offset:39936
	global_load_lds_dwordx4 v168, s[8:9]
	s_mov_b32 m0, s81
	s_nop 0
	global_load_lds_dwordx4 v172, s[8:9]
	s_waitcnt vmcnt(8) lgkmcnt(0)
	s_barrier
	s_setprio 1
	v_mfma_f32_16x16x32_bf16 v[124:127], v[128:131], v[160:163], v[124:127]
	v_mfma_f32_16x16x32_bf16 v[120:123], v[136:139], v[160:163], v[120:123]
	v_mfma_f32_16x16x32_bf16 v[108:111], v[128:131], v[186:189], v[108:111]
	v_mfma_f32_16x16x32_bf16 v[104:107], v[136:139], v[186:189], v[104:107]
	v_mfma_f32_16x16x32_bf16 v[92:95], v[128:131], v[194:197], v[92:95]
	v_mfma_f32_16x16x32_bf16 v[88:91], v[136:139], v[194:197], v[88:91]
	v_mfma_f32_16x16x32_bf16 v[76:79], v[128:131], v[202:205], v[76:79]
	v_mfma_f32_16x16x32_bf16 v[72:75], v[136:139], v[202:205], v[72:75]
	v_mfma_f32_16x16x32_bf16 v[124:127], v[132:135], v[164:167], v[124:127]
	v_mfma_f32_16x16x32_bf16 v[120:123], v[140:143], v[164:167], v[120:123]
	v_mfma_f32_16x16x32_bf16 v[108:111], v[132:135], v[190:193], v[108:111]
	v_mfma_f32_16x16x32_bf16 v[104:107], v[140:143], v[190:193], v[104:107]
	v_mfma_f32_16x16x32_bf16 v[92:95], v[132:135], v[198:201], v[92:95]
	v_mfma_f32_16x16x32_bf16 v[88:91], v[140:143], v[198:201], v[88:91]
	v_mfma_f32_16x16x32_bf16 v[76:79], v[132:135], v[206:209], v[76:79]
	v_mfma_f32_16x16x32_bf16 v[72:75], v[140:143], v[206:209], v[72:75]
	v_mfma_f32_16x16x32_bf16 v[116:119], v[144:147], v[160:163], v[116:119]
	v_mfma_f32_16x16x32_bf16 v[112:115], v[152:155], v[160:163], v[112:115]
	v_mfma_f32_16x16x32_bf16 v[100:103], v[144:147], v[186:189], v[100:103]
	v_mfma_f32_16x16x32_bf16 v[96:99], v[152:155], v[186:189], v[96:99]
	v_mfma_f32_16x16x32_bf16 v[84:87], v[144:147], v[194:197], v[84:87]
	v_mfma_f32_16x16x32_bf16 v[80:83], v[152:155], v[194:197], v[80:83]
	v_mfma_f32_16x16x32_bf16 v[68:71], v[144:147], v[202:205], v[68:71]
	v_mfma_f32_16x16x32_bf16 v[64:67], v[152:155], v[202:205], v[64:67]
	v_mfma_f32_16x16x32_bf16 v[116:119], v[148:151], v[164:167], v[116:119]
	v_mfma_f32_16x16x32_bf16 v[112:115], v[156:159], v[164:167], v[112:115]
	v_mfma_f32_16x16x32_bf16 v[100:103], v[148:151], v[190:193], v[100:103]
	v_mfma_f32_16x16x32_bf16 v[96:99], v[156:159], v[190:193], v[96:99]
	s_setprio 2
	s_barrier
	v_mfma_f32_16x16x32_bf16 v[84:87], v[148:151], v[198:201], v[84:87]
	v_mfma_f32_16x16x32_bf16 v[80:83], v[156:159], v[198:201], v[80:83]
	v_mfma_f32_16x16x32_bf16 v[68:71], v[148:151], v[206:209], v[68:71]
	v_mfma_f32_16x16x32_bf16 v[64:67], v[156:159], v[206:209], v[64:67]
	s_setprio 0
	s_add_i32 s8, s65, s72
	s_mov_b32 m0, s8
	ds_read_b128 v[160:163], v232 offset:49152
	ds_read_b128 v[164:167], v232 offset:50176
	ds_read_b128 v[186:189], v232 offset:51200
	ds_read_b128 v[190:193], v232 offset:52224
	ds_read_b128 v[194:197], v232 offset:53248
	ds_read_b128 v[198:201], v232 offset:54272
	ds_read_b128 v[202:205], v232 offset:55296
	ds_read_b128 v[206:209], v232 offset:56320
	global_load_lds_dwordx4 v170, s[98:99]
	s_add_i32 m0, s8, 0x2000
	s_add_u32 s8, s50, 0xb0080
	s_addc_u32 s9, s51, 0
	s_add_i32 s50, s66, s72
	global_load_lds_dwordx4 v174, s[98:99]
	s_mov_b32 m0, s50
	s_nop 0
	global_load_lds_dwordx4 v170, s[8:9]
	s_add_i32 m0, s50, 0x2000
	s_nop 0
	global_load_lds_dwordx4 v174, s[8:9]
	s_mov_b32 m0, s83
	s_nop 0
	global_load_lds_dwordx4 v168, s[100:101]
	s_mov_b32 m0, s91
	s_nop 0
	global_load_lds_dwordx4 v172, s[100:101]
	s_waitcnt vmcnt(8) lgkmcnt(0)
	s_barrier
	s_setprio 1
	v_mfma_f32_16x16x32_bf16 v[60:63], v[128:131], v[160:163], v[60:63]
	v_mfma_f32_16x16x32_bf16 v[56:59], v[136:139], v[160:163], v[56:59]
	v_mfma_f32_16x16x32_bf16 v[44:47], v[128:131], v[186:189], v[44:47]
	v_mfma_f32_16x16x32_bf16 v[40:43], v[136:139], v[186:189], v[40:43]
	v_mfma_f32_16x16x32_bf16 v[28:31], v[128:131], v[194:197], v[28:31]
	v_mfma_f32_16x16x32_bf16 v[24:27], v[136:139], v[194:197], v[24:27]
	v_mfma_f32_16x16x32_bf16 v[12:15], v[128:131], v[202:205], v[12:15]
	v_mfma_f32_16x16x32_bf16 v[8:11], v[136:139], v[202:205], v[8:11]
	v_mfma_f32_16x16x32_bf16 v[60:63], v[132:135], v[164:167], v[60:63]
	v_mfma_f32_16x16x32_bf16 v[56:59], v[140:143], v[164:167], v[56:59]
	v_mfma_f32_16x16x32_bf16 v[44:47], v[132:135], v[190:193], v[44:47]
	v_mfma_f32_16x16x32_bf16 v[40:43], v[140:143], v[190:193], v[40:43]
	v_mfma_f32_16x16x32_bf16 v[28:31], v[132:135], v[198:201], v[28:31]
	v_mfma_f32_16x16x32_bf16 v[24:27], v[140:143], v[198:201], v[24:27]
	v_mfma_f32_16x16x32_bf16 v[12:15], v[132:135], v[206:209], v[12:15]
	v_mfma_f32_16x16x32_bf16 v[8:11], v[140:143], v[206:209], v[8:11]
	v_mfma_f32_16x16x32_bf16 v[52:55], v[144:147], v[160:163], v[52:55]
	v_mfma_f32_16x16x32_bf16 v[48:51], v[152:155], v[160:163], v[48:51]
	v_mfma_f32_16x16x32_bf16 v[36:39], v[144:147], v[186:189], v[36:39]
	v_mfma_f32_16x16x32_bf16 v[32:35], v[152:155], v[186:189], v[32:35]
	v_mfma_f32_16x16x32_bf16 v[20:23], v[144:147], v[194:197], v[20:23]
	v_mfma_f32_16x16x32_bf16 v[16:19], v[152:155], v[194:197], v[16:19]
	v_mfma_f32_16x16x32_bf16 v[4:7], v[144:147], v[202:205], v[4:7]
	v_mfma_f32_16x16x32_bf16 v[0:3], v[152:155], v[202:205], v[0:3]
	v_mfma_f32_16x16x32_bf16 v[52:55], v[148:151], v[164:167], v[52:55]
	v_mfma_f32_16x16x32_bf16 v[48:51], v[156:159], v[164:167], v[48:51]
	v_mfma_f32_16x16x32_bf16 v[36:39], v[148:151], v[190:193], v[36:39]
	v_mfma_f32_16x16x32_bf16 v[32:35], v[156:159], v[190:193], v[32:35]
	s_setprio 2
	s_barrier
	v_mfma_f32_16x16x32_bf16 v[20:23], v[148:151], v[198:201], v[20:23]
	v_mfma_f32_16x16x32_bf16 v[16:19], v[156:159], v[198:201], v[16:19]
	v_mfma_f32_16x16x32_bf16 v[4:7], v[148:151], v[206:209], v[4:7]
	v_mfma_f32_16x16x32_bf16 v[0:3], v[156:159], v[206:209], v[0:3]
	s_setprio 0
	s_add_u32 vcc_lo, vcc_lo, 0x100
	s_addc_u32 vcc_hi, vcc_hi, 0
	s_cmp_ge_i32 s64, s63
	s_mov_b64 s[8:9], s[40:41]
	s_mov_b32 s50, s64
	s_cbranch_scc0 .LBB0_863

.LBB0_952:
	s_add_u32 s44, s38, 0x180
	s_addc_u32 s53, s39, 0
	s_mov_b32 s83, -2
	s_add_u32 s38, s8, 0x180
	s_addc_u32 s39, s9, 0
	s_add_i32 s64, 0, 0x10000
	s_cmp_eq_u32 s83, 12
	s_cselect_b32 s51, s1, s39
	s_cselect_b32 s50, s0, s38
	s_cselect_b32 s41, s29, s53
	s_cselect_b32 s40, s28, s44
	s_add_i32 s65, 0, 0x14000
	v_add_u32_e32 v68, s64, v228
	v_add_u32_e32 v156, s65, v228
	ds_read_b128 v[56:59], v68
	ds_read_b128 v[60:63], v68 offset:1024
	ds_read_b128 v[64:67], v68 offset:2048
	ds_read_b128 v[68:71], v68 offset:3072
	ds_read_b128 v[144:147], v156
	ds_read_b128 v[148:151], v156 offset:1024
	ds_read_b128 v[152:155], v156 offset:2048
	ds_read_b128 v[156:159], v156 offset:3072
	s_add_i32 m0, s60, 0xc000
	ds_read_b128 v[160:163], v231
	ds_read_b128 v[164:167], v231 offset:1024
	ds_read_b128 v[168:171], v231 offset:2048
	ds_read_b128 v[172:175], v231 offset:3072
	ds_read_b128 v[194:197], v231 offset:4096
	ds_read_b128 v[198:201], v231 offset:5120
	ds_read_b128 v[202:205], v231 offset:6144
	ds_read_b128 v[206:209], v231 offset:7168
	global_load_lds_dwordx4 v192, s[8:9]
	s_add_i32 m0, s60, 0xe000
	s_nop 0
	global_load_lds_dwordx4 v190, s[8:9]
	s_waitcnt vmcnt(24) lgkmcnt(0)
	s_barrier
	s_setprio 1
	v_mfma_f32_16x16x32_bf16 v[140:143], v[56:59], v[160:163], 0
	v_mfma_f32_16x16x32_bf16 v[136:139], v[64:67], v[160:163], 0
	v_mfma_f32_16x16x32_bf16 v[128:131], v[56:59], v[168:171], 0
	v_mfma_f32_16x16x32_bf16 v[120:123], v[64:67], v[168:171], 0
	v_mfma_f32_16x16x32_bf16 v[108:111], v[56:59], v[194:197], 0
	v_mfma_f32_16x16x32_bf16 v[104:107], v[64:67], v[194:197], 0
	v_mfma_f32_16x16x32_bf16 v[92:95], v[56:59], v[202:205], 0
	v_mfma_f32_16x16x32_bf16 v[88:91], v[64:67], v[202:205], 0
	v_mfma_f32_16x16x32_bf16 v[140:143], v[60:63], v[164:167], v[140:143]
	v_mfma_f32_16x16x32_bf16 v[136:139], v[68:71], v[164:167], v[136:139]
	v_mfma_f32_16x16x32_bf16 v[128:131], v[60:63], v[172:175], v[128:131]
	v_mfma_f32_16x16x32_bf16 v[120:123], v[68:71], v[172:175], v[120:123]
	v_mfma_f32_16x16x32_bf16 v[108:111], v[60:63], v[198:201], v[108:111]
	v_mfma_f32_16x16x32_bf16 v[104:107], v[68:71], v[198:201], v[104:107]
	v_mfma_f32_16x16x32_bf16 v[92:95], v[60:63], v[206:209], v[92:95]
	v_mfma_f32_16x16x32_bf16 v[88:91], v[68:71], v[206:209], v[88:91]
	v_mfma_f32_16x16x32_bf16 v[132:135], v[144:147], v[160:163], 0
	v_mfma_f32_16x16x32_bf16 v[124:127], v[152:155], v[160:163], 0
	v_mfma_f32_16x16x32_bf16 v[116:119], v[144:147], v[168:171], 0
	v_mfma_f32_16x16x32_bf16 v[112:115], v[152:155], v[168:171], 0
	v_mfma_f32_16x16x32_bf16 v[100:103], v[144:147], v[194:197], 0
	v_mfma_f32_16x16x32_bf16 v[96:99], v[152:155], v[194:197], 0
	v_mfma_f32_16x16x32_bf16 v[84:87], v[144:147], v[202:205], 0
	v_mfma_f32_16x16x32_bf16 v[80:83], v[152:155], v[202:205], 0
	v_mfma_f32_16x16x32_bf16 v[132:135], v[148:151], v[164:167], v[132:135]
	v_mfma_f32_16x16x32_bf16 v[124:127], v[156:159], v[164:167], v[124:127]
	v_mfma_f32_16x16x32_bf16 v[116:119], v[148:151], v[172:175], v[116:119]
	v_mfma_f32_16x16x32_bf16 v[112:115], v[156:159], v[172:175], v[112:115]
	s_setprio 2
	s_barrier
	v_mfma_f32_16x16x32_bf16 v[100:103], v[148:151], v[198:201], v[100:103]
	v_mfma_f32_16x16x32_bf16 v[96:99], v[156:159], v[198:201], v[96:99]
	v_mfma_f32_16x16x32_bf16 v[84:87], v[148:151], v[206:209], v[84:87]
	v_mfma_f32_16x16x32_bf16 v[80:83], v[156:159], v[206:209], v[80:83]
	s_setprio 0
	s_add_i32 s8, s64, s37
	s_add_u32 s98, s40, s34
	s_addc_u32 s99, s41, s35
	s_mov_b32 m0, s8
	ds_read_b128 v[160:163], v231 offset:16384
	ds_read_b128 v[164:167], v231 offset:17408
	ds_read_b128 v[168:171], v231 offset:18432
	ds_read_b128 v[172:175], v231 offset:19456
	ds_read_b128 v[194:197], v231 offset:20480
	ds_read_b128 v[198:201], v231 offset:21504
	ds_read_b128 v[202:205], v231 offset:22528
	ds_read_b128 v[206:209], v231 offset:23552
	global_load_lds_dwordx4 v184, s[40:41]
	s_add_i32 m0, s8, 0x2000
	s_add_u32 s8, s40, 0x60000
	s_addc_u32 s9, s41, 0
	s_add_i32 s64, s65, s37
	global_load_lds_dwordx4 v188, s[40:41]
	s_mov_b32 m0, s64
	s_nop 0
	global_load_lds_dwordx4 v184, s[8:9]
	s_add_i32 m0, s64, 0x2000
	s_nop 0
	global_load_lds_dwordx4 v188, s[8:9]
	s_add_u32 s100, s50, s34
	s_addc_u32 s101, s51, s35
	s_mov_b32 m0, s60
	s_nop 0
	global_load_lds_dwordx4 v182, s[50:51]
	s_waitcnt vmcnt(7) lgkmcnt(0)
	s_barrier
	s_setprio 1
	v_mfma_f32_16x16x32_bf16 v[76:79], v[56:59], v[160:163], 0
	v_mfma_f32_16x16x32_bf16 v[72:75], v[64:67], v[160:163], 0
	v_mfma_f32_16x16x32_bf16 v[44:47], v[56:59], v[168:171], 0
	v_mfma_f32_16x16x32_bf16 v[40:43], v[64:67], v[168:171], 0
	v_mfma_f32_16x16x32_bf16 v[28:31], v[56:59], v[194:197], 0
	v_mfma_f32_16x16x32_bf16 v[24:27], v[64:67], v[194:197], 0
	v_mfma_f32_16x16x32_bf16 v[12:15], v[56:59], v[202:205], 0
	v_mfma_f32_16x16x32_bf16 v[8:11], v[64:67], v[202:205], 0
	v_mfma_f32_16x16x32_bf16 v[76:79], v[60:63], v[164:167], v[76:79]
	v_mfma_f32_16x16x32_bf16 v[72:75], v[68:71], v[164:167], v[72:75]
	v_mfma_f32_16x16x32_bf16 v[44:47], v[60:63], v[172:175], v[44:47]
	v_mfma_f32_16x16x32_bf16 v[40:43], v[68:71], v[172:175], v[40:43]
	v_mfma_f32_16x16x32_bf16 v[28:31], v[60:63], v[198:201], v[28:31]
	v_mfma_f32_16x16x32_bf16 v[24:27], v[68:71], v[198:201], v[24:27]
	v_mfma_f32_16x16x32_bf16 v[12:15], v[60:63], v[206:209], v[12:15]
	v_mfma_f32_16x16x32_bf16 v[8:11], v[68:71], v[206:209], v[8:11]
	v_mfma_f32_16x16x32_bf16 v[52:55], v[144:147], v[160:163], 0
	v_mfma_f32_16x16x32_bf16 v[48:51], v[152:155], v[160:163], 0
	v_mfma_f32_16x16x32_bf16 v[36:39], v[144:147], v[168:171], 0
	v_mfma_f32_16x16x32_bf16 v[32:35], v[152:155], v[168:171], 0
	v_mfma_f32_16x16x32_bf16 v[20:23], v[144:147], v[194:197], 0
	v_mfma_f32_16x16x32_bf16 v[16:19], v[152:155], v[194:197], 0
	v_mfma_f32_16x16x32_bf16 v[4:7], v[144:147], v[202:205], 0
	v_mfma_f32_16x16x32_bf16 v[0:3], v[152:155], v[202:205], 0
	v_mfma_f32_16x16x32_bf16 v[52:55], v[148:151], v[164:167], v[52:55]
	v_mfma_f32_16x16x32_bf16 v[48:51], v[156:159], v[164:167], v[48:51]
	v_mfma_f32_16x16x32_bf16 v[36:39], v[148:151], v[172:175], v[36:39]
	v_mfma_f32_16x16x32_bf16 v[32:35], v[156:159], v[172:175], v[32:35]
	s_setprio 2
	s_barrier
	v_mfma_f32_16x16x32_bf16 v[20:23], v[148:151], v[198:201], v[20:23]
	v_mfma_f32_16x16x32_bf16 v[16:19], v[156:159], v[198:201], v[16:19]
	v_mfma_f32_16x16x32_bf16 v[4:7], v[148:151], v[206:209], v[4:7]
	v_mfma_f32_16x16x32_bf16 v[0:3], v[156:159], v[206:209], v[0:3]
	s_setprio 0
	s_mov_b32 m0, s61
	s_nop 0
	global_load_lds_dwordx4 v186, s[50:51]
	s_add_i32 s64, 0, 0x18000
	s_add_i32 s65, 0, 0x1c000
	v_add_u32_e32 v68, s64, v228
	v_add_u32_e32 v156, s65, v228
	ds_read_b128 v[56:59], v68
	ds_read_b128 v[60:63], v68 offset:1024
	ds_read_b128 v[64:67], v68 offset:2048
	ds_read_b128 v[68:71], v68 offset:3072
	ds_read_b128 v[144:147], v156
	ds_read_b128 v[148:151], v156 offset:1024
	ds_read_b128 v[152:155], v156 offset:2048
	ds_read_b128 v[156:159], v156 offset:3072
	s_add_u32 s8, s50, 0x60000
	s_addc_u32 s9, s51, 0
	s_mov_b32 m0, s62
	ds_read_b128 v[160:163], v231 offset:32768
	ds_read_b128 v[164:167], v231 offset:33792
	ds_read_b128 v[168:171], v231 offset:34816
	ds_read_b128 v[172:175], v231 offset:35840
	ds_read_b128 v[194:197], v231 offset:36864
	ds_read_b128 v[198:201], v231 offset:37888
	ds_read_b128 v[202:205], v231 offset:38912
	ds_read_b128 v[206:209], v231 offset:39936
	global_load_lds_dwordx4 v182, s[8:9]
	s_mov_b32 m0, s63
	s_nop 0
	global_load_lds_dwordx4 v186, s[8:9]
	s_waitcnt vmcnt(8) lgkmcnt(0)
	s_barrier
	s_setprio 1
	v_mfma_f32_16x16x32_bf16 v[140:143], v[56:59], v[160:163], v[140:143]
	v_mfma_f32_16x16x32_bf16 v[136:139], v[64:67], v[160:163], v[136:139]
	v_mfma_f32_16x16x32_bf16 v[128:131], v[56:59], v[168:171], v[128:131]
	v_mfma_f32_16x16x32_bf16 v[120:123], v[64:67], v[168:171], v[120:123]
	v_mfma_f32_16x16x32_bf16 v[108:111], v[56:59], v[194:197], v[108:111]
	v_mfma_f32_16x16x32_bf16 v[104:107], v[64:67], v[194:197], v[104:107]
	v_mfma_f32_16x16x32_bf16 v[92:95], v[56:59], v[202:205], v[92:95]
	v_mfma_f32_16x16x32_bf16 v[88:91], v[64:67], v[202:205], v[88:91]
	v_mfma_f32_16x16x32_bf16 v[140:143], v[60:63], v[164:167], v[140:143]
	v_mfma_f32_16x16x32_bf16 v[136:139], v[68:71], v[164:167], v[136:139]
	v_mfma_f32_16x16x32_bf16 v[128:131], v[60:63], v[172:175], v[128:131]
	v_mfma_f32_16x16x32_bf16 v[120:123], v[68:71], v[172:175], v[120:123]
	v_mfma_f32_16x16x32_bf16 v[108:111], v[60:63], v[198:201], v[108:111]
	v_mfma_f32_16x16x32_bf16 v[104:107], v[68:71], v[198:201], v[104:107]
	v_mfma_f32_16x16x32_bf16 v[92:95], v[60:63], v[206:209], v[92:95]
	v_mfma_f32_16x16x32_bf16 v[88:91], v[68:71], v[206:209], v[88:91]
	v_mfma_f32_16x16x32_bf16 v[132:135], v[144:147], v[160:163], v[132:135]
	v_mfma_f32_16x16x32_bf16 v[124:127], v[152:155], v[160:163], v[124:127]
	v_mfma_f32_16x16x32_bf16 v[116:119], v[144:147], v[168:171], v[116:119]
	v_mfma_f32_16x16x32_bf16 v[112:115], v[152:155], v[168:171], v[112:115]
	v_mfma_f32_16x16x32_bf16 v[100:103], v[144:147], v[194:197], v[100:103]
	v_mfma_f32_16x16x32_bf16 v[96:99], v[152:155], v[194:197], v[96:99]
	v_mfma_f32_16x16x32_bf16 v[84:87], v[144:147], v[202:205], v[84:87]
	v_mfma_f32_16x16x32_bf16 v[80:83], v[152:155], v[202:205], v[80:83]
	v_mfma_f32_16x16x32_bf16 v[132:135], v[148:151], v[164:167], v[132:135]
	v_mfma_f32_16x16x32_bf16 v[124:127], v[156:159], v[164:167], v[124:127]
	v_mfma_f32_16x16x32_bf16 v[116:119], v[148:151], v[172:175], v[116:119]
	v_mfma_f32_16x16x32_bf16 v[112:115], v[156:159], v[172:175], v[112:115]
	s_setprio 2
	s_barrier
	v_mfma_f32_16x16x32_bf16 v[100:103], v[148:151], v[198:201], v[100:103]
	v_mfma_f32_16x16x32_bf16 v[96:99], v[156:159], v[198:201], v[96:99]
	v_mfma_f32_16x16x32_bf16 v[84:87], v[148:151], v[206:209], v[84:87]
	v_mfma_f32_16x16x32_bf16 v[80:83], v[156:159], v[206:209], v[80:83]
	s_setprio 0
	s_add_i32 s8, s64, s37
	s_mov_b32 m0, s8
	ds_read_b128 v[160:163], v231 offset:49152
	ds_read_b128 v[164:167], v231 offset:50176
	ds_read_b128 v[168:171], v231 offset:51200
	ds_read_b128 v[172:175], v231 offset:52224
	ds_read_b128 v[194:197], v231 offset:53248
	ds_read_b128 v[198:201], v231 offset:54272
	ds_read_b128 v[202:205], v231 offset:55296
	ds_read_b128 v[206:209], v231 offset:56320
	global_load_lds_dwordx4 v184, s[98:99]
	s_add_i32 m0, s8, 0x2000
	s_add_u32 s8, s40, 0x60080
	s_addc_u32 s9, s41, 0
	s_add_i32 s40, s65, s37
	global_load_lds_dwordx4 v188, s[98:99]
	s_mov_b32 m0, s40
	s_nop 0
	global_load_lds_dwordx4 v184, s[8:9]
	s_add_i32 m0, s40, 0x2000
	s_nop 0
	global_load_lds_dwordx4 v188, s[8:9]
	s_mov_b32 m0, s69
	s_nop 0
	global_load_lds_dwordx4 v182, s[100:101]
	s_mov_b32 m0, s72
	s_nop 0
	global_load_lds_dwordx4 v186, s[100:101]
	s_waitcnt vmcnt(8) lgkmcnt(0)
	s_barrier
	s_setprio 1
	v_mfma_f32_16x16x32_bf16 v[76:79], v[56:59], v[160:163], v[76:79]
	v_mfma_f32_16x16x32_bf16 v[72:75], v[64:67], v[160:163], v[72:75]
	v_mfma_f32_16x16x32_bf16 v[44:47], v[56:59], v[168:171], v[44:47]
	v_mfma_f32_16x16x32_bf16 v[40:43], v[64:67], v[168:171], v[40:43]
	v_mfma_f32_16x16x32_bf16 v[28:31], v[56:59], v[194:197], v[28:31]
	v_mfma_f32_16x16x32_bf16 v[24:27], v[64:67], v[194:197], v[24:27]
	v_mfma_f32_16x16x32_bf16 v[12:15], v[56:59], v[202:205], v[12:15]
	v_mfma_f32_16x16x32_bf16 v[8:11], v[64:67], v[202:205], v[8:11]
	v_mfma_f32_16x16x32_bf16 v[76:79], v[60:63], v[164:167], v[76:79]
	v_mfma_f32_16x16x32_bf16 v[72:75], v[68:71], v[164:167], v[72:75]
	v_mfma_f32_16x16x32_bf16 v[44:47], v[60:63], v[172:175], v[44:47]
	v_mfma_f32_16x16x32_bf16 v[40:43], v[68:71], v[172:175], v[40:43]
	v_mfma_f32_16x16x32_bf16 v[28:31], v[60:63], v[198:201], v[28:31]
	v_mfma_f32_16x16x32_bf16 v[24:27], v[68:71], v[198:201], v[24:27]
	v_mfma_f32_16x16x32_bf16 v[12:15], v[60:63], v[206:209], v[12:15]
	v_mfma_f32_16x16x32_bf16 v[8:11], v[68:71], v[206:209], v[8:11]
	v_mfma_f32_16x16x32_bf16 v[52:55], v[144:147], v[160:163], v[52:55]
	v_mfma_f32_16x16x32_bf16 v[48:51], v[152:155], v[160:163], v[48:51]
	v_mfma_f32_16x16x32_bf16 v[36:39], v[144:147], v[168:171], v[36:39]
	v_mfma_f32_16x16x32_bf16 v[32:35], v[152:155], v[168:171], v[32:35]
	v_mfma_f32_16x16x32_bf16 v[20:23], v[144:147], v[194:197], v[20:23]
	v_mfma_f32_16x16x32_bf16 v[16:19], v[152:155], v[194:197], v[16:19]
	v_mfma_f32_16x16x32_bf16 v[4:7], v[144:147], v[202:205], v[4:7]
	v_mfma_f32_16x16x32_bf16 v[0:3], v[152:155], v[202:205], v[0:3]
	v_mfma_f32_16x16x32_bf16 v[52:55], v[148:151], v[164:167], v[52:55]
	v_mfma_f32_16x16x32_bf16 v[48:51], v[156:159], v[164:167], v[48:51]
	v_mfma_f32_16x16x32_bf16 v[36:39], v[148:151], v[172:175], v[36:39]
	v_mfma_f32_16x16x32_bf16 v[32:35], v[156:159], v[172:175], v[32:35]
	s_setprio 2
	s_barrier
	v_mfma_f32_16x16x32_bf16 v[20:23], v[148:151], v[198:201], v[20:23]
	v_mfma_f32_16x16x32_bf16 v[16:19], v[156:159], v[198:201], v[16:19]
	v_mfma_f32_16x16x32_bf16 v[4:7], v[148:151], v[206:209], v[4:7]
	v_mfma_f32_16x16x32_bf16 v[0:3], v[156:159], v[206:209], v[0:3]
	s_setprio 0
	s_add_i32 s83, s83, 2
	s_add_u32 s44, s44, 0x180
	s_addc_u32 s53, s53, 0
	s_cmp_gt_u32 s83, 13
	s_mov_b64 s[8:9], s[38:39]
	s_cbranch_scc1 .Lpeel_exit_4
.LBB0_953:
	s_add_u32 s38, s8, 0x180
	s_addc_u32 s39, s9, 0
	s_add_i32 s64, 0, 0x10000
	s_cmp_eq_u32 s83, 12
	s_cselect_b32 s51, s1, s39
	s_cselect_b32 s50, s0, s38
	s_cselect_b32 s41, s29, s53
	s_cselect_b32 s40, s28, s44
	s_add_i32 s65, 0, 0x14000
	v_add_u32_e32 v68, s64, v228
	v_add_u32_e32 v156, s65, v228
	ds_read_b128 v[56:59], v68
	ds_read_b128 v[60:63], v68 offset:1024
	ds_read_b128 v[64:67], v68 offset:2048
	ds_read_b128 v[68:71], v68 offset:3072
	ds_read_b128 v[144:147], v156
	ds_read_b128 v[148:151], v156 offset:1024
	ds_read_b128 v[152:155], v156 offset:2048
	ds_read_b128 v[156:159], v156 offset:3072
	s_add_i32 m0, s60, 0xc000
	ds_read_b128 v[160:163], v231
	ds_read_b128 v[164:167], v231 offset:1024
	ds_read_b128 v[168:171], v231 offset:2048
	ds_read_b128 v[172:175], v231 offset:3072
	ds_read_b128 v[194:197], v231 offset:4096
	ds_read_b128 v[198:201], v231 offset:5120
	ds_read_b128 v[202:205], v231 offset:6144
	ds_read_b128 v[206:209], v231 offset:7168
	global_load_lds_dwordx4 v192, s[8:9]
	s_add_i32 m0, s60, 0xe000
	s_nop 0
	global_load_lds_dwordx4 v190, s[8:9]
	s_waitcnt vmcnt(8) lgkmcnt(0)
	s_barrier
	s_setprio 1
	v_mfma_f32_16x16x32_bf16 v[140:143], v[56:59], v[160:163], v[140:143]
	v_mfma_f32_16x16x32_bf16 v[136:139], v[64:67], v[160:163], v[136:139]
	v_mfma_f32_16x16x32_bf16 v[128:131], v[56:59], v[168:171], v[128:131]
	v_mfma_f32_16x16x32_bf16 v[120:123], v[64:67], v[168:171], v[120:123]
	v_mfma_f32_16x16x32_bf16 v[108:111], v[56:59], v[194:197], v[108:111]
	v_mfma_f32_16x16x32_bf16 v[104:107], v[64:67], v[194:197], v[104:107]
	v_mfma_f32_16x16x32_bf16 v[92:95], v[56:59], v[202:205], v[92:95]
	v_mfma_f32_16x16x32_bf16 v[88:91], v[64:67], v[202:205], v[88:91]
	v_mfma_f32_16x16x32_bf16 v[140:143], v[60:63], v[164:167], v[140:143]
	v_mfma_f32_16x16x32_bf16 v[136:139], v[68:71], v[164:167], v[136:139]
	v_mfma_f32_16x16x32_bf16 v[128:131], v[60:63], v[172:175], v[128:131]
	v_mfma_f32_16x16x32_bf16 v[120:123], v[68:71], v[172:175], v[120:123]
	v_mfma_f32_16x16x32_bf16 v[108:111], v[60:63], v[198:201], v[108:111]
	v_mfma_f32_16x16x32_bf16 v[104:107], v[68:71], v[198:201], v[104:107]
	v_mfma_f32_16x16x32_bf16 v[92:95], v[60:63], v[206:209], v[92:95]
	v_mfma_f32_16x16x32_bf16 v[88:91], v[68:71], v[206:209], v[88:91]
	v_mfma_f32_16x16x32_bf16 v[132:135], v[144:147], v[160:163], v[132:135]
	v_mfma_f32_16x16x32_bf16 v[124:127], v[152:155], v[160:163], v[124:127]
	v_mfma_f32_16x16x32_bf16 v[116:119], v[144:147], v[168:171], v[116:119]
	v_mfma_f32_16x16x32_bf16 v[112:115], v[152:155], v[168:171], v[112:115]
	v_mfma_f32_16x16x32_bf16 v[100:103], v[144:147], v[194:197], v[100:103]
	v_mfma_f32_16x16x32_bf16 v[96:99], v[152:155], v[194:197], v[96:99]
	v_mfma_f32_16x16x32_bf16 v[84:87], v[144:147], v[202:205], v[84:87]
	v_mfma_f32_16x16x32_bf16 v[80:83], v[152:155], v[202:205], v[80:83]
	v_mfma_f32_16x16x32_bf16 v[132:135], v[148:151], v[164:167], v[132:135]
	v_mfma_f32_16x16x32_bf16 v[124:127], v[156:159], v[164:167], v[124:127]
	v_mfma_f32_16x16x32_bf16 v[116:119], v[148:151], v[172:175], v[116:119]
	v_mfma_f32_16x16x32_bf16 v[112:115], v[156:159], v[172:175], v[112:115]
	s_setprio 2
	s_barrier
	v_mfma_f32_16x16x32_bf16 v[100:103], v[148:151], v[198:201], v[100:103]
	v_mfma_f32_16x16x32_bf16 v[96:99], v[156:159], v[198:201], v[96:99]
	v_mfma_f32_16x16x32_bf16 v[84:87], v[148:151], v[206:209], v[84:87]
	v_mfma_f32_16x16x32_bf16 v[80:83], v[156:159], v[206:209], v[80:83]
	s_setprio 0
	s_add_i32 s8, s64, s37
	s_add_u32 s98, s40, s34
	s_addc_u32 s99, s41, s35
	s_mov_b32 m0, s8
	ds_read_b128 v[160:163], v231 offset:16384
	ds_read_b128 v[164:167], v231 offset:17408
	ds_read_b128 v[168:171], v231 offset:18432
	ds_read_b128 v[172:175], v231 offset:19456
	ds_read_b128 v[194:197], v231 offset:20480
	ds_read_b128 v[198:201], v231 offset:21504
	ds_read_b128 v[202:205], v231 offset:22528
	ds_read_b128 v[206:209], v231 offset:23552
	global_load_lds_dwordx4 v184, s[40:41]
	s_add_i32 m0, s8, 0x2000
	s_add_u32 s8, s40, 0x60000
	s_addc_u32 s9, s41, 0
	s_add_i32 s64, s65, s37
	global_load_lds_dwordx4 v188, s[40:41]
	s_mov_b32 m0, s64
	s_nop 0
	global_load_lds_dwordx4 v184, s[8:9]
	s_add_i32 m0, s64, 0x2000
	s_nop 0
	global_load_lds_dwordx4 v188, s[8:9]
	s_add_u32 s100, s50, s34
	s_addc_u32 s101, s51, s35
	s_mov_b32 m0, s60
	s_nop 0
	global_load_lds_dwordx4 v182, s[50:51]
	s_waitcnt vmcnt(7) lgkmcnt(0)
	s_barrier
	s_setprio 1
	v_mfma_f32_16x16x32_bf16 v[76:79], v[56:59], v[160:163], v[76:79]
	v_mfma_f32_16x16x32_bf16 v[72:75], v[64:67], v[160:163], v[72:75]
	v_mfma_f32_16x16x32_bf16 v[44:47], v[56:59], v[168:171], v[44:47]
	v_mfma_f32_16x16x32_bf16 v[40:43], v[64:67], v[168:171], v[40:43]
	v_mfma_f32_16x16x32_bf16 v[28:31], v[56:59], v[194:197], v[28:31]
	v_mfma_f32_16x16x32_bf16 v[24:27], v[64:67], v[194:197], v[24:27]
	v_mfma_f32_16x16x32_bf16 v[12:15], v[56:59], v[202:205], v[12:15]
	v_mfma_f32_16x16x32_bf16 v[8:11], v[64:67], v[202:205], v[8:11]
	v_mfma_f32_16x16x32_bf16 v[76:79], v[60:63], v[164:167], v[76:79]
	v_mfma_f32_16x16x32_bf16 v[72:75], v[68:71], v[164:167], v[72:75]
	v_mfma_f32_16x16x32_bf16 v[44:47], v[60:63], v[172:175], v[44:47]
	v_mfma_f32_16x16x32_bf16 v[40:43], v[68:71], v[172:175], v[40:43]
	v_mfma_f32_16x16x32_bf16 v[28:31], v[60:63], v[198:201], v[28:31]
	v_mfma_f32_16x16x32_bf16 v[24:27], v[68:71], v[198:201], v[24:27]
	v_mfma_f32_16x16x32_bf16 v[12:15], v[60:63], v[206:209], v[12:15]
	v_mfma_f32_16x16x32_bf16 v[8:11], v[68:71], v[206:209], v[8:11]
	v_mfma_f32_16x16x32_bf16 v[52:55], v[144:147], v[160:163], v[52:55]
	v_mfma_f32_16x16x32_bf16 v[48:51], v[152:155], v[160:163], v[48:51]
	v_mfma_f32_16x16x32_bf16 v[36:39], v[144:147], v[168:171], v[36:39]
	v_mfma_f32_16x16x32_bf16 v[32:35], v[152:155], v[168:171], v[32:35]
	v_mfma_f32_16x16x32_bf16 v[20:23], v[144:147], v[194:197], v[20:23]
	v_mfma_f32_16x16x32_bf16 v[16:19], v[152:155], v[194:197], v[16:19]
	v_mfma_f32_16x16x32_bf16 v[4:7], v[144:147], v[202:205], v[4:7]
	v_mfma_f32_16x16x32_bf16 v[0:3], v[152:155], v[202:205], v[0:3]
	v_mfma_f32_16x16x32_bf16 v[52:55], v[148:151], v[164:167], v[52:55]
	v_mfma_f32_16x16x32_bf16 v[48:51], v[156:159], v[164:167], v[48:51]
	v_mfma_f32_16x16x32_bf16 v[36:39], v[148:151], v[172:175], v[36:39]
	v_mfma_f32_16x16x32_bf16 v[32:35], v[156:159], v[172:175], v[32:35]
	s_setprio 2
	s_barrier
	v_mfma_f32_16x16x32_bf16 v[20:23], v[148:151], v[198:201], v[20:23]
	v_mfma_f32_16x16x32_bf16 v[16:19], v[156:159], v[198:201], v[16:19]
	v_mfma_f32_16x16x32_bf16 v[4:7], v[148:151], v[206:209], v[4:7]
	v_mfma_f32_16x16x32_bf16 v[0:3], v[156:159], v[206:209], v[0:3]
	s_setprio 0
	s_mov_b32 m0, s61
	s_nop 0
	global_load_lds_dwordx4 v186, s[50:51]
	s_add_i32 s64, 0, 0x18000
	s_add_i32 s65, 0, 0x1c000
	v_add_u32_e32 v68, s64, v228
	v_add_u32_e32 v156, s65, v228
	ds_read_b128 v[56:59], v68
	ds_read_b128 v[60:63], v68 offset:1024
	ds_read_b128 v[64:67], v68 offset:2048
	ds_read_b128 v[68:71], v68 offset:3072
	ds_read_b128 v[144:147], v156
	ds_read_b128 v[148:151], v156 offset:1024
	ds_read_b128 v[152:155], v156 offset:2048
	ds_read_b128 v[156:159], v156 offset:3072
	s_add_u32 s8, s50, 0x60000
	s_addc_u32 s9, s51, 0
	s_mov_b32 m0, s62
	ds_read_b128 v[160:163], v231 offset:32768
	ds_read_b128 v[164:167], v231 offset:33792
	ds_read_b128 v[168:171], v231 offset:34816
	ds_read_b128 v[172:175], v231 offset:35840
	ds_read_b128 v[194:197], v231 offset:36864
	ds_read_b128 v[198:201], v231 offset:37888
	ds_read_b128 v[202:205], v231 offset:38912
	ds_read_b128 v[206:209], v231 offset:39936
	global_load_lds_dwordx4 v182, s[8:9]
	s_mov_b32 m0, s63
	s_nop 0
	global_load_lds_dwordx4 v186, s[8:9]
	s_waitcnt vmcnt(8) lgkmcnt(0)
	s_barrier
	s_setprio 1
	v_mfma_f32_16x16x32_bf16 v[140:143], v[56:59], v[160:163], v[140:143]
	v_mfma_f32_16x16x32_bf16 v[136:139], v[64:67], v[160:163], v[136:139]
	v_mfma_f32_16x16x32_bf16 v[128:131], v[56:59], v[168:171], v[128:131]
	v_mfma_f32_16x16x32_bf16 v[120:123], v[64:67], v[168:171], v[120:123]
	v_mfma_f32_16x16x32_bf16 v[108:111], v[56:59], v[194:197], v[108:111]
	v_mfma_f32_16x16x32_bf16 v[104:107], v[64:67], v[194:197], v[104:107]
	v_mfma_f32_16x16x32_bf16 v[92:95], v[56:59], v[202:205], v[92:95]
	v_mfma_f32_16x16x32_bf16 v[88:91], v[64:67], v[202:205], v[88:91]
	v_mfma_f32_16x16x32_bf16 v[140:143], v[60:63], v[164:167], v[140:143]
	v_mfma_f32_16x16x32_bf16 v[136:139], v[68:71], v[164:167], v[136:139]
	v_mfma_f32_16x16x32_bf16 v[128:131], v[60:63], v[172:175], v[128:131]
	v_mfma_f32_16x16x32_bf16 v[120:123], v[68:71], v[172:175], v[120:123]
	v_mfma_f32_16x16x32_bf16 v[108:111], v[60:63], v[198:201], v[108:111]
	v_mfma_f32_16x16x32_bf16 v[104:107], v[68:71], v[198:201], v[104:107]
	v_mfma_f32_16x16x32_bf16 v[92:95], v[60:63], v[206:209], v[92:95]
	v_mfma_f32_16x16x32_bf16 v[88:91], v[68:71], v[206:209], v[88:91]
	v_mfma_f32_16x16x32_bf16 v[132:135], v[144:147], v[160:163], v[132:135]
	v_mfma_f32_16x16x32_bf16 v[124:127], v[152:155], v[160:163], v[124:127]
	v_mfma_f32_16x16x32_bf16 v[116:119], v[144:147], v[168:171], v[116:119]
	v_mfma_f32_16x16x32_bf16 v[112:115], v[152:155], v[168:171], v[112:115]
	v_mfma_f32_16x16x32_bf16 v[100:103], v[144:147], v[194:197], v[100:103]
	v_mfma_f32_16x16x32_bf16 v[96:99], v[152:155], v[194:197], v[96:99]
	v_mfma_f32_16x16x32_bf16 v[84:87], v[144:147], v[202:205], v[84:87]
	v_mfma_f32_16x16x32_bf16 v[80:83], v[152:155], v[202:205], v[80:83]
	v_mfma_f32_16x16x32_bf16 v[132:135], v[148:151], v[164:167], v[132:135]
	v_mfma_f32_16x16x32_bf16 v[124:127], v[156:159], v[164:167], v[124:127]
	v_mfma_f32_16x16x32_bf16 v[116:119], v[148:151], v[172:175], v[116:119]
	v_mfma_f32_16x16x32_bf16 v[112:115], v[156:159], v[172:175], v[112:115]
	s_setprio 2
	s_barrier
	v_mfma_f32_16x16x32_bf16 v[100:103], v[148:151], v[198:201], v[100:103]
	v_mfma_f32_16x16x32_bf16 v[96:99], v[156:159], v[198:201], v[96:99]
	v_mfma_f32_16x16x32_bf16 v[84:87], v[148:151], v[206:209], v[84:87]
	v_mfma_f32_16x16x32_bf16 v[80:83], v[156:159], v[206:209], v[80:83]
	s_setprio 0
	s_add_i32 s8, s64, s37
	s_mov_b32 m0, s8
	ds_read_b128 v[160:163], v231 offset:49152
	ds_read_b128 v[164:167], v231 offset:50176
	ds_read_b128 v[168:171], v231 offset:51200
	ds_read_b128 v[172:175], v231 offset:52224
	ds_read_b128 v[194:197], v231 offset:53248
	ds_read_b128 v[198:201], v231 offset:54272
	ds_read_b128 v[202:205], v231 offset:55296
	ds_read_b128 v[206:209], v231 offset:56320
	global_load_lds_dwordx4 v184, s[98:99]
	s_add_i32 m0, s8, 0x2000
	s_add_u32 s8, s40, 0x60080
	s_addc_u32 s9, s41, 0
	s_add_i32 s40, s65, s37
	global_load_lds_dwordx4 v188, s[98:99]
	s_mov_b32 m0, s40
	s_nop 0
	global_load_lds_dwordx4 v184, s[8:9]
	s_add_i32 m0, s40, 0x2000
	s_nop 0
	global_load_lds_dwordx4 v188, s[8:9]
	s_mov_b32 m0, s69
	s_nop 0
	global_load_lds_dwordx4 v182, s[100:101]
	s_mov_b32 m0, s72
	s_nop 0
	global_load_lds_dwordx4 v186, s[100:101]
	s_waitcnt vmcnt(8) lgkmcnt(0)
	s_barrier
	s_setprio 1
	v_mfma_f32_16x16x32_bf16 v[76:79], v[56:59], v[160:163], v[76:79]
	v_mfma_f32_16x16x32_bf16 v[72:75], v[64:67], v[160:163], v[72:75]
	v_mfma_f32_16x16x32_bf16 v[44:47], v[56:59], v[168:171], v[44:47]
	v_mfma_f32_16x16x32_bf16 v[40:43], v[64:67], v[168:171], v[40:43]
	v_mfma_f32_16x16x32_bf16 v[28:31], v[56:59], v[194:197], v[28:31]
	v_mfma_f32_16x16x32_bf16 v[24:27], v[64:67], v[194:197], v[24:27]
	v_mfma_f32_16x16x32_bf16 v[12:15], v[56:59], v[202:205], v[12:15]
	v_mfma_f32_16x16x32_bf16 v[8:11], v[64:67], v[202:205], v[8:11]
	v_mfma_f32_16x16x32_bf16 v[76:79], v[60:63], v[164:167], v[76:79]
	v_mfma_f32_16x16x32_bf16 v[72:75], v[68:71], v[164:167], v[72:75]
	v_mfma_f32_16x16x32_bf16 v[44:47], v[60:63], v[172:175], v[44:47]
	v_mfma_f32_16x16x32_bf16 v[40:43], v[68:71], v[172:175], v[40:43]
	v_mfma_f32_16x16x32_bf16 v[28:31], v[60:63], v[198:201], v[28:31]
	v_mfma_f32_16x16x32_bf16 v[24:27], v[68:71], v[198:201], v[24:27]
	v_mfma_f32_16x16x32_bf16 v[12:15], v[60:63], v[206:209], v[12:15]
	v_mfma_f32_16x16x32_bf16 v[8:11], v[68:71], v[206:209], v[8:11]
	v_mfma_f32_16x16x32_bf16 v[52:55], v[144:147], v[160:163], v[52:55]
	v_mfma_f32_16x16x32_bf16 v[48:51], v[152:155], v[160:163], v[48:51]
	v_mfma_f32_16x16x32_bf16 v[36:39], v[144:147], v[168:171], v[36:39]
	v_mfma_f32_16x16x32_bf16 v[32:35], v[152:155], v[168:171], v[32:35]
	v_mfma_f32_16x16x32_bf16 v[20:23], v[144:147], v[194:197], v[20:23]
	v_mfma_f32_16x16x32_bf16 v[16:19], v[152:155], v[194:197], v[16:19]
	v_mfma_f32_16x16x32_bf16 v[4:7], v[144:147], v[202:205], v[4:7]
	v_mfma_f32_16x16x32_bf16 v[0:3], v[152:155], v[202:205], v[0:3]
	v_mfma_f32_16x16x32_bf16 v[52:55], v[148:151], v[164:167], v[52:55]
	v_mfma_f32_16x16x32_bf16 v[48:51], v[156:159], v[164:167], v[48:51]
	v_mfma_f32_16x16x32_bf16 v[36:39], v[148:151], v[172:175], v[36:39]
	v_mfma_f32_16x16x32_bf16 v[32:35], v[156:159], v[172:175], v[32:35]
	s_setprio 2
	s_barrier
	v_mfma_f32_16x16x32_bf16 v[20:23], v[148:151], v[198:201], v[20:23]
	v_mfma_f32_16x16x32_bf16 v[16:19], v[156:159], v[198:201], v[16:19]
	v_mfma_f32_16x16x32_bf16 v[4:7], v[148:151], v[206:209], v[4:7]
	v_mfma_f32_16x16x32_bf16 v[0:3], v[156:159], v[206:209], v[0:3]
	s_setprio 0
	s_add_i32 s83, s83, 2
	s_add_u32 s44, s44, 0x180
	s_addc_u32 s53, s53, 0
	s_cmp_gt_u32 s83, 13
	s_mov_b64 s[8:9], s[38:39]
	s_cbranch_scc0 .LBB0_953

.LBB0_1045:
	s_add_i32 s25, s63, -2
	s_add_u32 s93, s38, 0x180
	s_addc_u32 s94, s39, 0
	s_mov_b32 s40, 0
	s_add_i32 s64, s40, 2
	s_add_u32 s38, s8, 0x180
	s_addc_u32 s39, s9, 0
	s_add_i32 s65, 0, 0x10000
	s_cmp_eq_u32 s25, s40
	s_cselect_b32 s51, s27, s39
	s_cselect_b32 s50, s26, s38
	s_cselect_b32 s41, s29, s94
	s_cselect_b32 s40, s28, s93
	s_add_i32 s66, 0, 0x14000
	v_add_u32_e32 v108, s65, v228
	v_add_u32_e32 v156, s66, v228
	ds_read_b128 v[88:91], v108
	ds_read_b128 v[92:95], v108 offset:1024
	ds_read_b128 v[104:107], v108 offset:2048
	ds_read_b128 v[108:111], v108 offset:3072
	ds_read_b128 v[144:147], v156
	ds_read_b128 v[148:151], v156 offset:1024
	ds_read_b128 v[152:155], v156 offset:2048
	ds_read_b128 v[156:159], v156 offset:3072
	s_add_i32 m0, s72, 0xc000
	ds_read_b128 v[160:163], v232
	ds_read_b128 v[164:167], v232 offset:1024
	ds_read_b128 v[168:171], v232 offset:2048
	ds_read_b128 v[172:175], v232 offset:3072
	ds_read_b128 v[194:197], v232 offset:4096
	ds_read_b128 v[198:201], v232 offset:5120
	ds_read_b128 v[202:205], v232 offset:6144
	ds_read_b128 v[206:209], v232 offset:7168
	global_load_lds_dwordx4 v192, s[8:9]
	s_add_i32 m0, s72, 0xe000
	s_nop 0
	global_load_lds_dwordx4 v190, s[8:9]
	s_waitcnt vmcnt(24) lgkmcnt(0)
	s_barrier
	s_setprio 1
	v_mfma_f32_16x16x32_bf16 v[140:143], v[88:91], v[160:163], 0
	v_mfma_f32_16x16x32_bf16 v[136:139], v[104:107], v[160:163], 0
	v_mfma_f32_16x16x32_bf16 v[124:127], v[88:91], v[168:171], 0
	v_mfma_f32_16x16x32_bf16 v[120:123], v[104:107], v[168:171], 0
	v_mfma_f32_16x16x32_bf16 v[100:103], v[88:91], v[194:197], 0
	v_mfma_f32_16x16x32_bf16 v[96:99], v[104:107], v[194:197], 0
	v_mfma_f32_16x16x32_bf16 v[76:79], v[88:91], v[202:205], 0
	v_mfma_f32_16x16x32_bf16 v[72:75], v[104:107], v[202:205], 0
	v_mfma_f32_16x16x32_bf16 v[140:143], v[92:95], v[164:167], v[140:143]
	v_mfma_f32_16x16x32_bf16 v[136:139], v[108:111], v[164:167], v[136:139]
	v_mfma_f32_16x16x32_bf16 v[124:127], v[92:95], v[172:175], v[124:127]
	v_mfma_f32_16x16x32_bf16 v[120:123], v[108:111], v[172:175], v[120:123]
	v_mfma_f32_16x16x32_bf16 v[100:103], v[92:95], v[198:201], v[100:103]
	v_mfma_f32_16x16x32_bf16 v[96:99], v[108:111], v[198:201], v[96:99]
	v_mfma_f32_16x16x32_bf16 v[76:79], v[92:95], v[206:209], v[76:79]
	v_mfma_f32_16x16x32_bf16 v[72:75], v[108:111], v[206:209], v[72:75]
	v_mfma_f32_16x16x32_bf16 v[132:135], v[144:147], v[160:163], 0
	v_mfma_f32_16x16x32_bf16 v[128:131], v[152:155], v[160:163], 0
	v_mfma_f32_16x16x32_bf16 v[116:119], v[144:147], v[168:171], 0
	v_mfma_f32_16x16x32_bf16 v[112:115], v[152:155], v[168:171], 0
	v_mfma_f32_16x16x32_bf16 v[84:87], v[144:147], v[194:197], 0
	v_mfma_f32_16x16x32_bf16 v[80:83], v[152:155], v[194:197], 0
	v_mfma_f32_16x16x32_bf16 v[68:71], v[144:147], v[202:205], 0
	v_mfma_f32_16x16x32_bf16 v[64:67], v[152:155], v[202:205], 0
	v_mfma_f32_16x16x32_bf16 v[132:135], v[148:151], v[164:167], v[132:135]
	v_mfma_f32_16x16x32_bf16 v[128:131], v[156:159], v[164:167], v[128:131]
	v_mfma_f32_16x16x32_bf16 v[116:119], v[148:151], v[172:175], v[116:119]
	v_mfma_f32_16x16x32_bf16 v[112:115], v[156:159], v[172:175], v[112:115]
	s_setprio 2
	s_barrier
	v_mfma_f32_16x16x32_bf16 v[84:87], v[148:151], v[198:201], v[84:87]
	v_mfma_f32_16x16x32_bf16 v[80:83], v[156:159], v[198:201], v[80:83]
	v_mfma_f32_16x16x32_bf16 v[68:71], v[148:151], v[206:209], v[68:71]
	v_mfma_f32_16x16x32_bf16 v[64:67], v[156:159], v[206:209], v[64:67]
	s_setprio 0
	s_add_i32 s8, s65, s68
	s_add_u32 s98, s40, s34
	s_addc_u32 s99, s41, s35
	s_mov_b32 m0, s8
	ds_read_b128 v[160:163], v232 offset:16384
	ds_read_b128 v[164:167], v232 offset:17408
	ds_read_b128 v[168:171], v232 offset:18432
	ds_read_b128 v[172:175], v232 offset:19456
	ds_read_b128 v[194:197], v232 offset:20480
	ds_read_b128 v[198:201], v232 offset:21504
	ds_read_b128 v[202:205], v232 offset:22528
	ds_read_b128 v[206:209], v232 offset:23552
	global_load_lds_dwordx4 v184, s[40:41]
	s_add_i32 m0, s8, 0x2000
	s_add_u32 s8, s40, 0x60000
	s_addc_u32 s9, s41, 0
	s_add_i32 s65, s66, s68
	global_load_lds_dwordx4 v188, s[40:41]
	s_mov_b32 m0, s65
	s_nop 0
	global_load_lds_dwordx4 v184, s[8:9]
	s_add_i32 m0, s65, 0x2000
	s_nop 0
	global_load_lds_dwordx4 v188, s[8:9]
	s_add_u32 s100, s50, s34
	s_addc_u32 s101, s51, s35
	s_mov_b32 m0, s72
	s_nop 0
	global_load_lds_dwordx4 v182, s[50:51]
	s_waitcnt vmcnt(7) lgkmcnt(0)
	s_barrier
	s_setprio 1
	v_mfma_f32_16x16x32_bf16 v[60:63], v[88:91], v[160:163], 0
	v_mfma_f32_16x16x32_bf16 v[56:59], v[104:107], v[160:163], 0
	v_mfma_f32_16x16x32_bf16 v[44:47], v[88:91], v[168:171], 0
	v_mfma_f32_16x16x32_bf16 v[40:43], v[104:107], v[168:171], 0
	v_mfma_f32_16x16x32_bf16 v[28:31], v[88:91], v[194:197], 0
	v_mfma_f32_16x16x32_bf16 v[24:27], v[104:107], v[194:197], 0
	v_mfma_f32_16x16x32_bf16 v[12:15], v[88:91], v[202:205], 0
	v_mfma_f32_16x16x32_bf16 v[8:11], v[104:107], v[202:205], 0
	v_mfma_f32_16x16x32_bf16 v[60:63], v[92:95], v[164:167], v[60:63]
	v_mfma_f32_16x16x32_bf16 v[56:59], v[108:111], v[164:167], v[56:59]
	v_mfma_f32_16x16x32_bf16 v[44:47], v[92:95], v[172:175], v[44:47]
	v_mfma_f32_16x16x32_bf16 v[40:43], v[108:111], v[172:175], v[40:43]
	v_mfma_f32_16x16x32_bf16 v[28:31], v[92:95], v[198:201], v[28:31]
	v_mfma_f32_16x16x32_bf16 v[24:27], v[108:111], v[198:201], v[24:27]
	v_mfma_f32_16x16x32_bf16 v[12:15], v[92:95], v[206:209], v[12:15]
	v_mfma_f32_16x16x32_bf16 v[8:11], v[108:111], v[206:209], v[8:11]
	v_mfma_f32_16x16x32_bf16 v[52:55], v[144:147], v[160:163], 0
	v_mfma_f32_16x16x32_bf16 v[48:51], v[152:155], v[160:163], 0
	v_mfma_f32_16x16x32_bf16 v[36:39], v[144:147], v[168:171], 0
	v_mfma_f32_16x16x32_bf16 v[32:35], v[152:155], v[168:171], 0
	v_mfma_f32_16x16x32_bf16 v[20:23], v[144:147], v[194:197], 0
	v_mfma_f32_16x16x32_bf16 v[16:19], v[152:155], v[194:197], 0
	v_mfma_f32_16x16x32_bf16 v[4:7], v[144:147], v[202:205], 0
	v_mfma_f32_16x16x32_bf16 v[0:3], v[152:155], v[202:205], 0
	v_mfma_f32_16x16x32_bf16 v[52:55], v[148:151], v[164:167], v[52:55]
	v_mfma_f32_16x16x32_bf16 v[48:51], v[156:159], v[164:167], v[48:51]
	v_mfma_f32_16x16x32_bf16 v[36:39], v[148:151], v[172:175], v[36:39]
	v_mfma_f32_16x16x32_bf16 v[32:35], v[156:159], v[172:175], v[32:35]
	s_setprio 2
	s_barrier
	v_mfma_f32_16x16x32_bf16 v[20:23], v[148:151], v[198:201], v[20:23]
	v_mfma_f32_16x16x32_bf16 v[16:19], v[156:159], v[198:201], v[16:19]
	v_mfma_f32_16x16x32_bf16 v[4:7], v[148:151], v[206:209], v[4:7]
	v_mfma_f32_16x16x32_bf16 v[0:3], v[156:159], v[206:209], v[0:3]
	s_setprio 0
	s_mov_b32 m0, s73
	s_nop 0
	global_load_lds_dwordx4 v186, s[50:51]
	s_add_i32 s65, 0, 0x18000
	s_add_i32 s66, 0, 0x1c000
	v_add_u32_e32 v108, s65, v228
	v_add_u32_e32 v156, s66, v228
	ds_read_b128 v[88:91], v108
	ds_read_b128 v[92:95], v108 offset:1024
	ds_read_b128 v[104:107], v108 offset:2048
	ds_read_b128 v[108:111], v108 offset:3072
	ds_read_b128 v[144:147], v156
	ds_read_b128 v[148:151], v156 offset:1024
	ds_read_b128 v[152:155], v156 offset:2048
	ds_read_b128 v[156:159], v156 offset:3072
	s_add_u32 s8, s50, 0x60000
	s_addc_u32 s9, s51, 0
	s_mov_b32 m0, s74
	ds_read_b128 v[160:163], v232 offset:32768
	ds_read_b128 v[164:167], v232 offset:33792
	ds_read_b128 v[168:171], v232 offset:34816
	ds_read_b128 v[172:175], v232 offset:35840
	ds_read_b128 v[194:197], v232 offset:36864
	ds_read_b128 v[198:201], v232 offset:37888
	ds_read_b128 v[202:205], v232 offset:38912
	ds_read_b128 v[206:209], v232 offset:39936
	global_load_lds_dwordx4 v182, s[8:9]
	s_mov_b32 m0, s75
	s_nop 0
	global_load_lds_dwordx4 v186, s[8:9]
	s_waitcnt vmcnt(8) lgkmcnt(0)
	s_barrier
	s_setprio 1
	v_mfma_f32_16x16x32_bf16 v[140:143], v[88:91], v[160:163], v[140:143]
	v_mfma_f32_16x16x32_bf16 v[136:139], v[104:107], v[160:163], v[136:139]
	v_mfma_f32_16x16x32_bf16 v[124:127], v[88:91], v[168:171], v[124:127]
	v_mfma_f32_16x16x32_bf16 v[120:123], v[104:107], v[168:171], v[120:123]
	v_mfma_f32_16x16x32_bf16 v[100:103], v[88:91], v[194:197], v[100:103]
	v_mfma_f32_16x16x32_bf16 v[96:99], v[104:107], v[194:197], v[96:99]
	v_mfma_f32_16x16x32_bf16 v[76:79], v[88:91], v[202:205], v[76:79]
	v_mfma_f32_16x16x32_bf16 v[72:75], v[104:107], v[202:205], v[72:75]
	v_mfma_f32_16x16x32_bf16 v[140:143], v[92:95], v[164:167], v[140:143]
	v_mfma_f32_16x16x32_bf16 v[136:139], v[108:111], v[164:167], v[136:139]
	v_mfma_f32_16x16x32_bf16 v[124:127], v[92:95], v[172:175], v[124:127]
	v_mfma_f32_16x16x32_bf16 v[120:123], v[108:111], v[172:175], v[120:123]
	v_mfma_f32_16x16x32_bf16 v[100:103], v[92:95], v[198:201], v[100:103]
	v_mfma_f32_16x16x32_bf16 v[96:99], v[108:111], v[198:201], v[96:99]
	v_mfma_f32_16x16x32_bf16 v[76:79], v[92:95], v[206:209], v[76:79]
	v_mfma_f32_16x16x32_bf16 v[72:75], v[108:111], v[206:209], v[72:75]
	v_mfma_f32_16x16x32_bf16 v[132:135], v[144:147], v[160:163], v[132:135]
	v_mfma_f32_16x16x32_bf16 v[128:131], v[152:155], v[160:163], v[128:131]
	v_mfma_f32_16x16x32_bf16 v[116:119], v[144:147], v[168:171], v[116:119]
	v_mfma_f32_16x16x32_bf16 v[112:115], v[152:155], v[168:171], v[112:115]
	v_mfma_f32_16x16x32_bf16 v[84:87], v[144:147], v[194:197], v[84:87]
	v_mfma_f32_16x16x32_bf16 v[80:83], v[152:155], v[194:197], v[80:83]
	v_mfma_f32_16x16x32_bf16 v[68:71], v[144:147], v[202:205], v[68:71]
	v_mfma_f32_16x16x32_bf16 v[64:67], v[152:155], v[202:205], v[64:67]
	v_mfma_f32_16x16x32_bf16 v[132:135], v[148:151], v[164:167], v[132:135]
	v_mfma_f32_16x16x32_bf16 v[128:131], v[156:159], v[164:167], v[128:131]
	v_mfma_f32_16x16x32_bf16 v[116:119], v[148:151], v[172:175], v[116:119]
	v_mfma_f32_16x16x32_bf16 v[112:115], v[156:159], v[172:175], v[112:115]
	s_setprio 2
	s_barrier
	v_mfma_f32_16x16x32_bf16 v[84:87], v[148:151], v[198:201], v[84:87]
	v_mfma_f32_16x16x32_bf16 v[80:83], v[156:159], v[198:201], v[80:83]
	v_mfma_f32_16x16x32_bf16 v[68:71], v[148:151], v[206:209], v[68:71]
	v_mfma_f32_16x16x32_bf16 v[64:67], v[156:159], v[206:209], v[64:67]
	s_setprio 0
	s_add_i32 s8, s65, s68
	s_mov_b32 m0, s8
	ds_read_b128 v[160:163], v232 offset:49152
	ds_read_b128 v[164:167], v232 offset:50176
	ds_read_b128 v[168:171], v232 offset:51200
	ds_read_b128 v[172:175], v232 offset:52224
	ds_read_b128 v[194:197], v232 offset:53248
	ds_read_b128 v[198:201], v232 offset:54272
	ds_read_b128 v[202:205], v232 offset:55296
	ds_read_b128 v[206:209], v232 offset:56320
	global_load_lds_dwordx4 v184, s[98:99]
	s_add_i32 m0, s8, 0x2000
	s_add_u32 s8, s40, 0x60080
	s_addc_u32 s9, s41, 0
	s_add_i32 s40, s66, s68
	global_load_lds_dwordx4 v188, s[98:99]
	s_mov_b32 m0, s40
	s_nop 0
	global_load_lds_dwordx4 v184, s[8:9]
	s_add_i32 m0, s40, 0x2000
	s_nop 0
	global_load_lds_dwordx4 v188, s[8:9]
	s_mov_b32 m0, s81
	s_nop 0
	global_load_lds_dwordx4 v182, s[100:101]
	s_mov_b32 m0, s82
	s_nop 0
	global_load_lds_dwordx4 v186, s[100:101]
	s_waitcnt vmcnt(8) lgkmcnt(0)
	s_barrier
	s_setprio 1
	v_mfma_f32_16x16x32_bf16 v[60:63], v[88:91], v[160:163], v[60:63]
	v_mfma_f32_16x16x32_bf16 v[56:59], v[104:107], v[160:163], v[56:59]
	v_mfma_f32_16x16x32_bf16 v[44:47], v[88:91], v[168:171], v[44:47]
	v_mfma_f32_16x16x32_bf16 v[40:43], v[104:107], v[168:171], v[40:43]
	v_mfma_f32_16x16x32_bf16 v[28:31], v[88:91], v[194:197], v[28:31]
	v_mfma_f32_16x16x32_bf16 v[24:27], v[104:107], v[194:197], v[24:27]
	v_mfma_f32_16x16x32_bf16 v[12:15], v[88:91], v[202:205], v[12:15]
	v_mfma_f32_16x16x32_bf16 v[8:11], v[104:107], v[202:205], v[8:11]
	v_mfma_f32_16x16x32_bf16 v[60:63], v[92:95], v[164:167], v[60:63]
	v_mfma_f32_16x16x32_bf16 v[56:59], v[108:111], v[164:167], v[56:59]
	v_mfma_f32_16x16x32_bf16 v[44:47], v[92:95], v[172:175], v[44:47]
	v_mfma_f32_16x16x32_bf16 v[40:43], v[108:111], v[172:175], v[40:43]
	v_mfma_f32_16x16x32_bf16 v[28:31], v[92:95], v[198:201], v[28:31]
	v_mfma_f32_16x16x32_bf16 v[24:27], v[108:111], v[198:201], v[24:27]
	v_mfma_f32_16x16x32_bf16 v[12:15], v[92:95], v[206:209], v[12:15]
	v_mfma_f32_16x16x32_bf16 v[8:11], v[108:111], v[206:209], v[8:11]
	v_mfma_f32_16x16x32_bf16 v[52:55], v[144:147], v[160:163], v[52:55]
	v_mfma_f32_16x16x32_bf16 v[48:51], v[152:155], v[160:163], v[48:51]
	v_mfma_f32_16x16x32_bf16 v[36:39], v[144:147], v[168:171], v[36:39]
	v_mfma_f32_16x16x32_bf16 v[32:35], v[152:155], v[168:171], v[32:35]
	v_mfma_f32_16x16x32_bf16 v[20:23], v[144:147], v[194:197], v[20:23]
	v_mfma_f32_16x16x32_bf16 v[16:19], v[152:155], v[194:197], v[16:19]
	v_mfma_f32_16x16x32_bf16 v[4:7], v[144:147], v[202:205], v[4:7]
	v_mfma_f32_16x16x32_bf16 v[0:3], v[152:155], v[202:205], v[0:3]
	v_mfma_f32_16x16x32_bf16 v[52:55], v[148:151], v[164:167], v[52:55]
	v_mfma_f32_16x16x32_bf16 v[48:51], v[156:159], v[164:167], v[48:51]
	v_mfma_f32_16x16x32_bf16 v[36:39], v[148:151], v[172:175], v[36:39]
	v_mfma_f32_16x16x32_bf16 v[32:35], v[156:159], v[172:175], v[32:35]
	s_setprio 2
	s_barrier
	v_mfma_f32_16x16x32_bf16 v[20:23], v[148:151], v[198:201], v[20:23]
	v_mfma_f32_16x16x32_bf16 v[16:19], v[156:159], v[198:201], v[16:19]
	v_mfma_f32_16x16x32_bf16 v[4:7], v[148:151], v[206:209], v[4:7]
	v_mfma_f32_16x16x32_bf16 v[0:3], v[156:159], v[206:209], v[0:3]
	s_setprio 0
	s_add_u32 s93, s93, 0x180
	s_addc_u32 s94, s94, 0
	s_cmp_ge_i32 s64, s63
	s_mov_b64 s[8:9], s[38:39]
	s_mov_b32 s40, s64
	s_cbranch_scc1 .Lpeel_exit_5
.LBB0_1046:
	s_add_i32 s64, s40, 2
	s_add_u32 s38, s8, 0x180
	s_addc_u32 s39, s9, 0
	s_add_i32 s65, 0, 0x10000
	s_cmp_eq_u32 s25, s40
	s_cselect_b32 s51, s27, s39
	s_cselect_b32 s50, s26, s38
	s_cselect_b32 s41, s29, s94
	s_cselect_b32 s40, s28, s93
	s_add_i32 s66, 0, 0x14000
	v_add_u32_e32 v108, s65, v228
	v_add_u32_e32 v156, s66, v228
	ds_read_b128 v[88:91], v108
	ds_read_b128 v[92:95], v108 offset:1024
	ds_read_b128 v[104:107], v108 offset:2048
	ds_read_b128 v[108:111], v108 offset:3072
	ds_read_b128 v[144:147], v156
	ds_read_b128 v[148:151], v156 offset:1024
	ds_read_b128 v[152:155], v156 offset:2048
	ds_read_b128 v[156:159], v156 offset:3072
	s_add_i32 m0, s72, 0xc000
	ds_read_b128 v[160:163], v232
	ds_read_b128 v[164:167], v232 offset:1024
	ds_read_b128 v[168:171], v232 offset:2048
	ds_read_b128 v[172:175], v232 offset:3072
	ds_read_b128 v[194:197], v232 offset:4096
	ds_read_b128 v[198:201], v232 offset:5120
	ds_read_b128 v[202:205], v232 offset:6144
	ds_read_b128 v[206:209], v232 offset:7168
	global_load_lds_dwordx4 v192, s[8:9]
	s_add_i32 m0, s72, 0xe000
	s_nop 0
	global_load_lds_dwordx4 v190, s[8:9]
	s_waitcnt vmcnt(8) lgkmcnt(0)
	s_barrier
	s_setprio 1
	v_mfma_f32_16x16x32_bf16 v[140:143], v[88:91], v[160:163], v[140:143]
	v_mfma_f32_16x16x32_bf16 v[136:139], v[104:107], v[160:163], v[136:139]
	v_mfma_f32_16x16x32_bf16 v[124:127], v[88:91], v[168:171], v[124:127]
	v_mfma_f32_16x16x32_bf16 v[120:123], v[104:107], v[168:171], v[120:123]
	v_mfma_f32_16x16x32_bf16 v[100:103], v[88:91], v[194:197], v[100:103]
	v_mfma_f32_16x16x32_bf16 v[96:99], v[104:107], v[194:197], v[96:99]
	v_mfma_f32_16x16x32_bf16 v[76:79], v[88:91], v[202:205], v[76:79]
	v_mfma_f32_16x16x32_bf16 v[72:75], v[104:107], v[202:205], v[72:75]
	v_mfma_f32_16x16x32_bf16 v[140:143], v[92:95], v[164:167], v[140:143]
	v_mfma_f32_16x16x32_bf16 v[136:139], v[108:111], v[164:167], v[136:139]
	v_mfma_f32_16x16x32_bf16 v[124:127], v[92:95], v[172:175], v[124:127]
	v_mfma_f32_16x16x32_bf16 v[120:123], v[108:111], v[172:175], v[120:123]
	v_mfma_f32_16x16x32_bf16 v[100:103], v[92:95], v[198:201], v[100:103]
	v_mfma_f32_16x16x32_bf16 v[96:99], v[108:111], v[198:201], v[96:99]
	v_mfma_f32_16x16x32_bf16 v[76:79], v[92:95], v[206:209], v[76:79]
	v_mfma_f32_16x16x32_bf16 v[72:75], v[108:111], v[206:209], v[72:75]
	v_mfma_f32_16x16x32_bf16 v[132:135], v[144:147], v[160:163], v[132:135]
	v_mfma_f32_16x16x32_bf16 v[128:131], v[152:155], v[160:163], v[128:131]
	v_mfma_f32_16x16x32_bf16 v[116:119], v[144:147], v[168:171], v[116:119]
	v_mfma_f32_16x16x32_bf16 v[112:115], v[152:155], v[168:171], v[112:115]
	v_mfma_f32_16x16x32_bf16 v[84:87], v[144:147], v[194:197], v[84:87]
	v_mfma_f32_16x16x32_bf16 v[80:83], v[152:155], v[194:197], v[80:83]
	v_mfma_f32_16x16x32_bf16 v[68:71], v[144:147], v[202:205], v[68:71]
	v_mfma_f32_16x16x32_bf16 v[64:67], v[152:155], v[202:205], v[64:67]
	v_mfma_f32_16x16x32_bf16 v[132:135], v[148:151], v[164:167], v[132:135]
	v_mfma_f32_16x16x32_bf16 v[128:131], v[156:159], v[164:167], v[128:131]
	v_mfma_f32_16x16x32_bf16 v[116:119], v[148:151], v[172:175], v[116:119]
	v_mfma_f32_16x16x32_bf16 v[112:115], v[156:159], v[172:175], v[112:115]
	s_setprio 2
	s_barrier
	v_mfma_f32_16x16x32_bf16 v[84:87], v[148:151], v[198:201], v[84:87]
	v_mfma_f32_16x16x32_bf16 v[80:83], v[156:159], v[198:201], v[80:83]
	v_mfma_f32_16x16x32_bf16 v[68:71], v[148:151], v[206:209], v[68:71]
	v_mfma_f32_16x16x32_bf16 v[64:67], v[156:159], v[206:209], v[64:67]
	s_setprio 0
	s_add_i32 s8, s65, s68
	s_add_u32 s98, s40, s34
	s_addc_u32 s99, s41, s35
	s_mov_b32 m0, s8
	ds_read_b128 v[160:163], v232 offset:16384
	ds_read_b128 v[164:167], v232 offset:17408
	ds_read_b128 v[168:171], v232 offset:18432
	ds_read_b128 v[172:175], v232 offset:19456
	ds_read_b128 v[194:197], v232 offset:20480
	ds_read_b128 v[198:201], v232 offset:21504
	ds_read_b128 v[202:205], v232 offset:22528
	ds_read_b128 v[206:209], v232 offset:23552
	global_load_lds_dwordx4 v184, s[40:41]
	s_add_i32 m0, s8, 0x2000
	s_add_u32 s8, s40, 0x60000
	s_addc_u32 s9, s41, 0
	s_add_i32 s65, s66, s68
	global_load_lds_dwordx4 v188, s[40:41]
	s_mov_b32 m0, s65
	s_nop 0
	global_load_lds_dwordx4 v184, s[8:9]
	s_add_i32 m0, s65, 0x2000
	s_nop 0
	global_load_lds_dwordx4 v188, s[8:9]
	s_add_u32 s100, s50, s34
	s_addc_u32 s101, s51, s35
	s_mov_b32 m0, s72
	s_nop 0
	global_load_lds_dwordx4 v182, s[50:51]
	s_waitcnt vmcnt(7) lgkmcnt(0)
	s_barrier
	s_setprio 1
	v_mfma_f32_16x16x32_bf16 v[60:63], v[88:91], v[160:163], v[60:63]
	v_mfma_f32_16x16x32_bf16 v[56:59], v[104:107], v[160:163], v[56:59]
	v_mfma_f32_16x16x32_bf16 v[44:47], v[88:91], v[168:171], v[44:47]
	v_mfma_f32_16x16x32_bf16 v[40:43], v[104:107], v[168:171], v[40:43]
	v_mfma_f32_16x16x32_bf16 v[28:31], v[88:91], v[194:197], v[28:31]
	v_mfma_f32_16x16x32_bf16 v[24:27], v[104:107], v[194:197], v[24:27]
	v_mfma_f32_16x16x32_bf16 v[12:15], v[88:91], v[202:205], v[12:15]
	v_mfma_f32_16x16x32_bf16 v[8:11], v[104:107], v[202:205], v[8:11]
	v_mfma_f32_16x16x32_bf16 v[60:63], v[92:95], v[164:167], v[60:63]
	v_mfma_f32_16x16x32_bf16 v[56:59], v[108:111], v[164:167], v[56:59]
	v_mfma_f32_16x16x32_bf16 v[44:47], v[92:95], v[172:175], v[44:47]
	v_mfma_f32_16x16x32_bf16 v[40:43], v[108:111], v[172:175], v[40:43]
	v_mfma_f32_16x16x32_bf16 v[28:31], v[92:95], v[198:201], v[28:31]
	v_mfma_f32_16x16x32_bf16 v[24:27], v[108:111], v[198:201], v[24:27]
	v_mfma_f32_16x16x32_bf16 v[12:15], v[92:95], v[206:209], v[12:15]
	v_mfma_f32_16x16x32_bf16 v[8:11], v[108:111], v[206:209], v[8:11]
	v_mfma_f32_16x16x32_bf16 v[52:55], v[144:147], v[160:163], v[52:55]
	v_mfma_f32_16x16x32_bf16 v[48:51], v[152:155], v[160:163], v[48:51]
	v_mfma_f32_16x16x32_bf16 v[36:39], v[144:147], v[168:171], v[36:39]
	v_mfma_f32_16x16x32_bf16 v[32:35], v[152:155], v[168:171], v[32:35]
	v_mfma_f32_16x16x32_bf16 v[20:23], v[144:147], v[194:197], v[20:23]
	v_mfma_f32_16x16x32_bf16 v[16:19], v[152:155], v[194:197], v[16:19]
	v_mfma_f32_16x16x32_bf16 v[4:7], v[144:147], v[202:205], v[4:7]
	v_mfma_f32_16x16x32_bf16 v[0:3], v[152:155], v[202:205], v[0:3]
	v_mfma_f32_16x16x32_bf16 v[52:55], v[148:151], v[164:167], v[52:55]
	v_mfma_f32_16x16x32_bf16 v[48:51], v[156:159], v[164:167], v[48:51]
	v_mfma_f32_16x16x32_bf16 v[36:39], v[148:151], v[172:175], v[36:39]
	v_mfma_f32_16x16x32_bf16 v[32:35], v[156:159], v[172:175], v[32:35]
	s_setprio 2
	s_barrier
	v_mfma_f32_16x16x32_bf16 v[20:23], v[148:151], v[198:201], v[20:23]
	v_mfma_f32_16x16x32_bf16 v[16:19], v[156:159], v[198:201], v[16:19]
	v_mfma_f32_16x16x32_bf16 v[4:7], v[148:151], v[206:209], v[4:7]
	v_mfma_f32_16x16x32_bf16 v[0:3], v[156:159], v[206:209], v[0:3]
	s_setprio 0
	s_mov_b32 m0, s73
	s_nop 0
	global_load_lds_dwordx4 v186, s[50:51]
	s_add_i32 s65, 0, 0x18000
	s_add_i32 s66, 0, 0x1c000
	v_add_u32_e32 v108, s65, v228
	v_add_u32_e32 v156, s66, v228
	ds_read_b128 v[88:91], v108
	ds_read_b128 v[92:95], v108 offset:1024
	ds_read_b128 v[104:107], v108 offset:2048
	ds_read_b128 v[108:111], v108 offset:3072
	ds_read_b128 v[144:147], v156
	ds_read_b128 v[148:151], v156 offset:1024
	ds_read_b128 v[152:155], v156 offset:2048
	ds_read_b128 v[156:159], v156 offset:3072
	s_add_u32 s8, s50, 0x60000
	s_addc_u32 s9, s51, 0
	s_mov_b32 m0, s74
	ds_read_b128 v[160:163], v232 offset:32768
	ds_read_b128 v[164:167], v232 offset:33792
	ds_read_b128 v[168:171], v232 offset:34816
	ds_read_b128 v[172:175], v232 offset:35840
	ds_read_b128 v[194:197], v232 offset:36864
	ds_read_b128 v[198:201], v232 offset:37888
	ds_read_b128 v[202:205], v232 offset:38912
	ds_read_b128 v[206:209], v232 offset:39936
	global_load_lds_dwordx4 v182, s[8:9]
	s_mov_b32 m0, s75
	s_nop 0
	global_load_lds_dwordx4 v186, s[8:9]
	s_waitcnt vmcnt(8) lgkmcnt(0)
	s_barrier
	s_setprio 1
	v_mfma_f32_16x16x32_bf16 v[140:143], v[88:91], v[160:163], v[140:143]
	v_mfma_f32_16x16x32_bf16 v[136:139], v[104:107], v[160:163], v[136:139]
	v_mfma_f32_16x16x32_bf16 v[124:127], v[88:91], v[168:171], v[124:127]
	v_mfma_f32_16x16x32_bf16 v[120:123], v[104:107], v[168:171], v[120:123]
	v_mfma_f32_16x16x32_bf16 v[100:103], v[88:91], v[194:197], v[100:103]
	v_mfma_f32_16x16x32_bf16 v[96:99], v[104:107], v[194:197], v[96:99]
	v_mfma_f32_16x16x32_bf16 v[76:79], v[88:91], v[202:205], v[76:79]
	v_mfma_f32_16x16x32_bf16 v[72:75], v[104:107], v[202:205], v[72:75]
	v_mfma_f32_16x16x32_bf16 v[140:143], v[92:95], v[164:167], v[140:143]
	v_mfma_f32_16x16x32_bf16 v[136:139], v[108:111], v[164:167], v[136:139]
	v_mfma_f32_16x16x32_bf16 v[124:127], v[92:95], v[172:175], v[124:127]
	v_mfma_f32_16x16x32_bf16 v[120:123], v[108:111], v[172:175], v[120:123]
	v_mfma_f32_16x16x32_bf16 v[100:103], v[92:95], v[198:201], v[100:103]
	v_mfma_f32_16x16x32_bf16 v[96:99], v[108:111], v[198:201], v[96:99]
	v_mfma_f32_16x16x32_bf16 v[76:79], v[92:95], v[206:209], v[76:79]
	v_mfma_f32_16x16x32_bf16 v[72:75], v[108:111], v[206:209], v[72:75]
	v_mfma_f32_16x16x32_bf16 v[132:135], v[144:147], v[160:163], v[132:135]
	v_mfma_f32_16x16x32_bf16 v[128:131], v[152:155], v[160:163], v[128:131]
	v_mfma_f32_16x16x32_bf16 v[116:119], v[144:147], v[168:171], v[116:119]
	v_mfma_f32_16x16x32_bf16 v[112:115], v[152:155], v[168:171], v[112:115]
	v_mfma_f32_16x16x32_bf16 v[84:87], v[144:147], v[194:197], v[84:87]
	v_mfma_f32_16x16x32_bf16 v[80:83], v[152:155], v[194:197], v[80:83]
	v_mfma_f32_16x16x32_bf16 v[68:71], v[144:147], v[202:205], v[68:71]
	v_mfma_f32_16x16x32_bf16 v[64:67], v[152:155], v[202:205], v[64:67]
	v_mfma_f32_16x16x32_bf16 v[132:135], v[148:151], v[164:167], v[132:135]
	v_mfma_f32_16x16x32_bf16 v[128:131], v[156:159], v[164:167], v[128:131]
	v_mfma_f32_16x16x32_bf16 v[116:119], v[148:151], v[172:175], v[116:119]
	v_mfma_f32_16x16x32_bf16 v[112:115], v[156:159], v[172:175], v[112:115]
	s_setprio 2
	s_barrier
	v_mfma_f32_16x16x32_bf16 v[84:87], v[148:151], v[198:201], v[84:87]
	v_mfma_f32_16x16x32_bf16 v[80:83], v[156:159], v[198:201], v[80:83]
	v_mfma_f32_16x16x32_bf16 v[68:71], v[148:151], v[206:209], v[68:71]
	v_mfma_f32_16x16x32_bf16 v[64:67], v[156:159], v[206:209], v[64:67]
	s_setprio 0
	s_add_i32 s8, s65, s68
	s_mov_b32 m0, s8
	ds_read_b128 v[160:163], v232 offset:49152
	ds_read_b128 v[164:167], v232 offset:50176
	ds_read_b128 v[168:171], v232 offset:51200
	ds_read_b128 v[172:175], v232 offset:52224
	ds_read_b128 v[194:197], v232 offset:53248
	ds_read_b128 v[198:201], v232 offset:54272
	ds_read_b128 v[202:205], v232 offset:55296
	ds_read_b128 v[206:209], v232 offset:56320
	global_load_lds_dwordx4 v184, s[98:99]
	s_add_i32 m0, s8, 0x2000
	s_add_u32 s8, s40, 0x60080
	s_addc_u32 s9, s41, 0
	s_add_i32 s40, s66, s68
	global_load_lds_dwordx4 v188, s[98:99]
	s_mov_b32 m0, s40
	s_nop 0
	global_load_lds_dwordx4 v184, s[8:9]
	s_add_i32 m0, s40, 0x2000
	s_nop 0
	global_load_lds_dwordx4 v188, s[8:9]
	s_mov_b32 m0, s81
	s_nop 0
	global_load_lds_dwordx4 v182, s[100:101]
	s_mov_b32 m0, s82
	s_nop 0
	global_load_lds_dwordx4 v186, s[100:101]
	s_waitcnt vmcnt(8) lgkmcnt(0)
	s_barrier
	s_setprio 1
	v_mfma_f32_16x16x32_bf16 v[60:63], v[88:91], v[160:163], v[60:63]
	v_mfma_f32_16x16x32_bf16 v[56:59], v[104:107], v[160:163], v[56:59]
	v_mfma_f32_16x16x32_bf16 v[44:47], v[88:91], v[168:171], v[44:47]
	v_mfma_f32_16x16x32_bf16 v[40:43], v[104:107], v[168:171], v[40:43]
	v_mfma_f32_16x16x32_bf16 v[28:31], v[88:91], v[194:197], v[28:31]
	v_mfma_f32_16x16x32_bf16 v[24:27], v[104:107], v[194:197], v[24:27]
	v_mfma_f32_16x16x32_bf16 v[12:15], v[88:91], v[202:205], v[12:15]
	v_mfma_f32_16x16x32_bf16 v[8:11], v[104:107], v[202:205], v[8:11]
	v_mfma_f32_16x16x32_bf16 v[60:63], v[92:95], v[164:167], v[60:63]
	v_mfma_f32_16x16x32_bf16 v[56:59], v[108:111], v[164:167], v[56:59]
	v_mfma_f32_16x16x32_bf16 v[44:47], v[92:95], v[172:175], v[44:47]
	v_mfma_f32_16x16x32_bf16 v[40:43], v[108:111], v[172:175], v[40:43]
	v_mfma_f32_16x16x32_bf16 v[28:31], v[92:95], v[198:201], v[28:31]
	v_mfma_f32_16x16x32_bf16 v[24:27], v[108:111], v[198:201], v[24:27]
	v_mfma_f32_16x16x32_bf16 v[12:15], v[92:95], v[206:209], v[12:15]
	v_mfma_f32_16x16x32_bf16 v[8:11], v[108:111], v[206:209], v[8:11]
	v_mfma_f32_16x16x32_bf16 v[52:55], v[144:147], v[160:163], v[52:55]
	v_mfma_f32_16x16x32_bf16 v[48:51], v[152:155], v[160:163], v[48:51]
	v_mfma_f32_16x16x32_bf16 v[36:39], v[144:147], v[168:171], v[36:39]
	v_mfma_f32_16x16x32_bf16 v[32:35], v[152:155], v[168:171], v[32:35]
	v_mfma_f32_16x16x32_bf16 v[20:23], v[144:147], v[194:197], v[20:23]
	v_mfma_f32_16x16x32_bf16 v[16:19], v[152:155], v[194:197], v[16:19]
	v_mfma_f32_16x16x32_bf16 v[4:7], v[144:147], v[202:205], v[4:7]
	v_mfma_f32_16x16x32_bf16 v[0:3], v[152:155], v[202:205], v[0:3]
	v_mfma_f32_16x16x32_bf16 v[52:55], v[148:151], v[164:167], v[52:55]
	v_mfma_f32_16x16x32_bf16 v[48:51], v[156:159], v[164:167], v[48:51]
	v_mfma_f32_16x16x32_bf16 v[36:39], v[148:151], v[172:175], v[36:39]
	v_mfma_f32_16x16x32_bf16 v[32:35], v[156:159], v[172:175], v[32:35]
	s_setprio 2
	s_barrier
	v_mfma_f32_16x16x32_bf16 v[20:23], v[148:151], v[198:201], v[20:23]
	v_mfma_f32_16x16x32_bf16 v[16:19], v[156:159], v[198:201], v[16:19]
	v_mfma_f32_16x16x32_bf16 v[4:7], v[148:151], v[206:209], v[4:7]
	v_mfma_f32_16x16x32_bf16 v[0:3], v[156:159], v[206:209], v[0:3]
	s_setprio 0
	s_add_u32 s93, s93, 0x180
	s_addc_u32 s94, s94, 0
	s_cmp_ge_i32 s64, s63
	s_mov_b64 s[8:9], s[38:39]
	s_mov_b32 s40, s64
	s_cbranch_scc0 .LBB0_1046

.LBB0_1220:
	s_ashr_i32 s21, s20, 31
	s_lshl_b64 s[28:29], s[20:21], 19
	s_add_u32 s21, s54, s28
	s_addc_u32 s23, s55, s29
	s_ashr_i32 s27, s26, 31
	s_lshl_b64 s[38:39], s[26:27], 7
	s_add_u32 s28, s21, s38
	s_addc_u32 s29, s23, s39
	s_ashr_i32 s23, s22, 31
	s_lshl_b64 s[50:51], s[22:23], 19
	s_add_u32 s21, s58, s50
	s_addc_u32 s23, s59, s51
	s_add_u32 s38, s21, s38
	s_addc_u32 s39, s23, s39
	s_cmp_lt_i32 s52, 1
	s_cbranch_scc1 .LBB0_1227
	s_and_b64 s[50:51], s[24:25], exec
	s_cselect_b32 s21, s29, s43
	s_cselect_b32 s23, s28, s42
	s_cselect_b32 s27, s39, s5
	s_cselect_b32 s53, s38, s4
	s_add_i32 s63, s52, -2
	s_add_u32 s95, s4, 0x100
	s_addc_u32 vcc_lo, s5, 0
	s_add_u32 s4, s42, 0x40080
	s_addc_u32 s5, s43, 0
	s_mov_b32 s42, 0
	s_add_i32 vcc_hi, s42, 2
	s_add_u32 s43, s4, 0xfffc0080
	s_addc_u32 s50, s5, -1
	s_add_i32 s64, 0, 0x10000
	s_cmp_eq_u32 s63, s42
	s_cselect_b32 s51, s21, s50
	s_cselect_b32 s50, s23, s43
	s_cselect_b32 s43, s27, vcc_lo
	s_cselect_b32 s42, s53, s95
	s_add_i32 s66, 0, 0x14000
	v_add_u32_e32 v108, s64, v228
	v_add_u32_e32 v156, s66, v228
	ds_read_b128 v[88:91], v108
	ds_read_b128 v[92:95], v108 offset:1024
	ds_read_b128 v[104:107], v108 offset:2048
	ds_read_b128 v[108:111], v108 offset:3072
	ds_read_b128 v[144:147], v156
	ds_read_b128 v[148:151], v156 offset:1024
	ds_read_b128 v[152:155], v156 offset:2048
	ds_read_b128 v[156:159], v156 offset:3072
	s_add_i32 m0, s7, 0xc000
	ds_read_b128 v[160:163], v232
	ds_read_b128 v[164:167], v232 offset:1024
	ds_read_b128 v[168:171], v232 offset:2048
	ds_read_b128 v[172:175], v232 offset:3072
	ds_read_b128 v[194:197], v232 offset:4096
	ds_read_b128 v[198:201], v232 offset:5120
	ds_read_b128 v[202:205], v232 offset:6144
	ds_read_b128 v[206:209], v232 offset:7168
	global_load_lds_dwordx4 v192, s[4:5]
	s_add_i32 m0, s7, 0xe000
	s_nop 0
	global_load_lds_dwordx4 v190, s[4:5]
	s_waitcnt vmcnt(24) lgkmcnt(0)
	s_barrier
	s_setprio 1
	v_mfma_f32_16x16x32_bf16 v[140:143], v[88:91], v[160:163], 0
	v_mfma_f32_16x16x32_bf16 v[136:139], v[104:107], v[160:163], 0
	v_mfma_f32_16x16x32_bf16 v[124:127], v[88:91], v[168:171], 0
	v_mfma_f32_16x16x32_bf16 v[120:123], v[104:107], v[168:171], 0
	v_mfma_f32_16x16x32_bf16 v[100:103], v[88:91], v[194:197], 0
	v_mfma_f32_16x16x32_bf16 v[96:99], v[104:107], v[194:197], 0
	v_mfma_f32_16x16x32_bf16 v[76:79], v[88:91], v[202:205], 0
	v_mfma_f32_16x16x32_bf16 v[72:75], v[104:107], v[202:205], 0
	v_mfma_f32_16x16x32_bf16 v[140:143], v[92:95], v[164:167], v[140:143]
	v_mfma_f32_16x16x32_bf16 v[136:139], v[108:111], v[164:167], v[136:139]
	v_mfma_f32_16x16x32_bf16 v[124:127], v[92:95], v[172:175], v[124:127]
	v_mfma_f32_16x16x32_bf16 v[120:123], v[108:111], v[172:175], v[120:123]
	v_mfma_f32_16x16x32_bf16 v[100:103], v[92:95], v[198:201], v[100:103]
	v_mfma_f32_16x16x32_bf16 v[96:99], v[108:111], v[198:201], v[96:99]
	v_mfma_f32_16x16x32_bf16 v[76:79], v[92:95], v[206:209], v[76:79]
	v_mfma_f32_16x16x32_bf16 v[72:75], v[108:111], v[206:209], v[72:75]
	v_mfma_f32_16x16x32_bf16 v[132:135], v[144:147], v[160:163], 0
	v_mfma_f32_16x16x32_bf16 v[128:131], v[152:155], v[160:163], 0
	v_mfma_f32_16x16x32_bf16 v[116:119], v[144:147], v[168:171], 0
	v_mfma_f32_16x16x32_bf16 v[112:115], v[152:155], v[168:171], 0
	v_mfma_f32_16x16x32_bf16 v[84:87], v[144:147], v[194:197], 0
	v_mfma_f32_16x16x32_bf16 v[80:83], v[152:155], v[194:197], 0
	v_mfma_f32_16x16x32_bf16 v[68:71], v[144:147], v[202:205], 0
	v_mfma_f32_16x16x32_bf16 v[64:67], v[152:155], v[202:205], 0
	v_mfma_f32_16x16x32_bf16 v[132:135], v[148:151], v[164:167], v[132:135]
	v_mfma_f32_16x16x32_bf16 v[128:131], v[156:159], v[164:167], v[128:131]
	v_mfma_f32_16x16x32_bf16 v[116:119], v[148:151], v[172:175], v[116:119]
	v_mfma_f32_16x16x32_bf16 v[112:115], v[156:159], v[172:175], v[112:115]
	s_setprio 2
	s_barrier
	v_mfma_f32_16x16x32_bf16 v[84:87], v[148:151], v[198:201], v[84:87]
	v_mfma_f32_16x16x32_bf16 v[80:83], v[156:159], v[198:201], v[80:83]
	v_mfma_f32_16x16x32_bf16 v[68:71], v[148:151], v[206:209], v[68:71]
	v_mfma_f32_16x16x32_bf16 v[64:67], v[156:159], v[206:209], v[64:67]
	s_setprio 0
	s_add_i32 s64, s64, s72
	s_add_u32 s98, s42, s34
	s_addc_u32 s99, s43, s35
	s_mov_b32 m0, s64
	ds_read_b128 v[160:163], v232 offset:16384
	ds_read_b128 v[164:167], v232 offset:17408
	ds_read_b128 v[168:171], v232 offset:18432
	ds_read_b128 v[172:175], v232 offset:19456
	ds_read_b128 v[194:197], v232 offset:20480
	ds_read_b128 v[198:201], v232 offset:21504
	ds_read_b128 v[202:205], v232 offset:22528
	ds_read_b128 v[206:209], v232 offset:23552
	global_load_lds_dwordx4 v184, s[42:43]
	s_add_i32 m0, s64, 0x2000
	s_add_u32 s64, s42, 0x40000
	s_addc_u32 s65, s43, 0
	s_add_i32 s66, s66, s72
	global_load_lds_dwordx4 v188, s[42:43]
	s_mov_b32 m0, s66
	s_nop 0
	global_load_lds_dwordx4 v184, s[64:65]
	s_add_i32 m0, s66, 0x2000
	s_nop 0
	global_load_lds_dwordx4 v188, s[64:65]
	s_add_u32 s100, s50, s34
	s_addc_u32 s101, s51, s35
	s_mov_b32 m0, s7
	s_nop 0
	global_load_lds_dwordx4 v182, s[50:51]
	s_waitcnt vmcnt(7) lgkmcnt(0)
	s_barrier
	s_setprio 1
	v_mfma_f32_16x16x32_bf16 v[60:63], v[88:91], v[160:163], 0
	v_mfma_f32_16x16x32_bf16 v[56:59], v[104:107], v[160:163], 0
	v_mfma_f32_16x16x32_bf16 v[44:47], v[88:91], v[168:171], 0
	v_mfma_f32_16x16x32_bf16 v[40:43], v[104:107], v[168:171], 0
	v_mfma_f32_16x16x32_bf16 v[28:31], v[88:91], v[194:197], 0
	v_mfma_f32_16x16x32_bf16 v[24:27], v[104:107], v[194:197], 0
	v_mfma_f32_16x16x32_bf16 v[12:15], v[88:91], v[202:205], 0
	v_mfma_f32_16x16x32_bf16 v[8:11], v[104:107], v[202:205], 0
	v_mfma_f32_16x16x32_bf16 v[60:63], v[92:95], v[164:167], v[60:63]
	v_mfma_f32_16x16x32_bf16 v[56:59], v[108:111], v[164:167], v[56:59]
	v_mfma_f32_16x16x32_bf16 v[44:47], v[92:95], v[172:175], v[44:47]
	v_mfma_f32_16x16x32_bf16 v[40:43], v[108:111], v[172:175], v[40:43]
	v_mfma_f32_16x16x32_bf16 v[28:31], v[92:95], v[198:201], v[28:31]
	v_mfma_f32_16x16x32_bf16 v[24:27], v[108:111], v[198:201], v[24:27]
	v_mfma_f32_16x16x32_bf16 v[12:15], v[92:95], v[206:209], v[12:15]
	v_mfma_f32_16x16x32_bf16 v[8:11], v[108:111], v[206:209], v[8:11]
	v_mfma_f32_16x16x32_bf16 v[52:55], v[144:147], v[160:163], 0
	v_mfma_f32_16x16x32_bf16 v[48:51], v[152:155], v[160:163], 0
	v_mfma_f32_16x16x32_bf16 v[36:39], v[144:147], v[168:171], 0
	v_mfma_f32_16x16x32_bf16 v[32:35], v[152:155], v[168:171], 0
	v_mfma_f32_16x16x32_bf16 v[20:23], v[144:147], v[194:197], 0
	v_mfma_f32_16x16x32_bf16 v[16:19], v[152:155], v[194:197], 0
	v_mfma_f32_16x16x32_bf16 v[4:7], v[144:147], v[202:205], 0
	v_mfma_f32_16x16x32_bf16 v[0:3], v[152:155], v[202:205], 0
	v_mfma_f32_16x16x32_bf16 v[52:55], v[148:151], v[164:167], v[52:55]
	v_mfma_f32_16x16x32_bf16 v[48:51], v[156:159], v[164:167], v[48:51]
	v_mfma_f32_16x16x32_bf16 v[36:39], v[148:151], v[172:175], v[36:39]
	v_mfma_f32_16x16x32_bf16 v[32:35], v[156:159], v[172:175], v[32:35]
	s_setprio 2
	s_barrier
	v_mfma_f32_16x16x32_bf16 v[20:23], v[148:151], v[198:201], v[20:23]
	v_mfma_f32_16x16x32_bf16 v[16:19], v[156:159], v[198:201], v[16:19]
	v_mfma_f32_16x16x32_bf16 v[4:7], v[148:151], v[206:209], v[4:7]
	v_mfma_f32_16x16x32_bf16 v[0:3], v[156:159], v[206:209], v[0:3]
	s_setprio 0
	s_mov_b32 m0, s73
	s_nop 0
	global_load_lds_dwordx4 v186, s[50:51]
	s_add_i32 s64, 0, 0x18000
	s_add_i32 s65, 0, 0x1c000
	v_add_u32_e32 v108, s64, v228
	v_add_u32_e32 v156, s65, v228
	ds_read_b128 v[88:91], v108
	ds_read_b128 v[92:95], v108 offset:1024
	ds_read_b128 v[104:107], v108 offset:2048
	ds_read_b128 v[108:111], v108 offset:3072
	ds_read_b128 v[144:147], v156
	ds_read_b128 v[148:151], v156 offset:1024
	ds_read_b128 v[152:155], v156 offset:2048
	ds_read_b128 v[156:159], v156 offset:3072
	s_add_u32 s50, s50, 0x40000
	s_addc_u32 s51, s51, 0
	s_mov_b32 m0, s74
	ds_read_b128 v[160:163], v232 offset:32768
	ds_read_b128 v[164:167], v232 offset:33792
	ds_read_b128 v[168:171], v232 offset:34816
	ds_read_b128 v[172:175], v232 offset:35840
	ds_read_b128 v[194:197], v232 offset:36864
	ds_read_b128 v[198:201], v232 offset:37888
	ds_read_b128 v[202:205], v232 offset:38912
	ds_read_b128 v[206:209], v232 offset:39936
	global_load_lds_dwordx4 v182, s[50:51]
	s_mov_b32 m0, s75
	s_nop 0
	global_load_lds_dwordx4 v186, s[50:51]
	s_waitcnt vmcnt(8) lgkmcnt(0)
	s_barrier
	s_setprio 1
	v_mfma_f32_16x16x32_bf16 v[140:143], v[88:91], v[160:163], v[140:143]
	v_mfma_f32_16x16x32_bf16 v[136:139], v[104:107], v[160:163], v[136:139]
	v_mfma_f32_16x16x32_bf16 v[124:127], v[88:91], v[168:171], v[124:127]
	v_mfma_f32_16x16x32_bf16 v[120:123], v[104:107], v[168:171], v[120:123]
	v_mfma_f32_16x16x32_bf16 v[100:103], v[88:91], v[194:197], v[100:103]
	v_mfma_f32_16x16x32_bf16 v[96:99], v[104:107], v[194:197], v[96:99]
	v_mfma_f32_16x16x32_bf16 v[76:79], v[88:91], v[202:205], v[76:79]
	v_mfma_f32_16x16x32_bf16 v[72:75], v[104:107], v[202:205], v[72:75]
	v_mfma_f32_16x16x32_bf16 v[140:143], v[92:95], v[164:167], v[140:143]
	v_mfma_f32_16x16x32_bf16 v[136:139], v[108:111], v[164:167], v[136:139]
	v_mfma_f32_16x16x32_bf16 v[124:127], v[92:95], v[172:175], v[124:127]
	v_mfma_f32_16x16x32_bf16 v[120:123], v[108:111], v[172:175], v[120:123]
	v_mfma_f32_16x16x32_bf16 v[100:103], v[92:95], v[198:201], v[100:103]
	v_mfma_f32_16x16x32_bf16 v[96:99], v[108:111], v[198:201], v[96:99]
	v_mfma_f32_16x16x32_bf16 v[76:79], v[92:95], v[206:209], v[76:79]
	v_mfma_f32_16x16x32_bf16 v[72:75], v[108:111], v[206:209], v[72:75]
	v_mfma_f32_16x16x32_bf16 v[132:135], v[144:147], v[160:163], v[132:135]
	v_mfma_f32_16x16x32_bf16 v[128:131], v[152:155], v[160:163], v[128:131]
	v_mfma_f32_16x16x32_bf16 v[116:119], v[144:147], v[168:171], v[116:119]
	v_mfma_f32_16x16x32_bf16 v[112:115], v[152:155], v[168:171], v[112:115]
	v_mfma_f32_16x16x32_bf16 v[84:87], v[144:147], v[194:197], v[84:87]
	v_mfma_f32_16x16x32_bf16 v[80:83], v[152:155], v[194:197], v[80:83]
	v_mfma_f32_16x16x32_bf16 v[68:71], v[144:147], v[202:205], v[68:71]
	v_mfma_f32_16x16x32_bf16 v[64:67], v[152:155], v[202:205], v[64:67]
	v_mfma_f32_16x16x32_bf16 v[132:135], v[148:151], v[164:167], v[132:135]
	v_mfma_f32_16x16x32_bf16 v[128:131], v[156:159], v[164:167], v[128:131]
	v_mfma_f32_16x16x32_bf16 v[116:119], v[148:151], v[172:175], v[116:119]
	v_mfma_f32_16x16x32_bf16 v[112:115], v[156:159], v[172:175], v[112:115]
	s_setprio 2
	s_barrier
	v_mfma_f32_16x16x32_bf16 v[84:87], v[148:151], v[198:201], v[84:87]
	v_mfma_f32_16x16x32_bf16 v[80:83], v[156:159], v[198:201], v[80:83]
	v_mfma_f32_16x16x32_bf16 v[68:71], v[148:151], v[206:209], v[68:71]
	v_mfma_f32_16x16x32_bf16 v[64:67], v[156:159], v[206:209], v[64:67]
	s_setprio 0
	s_add_i32 s50, s64, s72
	s_mov_b32 m0, s50
	ds_read_b128 v[160:163], v232 offset:49152
	ds_read_b128 v[164:167], v232 offset:50176
	ds_read_b128 v[168:171], v232 offset:51200
	ds_read_b128 v[172:175], v232 offset:52224
	ds_read_b128 v[194:197], v232 offset:53248
	ds_read_b128 v[198:201], v232 offset:54272
	ds_read_b128 v[202:205], v232 offset:55296
	ds_read_b128 v[206:209], v232 offset:56320
	global_load_lds_dwordx4 v184, s[98:99]
	s_add_i32 m0, s50, 0x2000
	s_add_u32 s42, s42, 0x40080
	s_addc_u32 s43, s43, 0
	s_add_i32 s50, s65, s72
	global_load_lds_dwordx4 v188, s[98:99]
	s_mov_b32 m0, s50
	s_nop 0
	global_load_lds_dwordx4 v184, s[42:43]
	s_add_i32 m0, s50, 0x2000
	s_nop 0
	global_load_lds_dwordx4 v188, s[42:43]
	s_mov_b32 m0, s81
	s_nop 0
	global_load_lds_dwordx4 v182, s[100:101]
	s_mov_b32 m0, s82
	s_nop 0
	global_load_lds_dwordx4 v186, s[100:101]
	s_waitcnt vmcnt(8) lgkmcnt(0)
	s_barrier
	s_setprio 1
	v_mfma_f32_16x16x32_bf16 v[60:63], v[88:91], v[160:163], v[60:63]
	v_mfma_f32_16x16x32_bf16 v[56:59], v[104:107], v[160:163], v[56:59]
	v_mfma_f32_16x16x32_bf16 v[44:47], v[88:91], v[168:171], v[44:47]
	v_mfma_f32_16x16x32_bf16 v[40:43], v[104:107], v[168:171], v[40:43]
	v_mfma_f32_16x16x32_bf16 v[28:31], v[88:91], v[194:197], v[28:31]
	v_mfma_f32_16x16x32_bf16 v[24:27], v[104:107], v[194:197], v[24:27]
	v_mfma_f32_16x16x32_bf16 v[12:15], v[88:91], v[202:205], v[12:15]
	v_mfma_f32_16x16x32_bf16 v[8:11], v[104:107], v[202:205], v[8:11]
	v_mfma_f32_16x16x32_bf16 v[60:63], v[92:95], v[164:167], v[60:63]
	v_mfma_f32_16x16x32_bf16 v[56:59], v[108:111], v[164:167], v[56:59]
	v_mfma_f32_16x16x32_bf16 v[44:47], v[92:95], v[172:175], v[44:47]
	v_mfma_f32_16x16x32_bf16 v[40:43], v[108:111], v[172:175], v[40:43]
	v_mfma_f32_16x16x32_bf16 v[28:31], v[92:95], v[198:201], v[28:31]
	v_mfma_f32_16x16x32_bf16 v[24:27], v[108:111], v[198:201], v[24:27]
	v_mfma_f32_16x16x32_bf16 v[12:15], v[92:95], v[206:209], v[12:15]
	v_mfma_f32_16x16x32_bf16 v[8:11], v[108:111], v[206:209], v[8:11]
	v_mfma_f32_16x16x32_bf16 v[52:55], v[144:147], v[160:163], v[52:55]
	v_mfma_f32_16x16x32_bf16 v[48:51], v[152:155], v[160:163], v[48:51]
	v_mfma_f32_16x16x32_bf16 v[36:39], v[144:147], v[168:171], v[36:39]
	v_mfma_f32_16x16x32_bf16 v[32:35], v[152:155], v[168:171], v[32:35]
	v_mfma_f32_16x16x32_bf16 v[20:23], v[144:147], v[194:197], v[20:23]
	v_mfma_f32_16x16x32_bf16 v[16:19], v[152:155], v[194:197], v[16:19]
	v_mfma_f32_16x16x32_bf16 v[4:7], v[144:147], v[202:205], v[4:7]
	v_mfma_f32_16x16x32_bf16 v[0:3], v[152:155], v[202:205], v[0:3]
	v_mfma_f32_16x16x32_bf16 v[52:55], v[148:151], v[164:167], v[52:55]
	v_mfma_f32_16x16x32_bf16 v[48:51], v[156:159], v[164:167], v[48:51]
	v_mfma_f32_16x16x32_bf16 v[36:39], v[148:151], v[172:175], v[36:39]
	v_mfma_f32_16x16x32_bf16 v[32:35], v[156:159], v[172:175], v[32:35]
	s_setprio 2
	s_barrier
	v_mfma_f32_16x16x32_bf16 v[20:23], v[148:151], v[198:201], v[20:23]
	v_mfma_f32_16x16x32_bf16 v[16:19], v[156:159], v[198:201], v[16:19]
	v_mfma_f32_16x16x32_bf16 v[4:7], v[148:151], v[206:209], v[4:7]
	v_mfma_f32_16x16x32_bf16 v[0:3], v[156:159], v[206:209], v[0:3]
	s_setprio 0
	s_add_u32 s95, s95, 0x100
	s_addc_u32 vcc_lo, vcc_lo, 0
	s_add_u32 s4, s4, 0x100
	s_addc_u32 s5, s5, 0
	s_cmp_ge_i32 vcc_hi, s52
	s_mov_b32 s42, vcc_hi
	s_cbranch_scc1 .Lpeel_exit_6
.LBB0_1222:
	s_add_i32 vcc_hi, s42, 2
	s_add_u32 s43, s4, 0xfffc0080
	s_addc_u32 s50, s5, -1
	s_add_i32 s64, 0, 0x10000
	s_cmp_eq_u32 s63, s42
	s_cselect_b32 s51, s21, s50
	s_cselect_b32 s50, s23, s43
	s_cselect_b32 s43, s27, vcc_lo
	s_cselect_b32 s42, s53, s95
	s_add_i32 s66, 0, 0x14000
	v_add_u32_e32 v108, s64, v228
	v_add_u32_e32 v156, s66, v228
	ds_read_b128 v[88:91], v108
	ds_read_b128 v[92:95], v108 offset:1024
	ds_read_b128 v[104:107], v108 offset:2048
	ds_read_b128 v[108:111], v108 offset:3072
	ds_read_b128 v[144:147], v156
	ds_read_b128 v[148:151], v156 offset:1024
	ds_read_b128 v[152:155], v156 offset:2048
	ds_read_b128 v[156:159], v156 offset:3072
	s_add_i32 m0, s7, 0xc000
	ds_read_b128 v[160:163], v232
	ds_read_b128 v[164:167], v232 offset:1024
	ds_read_b128 v[168:171], v232 offset:2048
	ds_read_b128 v[172:175], v232 offset:3072
	ds_read_b128 v[194:197], v232 offset:4096
	ds_read_b128 v[198:201], v232 offset:5120
	ds_read_b128 v[202:205], v232 offset:6144
	ds_read_b128 v[206:209], v232 offset:7168
	global_load_lds_dwordx4 v192, s[4:5]
	s_add_i32 m0, s7, 0xe000
	s_nop 0
	global_load_lds_dwordx4 v190, s[4:5]
	s_waitcnt vmcnt(8) lgkmcnt(0)
	s_barrier
	s_setprio 1
	v_mfma_f32_16x16x32_bf16 v[140:143], v[88:91], v[160:163], v[140:143]
	v_mfma_f32_16x16x32_bf16 v[136:139], v[104:107], v[160:163], v[136:139]
	v_mfma_f32_16x16x32_bf16 v[124:127], v[88:91], v[168:171], v[124:127]
	v_mfma_f32_16x16x32_bf16 v[120:123], v[104:107], v[168:171], v[120:123]
	v_mfma_f32_16x16x32_bf16 v[100:103], v[88:91], v[194:197], v[100:103]
	v_mfma_f32_16x16x32_bf16 v[96:99], v[104:107], v[194:197], v[96:99]
	v_mfma_f32_16x16x32_bf16 v[76:79], v[88:91], v[202:205], v[76:79]
	v_mfma_f32_16x16x32_bf16 v[72:75], v[104:107], v[202:205], v[72:75]
	v_mfma_f32_16x16x32_bf16 v[140:143], v[92:95], v[164:167], v[140:143]
	v_mfma_f32_16x16x32_bf16 v[136:139], v[108:111], v[164:167], v[136:139]
	v_mfma_f32_16x16x32_bf16 v[124:127], v[92:95], v[172:175], v[124:127]
	v_mfma_f32_16x16x32_bf16 v[120:123], v[108:111], v[172:175], v[120:123]
	v_mfma_f32_16x16x32_bf16 v[100:103], v[92:95], v[198:201], v[100:103]
	v_mfma_f32_16x16x32_bf16 v[96:99], v[108:111], v[198:201], v[96:99]
	v_mfma_f32_16x16x32_bf16 v[76:79], v[92:95], v[206:209], v[76:79]
	v_mfma_f32_16x16x32_bf16 v[72:75], v[108:111], v[206:209], v[72:75]
	v_mfma_f32_16x16x32_bf16 v[132:135], v[144:147], v[160:163], v[132:135]
	v_mfma_f32_16x16x32_bf16 v[128:131], v[152:155], v[160:163], v[128:131]
	v_mfma_f32_16x16x32_bf16 v[116:119], v[144:147], v[168:171], v[116:119]
	v_mfma_f32_16x16x32_bf16 v[112:115], v[152:155], v[168:171], v[112:115]
	v_mfma_f32_16x16x32_bf16 v[84:87], v[144:147], v[194:197], v[84:87]
	v_mfma_f32_16x16x32_bf16 v[80:83], v[152:155], v[194:197], v[80:83]
	v_mfma_f32_16x16x32_bf16 v[68:71], v[144:147], v[202:205], v[68:71]
	v_mfma_f32_16x16x32_bf16 v[64:67], v[152:155], v[202:205], v[64:67]
	v_mfma_f32_16x16x32_bf16 v[132:135], v[148:151], v[164:167], v[132:135]
	v_mfma_f32_16x16x32_bf16 v[128:131], v[156:159], v[164:167], v[128:131]
	v_mfma_f32_16x16x32_bf16 v[116:119], v[148:151], v[172:175], v[116:119]
	v_mfma_f32_16x16x32_bf16 v[112:115], v[156:159], v[172:175], v[112:115]
	s_setprio 2
	s_barrier
	v_mfma_f32_16x16x32_bf16 v[84:87], v[148:151], v[198:201], v[84:87]
	v_mfma_f32_16x16x32_bf16 v[80:83], v[156:159], v[198:201], v[80:83]
	v_mfma_f32_16x16x32_bf16 v[68:71], v[148:151], v[206:209], v[68:71]
	v_mfma_f32_16x16x32_bf16 v[64:67], v[156:159], v[206:209], v[64:67]
	s_setprio 0
	s_add_i32 s64, s64, s72
	s_add_u32 s98, s42, s34
	s_addc_u32 s99, s43, s35
	s_mov_b32 m0, s64
	ds_read_b128 v[160:163], v232 offset:16384
	ds_read_b128 v[164:167], v232 offset:17408
	ds_read_b128 v[168:171], v232 offset:18432
	ds_read_b128 v[172:175], v232 offset:19456
	ds_read_b128 v[194:197], v232 offset:20480
	ds_read_b128 v[198:201], v232 offset:21504
	ds_read_b128 v[202:205], v232 offset:22528
	ds_read_b128 v[206:209], v232 offset:23552
	global_load_lds_dwordx4 v184, s[42:43]
	s_add_i32 m0, s64, 0x2000
	s_add_u32 s64, s42, 0x40000
	s_addc_u32 s65, s43, 0
	s_add_i32 s66, s66, s72
	global_load_lds_dwordx4 v188, s[42:43]
	s_mov_b32 m0, s66
	s_nop 0
	global_load_lds_dwordx4 v184, s[64:65]
	s_add_i32 m0, s66, 0x2000
	s_nop 0
	global_load_lds_dwordx4 v188, s[64:65]
	s_add_u32 s100, s50, s34
	s_addc_u32 s101, s51, s35
	s_mov_b32 m0, s7
	s_nop 0
	global_load_lds_dwordx4 v182, s[50:51]
	s_waitcnt vmcnt(7) lgkmcnt(0)
	s_barrier
	s_setprio 1
	v_mfma_f32_16x16x32_bf16 v[60:63], v[88:91], v[160:163], v[60:63]
	v_mfma_f32_16x16x32_bf16 v[56:59], v[104:107], v[160:163], v[56:59]
	v_mfma_f32_16x16x32_bf16 v[44:47], v[88:91], v[168:171], v[44:47]
	v_mfma_f32_16x16x32_bf16 v[40:43], v[104:107], v[168:171], v[40:43]
	v_mfma_f32_16x16x32_bf16 v[28:31], v[88:91], v[194:197], v[28:31]
	v_mfma_f32_16x16x32_bf16 v[24:27], v[104:107], v[194:197], v[24:27]
	v_mfma_f32_16x16x32_bf16 v[12:15], v[88:91], v[202:205], v[12:15]
	v_mfma_f32_16x16x32_bf16 v[8:11], v[104:107], v[202:205], v[8:11]
	v_mfma_f32_16x16x32_bf16 v[60:63], v[92:95], v[164:167], v[60:63]
	v_mfma_f32_16x16x32_bf16 v[56:59], v[108:111], v[164:167], v[56:59]
	v_mfma_f32_16x16x32_bf16 v[44:47], v[92:95], v[172:175], v[44:47]
	v_mfma_f32_16x16x32_bf16 v[40:43], v[108:111], v[172:175], v[40:43]
	v_mfma_f32_16x16x32_bf16 v[28:31], v[92:95], v[198:201], v[28:31]
	v_mfma_f32_16x16x32_bf16 v[24:27], v[108:111], v[198:201], v[24:27]
	v_mfma_f32_16x16x32_bf16 v[12:15], v[92:95], v[206:209], v[12:15]
	v_mfma_f32_16x16x32_bf16 v[8:11], v[108:111], v[206:209], v[8:11]
	v_mfma_f32_16x16x32_bf16 v[52:55], v[144:147], v[160:163], v[52:55]
	v_mfma_f32_16x16x32_bf16 v[48:51], v[152:155], v[160:163], v[48:51]
	v_mfma_f32_16x16x32_bf16 v[36:39], v[144:147], v[168:171], v[36:39]
	v_mfma_f32_16x16x32_bf16 v[32:35], v[152:155], v[168:171], v[32:35]
	v_mfma_f32_16x16x32_bf16 v[20:23], v[144:147], v[194:197], v[20:23]
	v_mfma_f32_16x16x32_bf16 v[16:19], v[152:155], v[194:197], v[16:19]
	v_mfma_f32_16x16x32_bf16 v[4:7], v[144:147], v[202:205], v[4:7]
	v_mfma_f32_16x16x32_bf16 v[0:3], v[152:155], v[202:205], v[0:3]
	v_mfma_f32_16x16x32_bf16 v[52:55], v[148:151], v[164:167], v[52:55]
	v_mfma_f32_16x16x32_bf16 v[48:51], v[156:159], v[164:167], v[48:51]
	v_mfma_f32_16x16x32_bf16 v[36:39], v[148:151], v[172:175], v[36:39]
	v_mfma_f32_16x16x32_bf16 v[32:35], v[156:159], v[172:175], v[32:35]
	s_setprio 2
	s_barrier
	v_mfma_f32_16x16x32_bf16 v[20:23], v[148:151], v[198:201], v[20:23]
	v_mfma_f32_16x16x32_bf16 v[16:19], v[156:159], v[198:201], v[16:19]
	v_mfma_f32_16x16x32_bf16 v[4:7], v[148:151], v[206:209], v[4:7]
	v_mfma_f32_16x16x32_bf16 v[0:3], v[156:159], v[206:209], v[0:3]
	s_setprio 0
	s_mov_b32 m0, s73
	s_nop 0
	global_load_lds_dwordx4 v186, s[50:51]
	s_add_i32 s64, 0, 0x18000
	s_add_i32 s65, 0, 0x1c000
	v_add_u32_e32 v108, s64, v228
	v_add_u32_e32 v156, s65, v228
	ds_read_b128 v[88:91], v108
	ds_read_b128 v[92:95], v108 offset:1024
	ds_read_b128 v[104:107], v108 offset:2048
	ds_read_b128 v[108:111], v108 offset:3072
	ds_read_b128 v[144:147], v156
	ds_read_b128 v[148:151], v156 offset:1024
	ds_read_b128 v[152:155], v156 offset:2048
	ds_read_b128 v[156:159], v156 offset:3072
	s_add_u32 s50, s50, 0x40000
	s_addc_u32 s51, s51, 0
	s_mov_b32 m0, s74
	ds_read_b128 v[160:163], v232 offset:32768
	ds_read_b128 v[164:167], v232 offset:33792
	ds_read_b128 v[168:171], v232 offset:34816
	ds_read_b128 v[172:175], v232 offset:35840
	ds_read_b128 v[194:197], v232 offset:36864
	ds_read_b128 v[198:201], v232 offset:37888
	ds_read_b128 v[202:205], v232 offset:38912
	ds_read_b128 v[206:209], v232 offset:39936
	global_load_lds_dwordx4 v182, s[50:51]
	s_mov_b32 m0, s75
	s_nop 0
	global_load_lds_dwordx4 v186, s[50:51]
	s_waitcnt vmcnt(8) lgkmcnt(0)
	s_barrier
	s_setprio 1
	v_mfma_f32_16x16x32_bf16 v[140:143], v[88:91], v[160:163], v[140:143]
	v_mfma_f32_16x16x32_bf16 v[136:139], v[104:107], v[160:163], v[136:139]
	v_mfma_f32_16x16x32_bf16 v[124:127], v[88:91], v[168:171], v[124:127]
	v_mfma_f32_16x16x32_bf16 v[120:123], v[104:107], v[168:171], v[120:123]
	v_mfma_f32_16x16x32_bf16 v[100:103], v[88:91], v[194:197], v[100:103]
	v_mfma_f32_16x16x32_bf16 v[96:99], v[104:107], v[194:197], v[96:99]
	v_mfma_f32_16x16x32_bf16 v[76:79], v[88:91], v[202:205], v[76:79]
	v_mfma_f32_16x16x32_bf16 v[72:75], v[104:107], v[202:205], v[72:75]
	v_mfma_f32_16x16x32_bf16 v[140:143], v[92:95], v[164:167], v[140:143]
	v_mfma_f32_16x16x32_bf16 v[136:139], v[108:111], v[164:167], v[136:139]
	v_mfma_f32_16x16x32_bf16 v[124:127], v[92:95], v[172:175], v[124:127]
	v_mfma_f32_16x16x32_bf16 v[120:123], v[108:111], v[172:175], v[120:123]
	v_mfma_f32_16x16x32_bf16 v[100:103], v[92:95], v[198:201], v[100:103]
	v_mfma_f32_16x16x32_bf16 v[96:99], v[108:111], v[198:201], v[96:99]
	v_mfma_f32_16x16x32_bf16 v[76:79], v[92:95], v[206:209], v[76:79]
	v_mfma_f32_16x16x32_bf16 v[72:75], v[108:111], v[206:209], v[72:75]
	v_mfma_f32_16x16x32_bf16 v[132:135], v[144:147], v[160:163], v[132:135]
	v_mfma_f32_16x16x32_bf16 v[128:131], v[152:155], v[160:163], v[128:131]
	v_mfma_f32_16x16x32_bf16 v[116:119], v[144:147], v[168:171], v[116:119]
	v_mfma_f32_16x16x32_bf16 v[112:115], v[152:155], v[168:171], v[112:115]
	v_mfma_f32_16x16x32_bf16 v[84:87], v[144:147], v[194:197], v[84:87]
	v_mfma_f32_16x16x32_bf16 v[80:83], v[152:155], v[194:197], v[80:83]
	v_mfma_f32_16x16x32_bf16 v[68:71], v[144:147], v[202:205], v[68:71]
	v_mfma_f32_16x16x32_bf16 v[64:67], v[152:155], v[202:205], v[64:67]
	v_mfma_f32_16x16x32_bf16 v[132:135], v[148:151], v[164:167], v[132:135]
	v_mfma_f32_16x16x32_bf16 v[128:131], v[156:159], v[164:167], v[128:131]
	v_mfma_f32_16x16x32_bf16 v[116:119], v[148:151], v[172:175], v[116:119]
	v_mfma_f32_16x16x32_bf16 v[112:115], v[156:159], v[172:175], v[112:115]
	s_setprio 2
	s_barrier
	v_mfma_f32_16x16x32_bf16 v[84:87], v[148:151], v[198:201], v[84:87]
	v_mfma_f32_16x16x32_bf16 v[80:83], v[156:159], v[198:201], v[80:83]
	v_mfma_f32_16x16x32_bf16 v[68:71], v[148:151], v[206:209], v[68:71]
	v_mfma_f32_16x16x32_bf16 v[64:67], v[156:159], v[206:209], v[64:67]
	s_setprio 0
	s_add_i32 s50, s64, s72
	s_mov_b32 m0, s50
	ds_read_b128 v[160:163], v232 offset:49152
	ds_read_b128 v[164:167], v232 offset:50176
	ds_read_b128 v[168:171], v232 offset:51200
	ds_read_b128 v[172:175], v232 offset:52224
	ds_read_b128 v[194:197], v232 offset:53248
	ds_read_b128 v[198:201], v232 offset:54272
	ds_read_b128 v[202:205], v232 offset:55296
	ds_read_b128 v[206:209], v232 offset:56320
	global_load_lds_dwordx4 v184, s[98:99]
	s_add_i32 m0, s50, 0x2000
	s_add_u32 s42, s42, 0x40080
	s_addc_u32 s43, s43, 0
	s_add_i32 s50, s65, s72
	global_load_lds_dwordx4 v188, s[98:99]
	s_mov_b32 m0, s50
	s_nop 0
	global_load_lds_dwordx4 v184, s[42:43]
	s_add_i32 m0, s50, 0x2000
	s_nop 0
	global_load_lds_dwordx4 v188, s[42:43]
	s_mov_b32 m0, s81
	s_nop 0
	global_load_lds_dwordx4 v182, s[100:101]
	s_mov_b32 m0, s82
	s_nop 0
	global_load_lds_dwordx4 v186, s[100:101]
	s_waitcnt vmcnt(8) lgkmcnt(0)
	s_barrier
	s_setprio 1
	v_mfma_f32_16x16x32_bf16 v[60:63], v[88:91], v[160:163], v[60:63]
	v_mfma_f32_16x16x32_bf16 v[56:59], v[104:107], v[160:163], v[56:59]
	v_mfma_f32_16x16x32_bf16 v[44:47], v[88:91], v[168:171], v[44:47]
	v_mfma_f32_16x16x32_bf16 v[40:43], v[104:107], v[168:171], v[40:43]
	v_mfma_f32_16x16x32_bf16 v[28:31], v[88:91], v[194:197], v[28:31]
	v_mfma_f32_16x16x32_bf16 v[24:27], v[104:107], v[194:197], v[24:27]
	v_mfma_f32_16x16x32_bf16 v[12:15], v[88:91], v[202:205], v[12:15]
	v_mfma_f32_16x16x32_bf16 v[8:11], v[104:107], v[202:205], v[8:11]
	v_mfma_f32_16x16x32_bf16 v[60:63], v[92:95], v[164:167], v[60:63]
	v_mfma_f32_16x16x32_bf16 v[56:59], v[108:111], v[164:167], v[56:59]
	v_mfma_f32_16x16x32_bf16 v[44:47], v[92:95], v[172:175], v[44:47]
	v_mfma_f32_16x16x32_bf16 v[40:43], v[108:111], v[172:175], v[40:43]
	v_mfma_f32_16x16x32_bf16 v[28:31], v[92:95], v[198:201], v[28:31]
	v_mfma_f32_16x16x32_bf16 v[24:27], v[108:111], v[198:201], v[24:27]
	v_mfma_f32_16x16x32_bf16 v[12:15], v[92:95], v[206:209], v[12:15]
	v_mfma_f32_16x16x32_bf16 v[8:11], v[108:111], v[206:209], v[8:11]
	v_mfma_f32_16x16x32_bf16 v[52:55], v[144:147], v[160:163], v[52:55]
	v_mfma_f32_16x16x32_bf16 v[48:51], v[152:155], v[160:163], v[48:51]
	v_mfma_f32_16x16x32_bf16 v[36:39], v[144:147], v[168:171], v[36:39]
	v_mfma_f32_16x16x32_bf16 v[32:35], v[152:155], v[168:171], v[32:35]
	v_mfma_f32_16x16x32_bf16 v[20:23], v[144:147], v[194:197], v[20:23]
	v_mfma_f32_16x16x32_bf16 v[16:19], v[152:155], v[194:197], v[16:19]
	v_mfma_f32_16x16x32_bf16 v[4:7], v[144:147], v[202:205], v[4:7]
	v_mfma_f32_16x16x32_bf16 v[0:3], v[152:155], v[202:205], v[0:3]
	v_mfma_f32_16x16x32_bf16 v[52:55], v[148:151], v[164:167], v[52:55]
	v_mfma_f32_16x16x32_bf16 v[48:51], v[156:159], v[164:167], v[48:51]
	v_mfma_f32_16x16x32_bf16 v[36:39], v[148:151], v[172:175], v[36:39]
	v_mfma_f32_16x16x32_bf16 v[32:35], v[156:159], v[172:175], v[32:35]
	s_setprio 2
	s_barrier
	v_mfma_f32_16x16x32_bf16 v[20:23], v[148:151], v[198:201], v[20:23]
	v_mfma_f32_16x16x32_bf16 v[16:19], v[156:159], v[198:201], v[16:19]
	v_mfma_f32_16x16x32_bf16 v[4:7], v[148:151], v[206:209], v[4:7]
	v_mfma_f32_16x16x32_bf16 v[0:3], v[156:159], v[206:209], v[0:3]
	s_setprio 0
	s_add_u32 s95, s95, 0x100
	s_addc_u32 vcc_lo, vcc_lo, 0
	s_add_u32 s4, s4, 0x100
	s_addc_u32 s5, s5, 0
	s_cmp_ge_i32 vcc_hi, s52
	s_mov_b32 s42, vcc_hi
	s_cbranch_scc0 .LBB0_1222
